# speedup vs baseline: 1.0245x; 1.0245x over previous
; __device__ __forceinline__ unsigned pack2(float a, float b) { return (unsigned)f2bf(a) | ((unsigned)f2bf(b) << 16); }
; __device__ __forceinline__ float lo16(unsigned v) { return __uint_as_float(v << 16); }
; __device__ __forceinline__ float hi16(unsigned v) { return __uint_as_float(v & 0xffff0000u); }
; __device__ __forceinline__ void phase_scan(const Params& p, unsigned* st, int npairs, int pairs_per_head_shift, int mode) {
;     ...
;   for (int e = blockIdx.x * 256 + tid; e < npairs; e += gridDim.x * 256) {
;     int h = e >> pairs_per_head_shift;
;     float r0 = 0.f, r1 = 0.f;
;     float rdec = 1.f;
;     if (mode == 1) rdec = expf(128.f * logf(1.f - exp2f(-5.f - (float)h)));
;     for (int c0 = 0; c0 < NCH; c0 += 8) {
;       unsigned v[8];
;       float dc[8];
; #pragma unroll
;       for (int i = 0; i < 8; i++) {
;         int c = c0 + i;
;         if (c < NCH) {
;           v[i] = st[(size_t)c * npairs + e];
;           dc[i] = (mode == 0) ? expf(acs[((size_t)c * 16 + h) * 128 + 127]) : rdec;
;         } else { v[i] = 0; dc[i] = 0.f; }
;       }
; #pragma unroll
;       for (int i = 0; i < 8; i++) {
;         int c = c0 + i;
;         if (c < NCH) {
;           *(st + (size_t)c * npairs + e) = pack2(r0, r1);
;           r0 = r0 * dc[i] + lo16(v[i]);
;           r1 = r1 * dc[i] + hi16(v[i]);
;         }
;       }
;     }
;   }
.LBB0_1190:
	s_movk_i32 s99, 0x7fff
	s_mov_b32 s100, 0xffff0000
	s_mov_b32 s101, 0x3fb8aa3b
	v_mov_b32_e32 v16, 0x7f800000
	v_lshlrev_b32_e32 v26, 2, v0
	v_mov_b32_e32 v20, 0
	v_mov_b32_e32 v21, 0
	v_mov_b32_e32 v27, v26
	v_add_u32_e32 v28, 0x2000000, v26
	v_ashrrev_i32_e32 v30, 12, v0
	v_lshlrev_b32_e32 v30, 9, v30
	v_add_u32_e32 v31, 0x100000, v30
	global_load_dword v40, v26, s[6:7]
	v_add_u32_e32 v26, 0x40000, v26
	global_load_dword v60, v30, s[8:9]
	v_add_u32_e32 v30, 0x2000, v30
	global_load_dword v41, v26, s[6:7]
	v_add_u32_e32 v26, 0x40000, v26
	global_load_dword v61, v30, s[8:9]
	v_add_u32_e32 v30, 0x2000, v30
	global_load_dword v42, v26, s[6:7]
	v_add_u32_e32 v26, 0x40000, v26
	global_load_dword v62, v30, s[8:9]
	v_add_u32_e32 v30, 0x2000, v30
	global_load_dword v43, v26, s[6:7]
	v_add_u32_e32 v26, 0x40000, v26
	global_load_dword v63, v30, s[8:9]
	v_add_u32_e32 v30, 0x2000, v30
	global_load_dword v44, v26, s[6:7]
	v_add_u32_e32 v26, 0x40000, v26
	global_load_dword v64, v30, s[8:9]
	v_add_u32_e32 v30, 0x2000, v30
	global_load_dword v45, v26, s[6:7]
	v_add_u32_e32 v26, 0x40000, v26
	global_load_dword v65, v30, s[8:9]
	v_add_u32_e32 v30, 0x2000, v30
	global_load_dword v46, v26, s[6:7]
	v_add_u32_e32 v26, 0x40000, v26
	global_load_dword v66, v30, s[8:9]
	v_add_u32_e32 v30, 0x2000, v30
	global_load_dword v47, v26, s[6:7]
	v_add_u32_e32 v26, 0x40000, v26
	global_load_dword v67, v30, s[8:9]
	v_add_u32_e32 v30, 0x2000, v30
	global_load_dword v48, v26, s[6:7]
	v_add_u32_e32 v26, 0x40000, v26
	global_load_dword v68, v30, s[8:9]
	v_add_u32_e32 v30, 0x2000, v30
	global_load_dword v49, v26, s[6:7]
	v_add_u32_e32 v26, 0x40000, v26
	global_load_dword v69, v30, s[8:9]
	v_add_u32_e32 v30, 0x2000, v30
	global_load_dword v50, v26, s[6:7]
	v_add_u32_e32 v26, 0x40000, v26
	global_load_dword v70, v30, s[8:9]
	v_add_u32_e32 v30, 0x2000, v30
	global_load_dword v51, v26, s[6:7]
	v_add_u32_e32 v26, 0x40000, v26
	global_load_dword v71, v30, s[8:9]
	v_add_u32_e32 v30, 0x2000, v30
	global_load_dword v52, v26, s[6:7]
	v_add_u32_e32 v26, 0x40000, v26
	global_load_dword v72, v30, s[8:9]
	v_add_u32_e32 v30, 0x2000, v30
	global_load_dword v53, v26, s[6:7]
	v_add_u32_e32 v26, 0x40000, v26
	global_load_dword v73, v30, s[8:9]
	v_add_u32_e32 v30, 0x2000, v30
	global_load_dword v54, v26, s[6:7]
	v_add_u32_e32 v26, 0x40000, v26
	global_load_dword v74, v30, s[8:9]
	v_add_u32_e32 v30, 0x2000, v30
	global_load_dword v55, v26, s[6:7]
	v_add_u32_e32 v26, 0x40000, v26
	global_load_dword v75, v30, s[8:9]
	v_add_u32_e32 v30, 0x2000, v30
	s_waitcnt vmcnt(30)
	v_mul_f32_e32 v13, 0x3fb8aa3b, v60
	v_fma_f32 v14, v60, s101, -v13
	v_rndne_f32_e32 v15, v13
	v_fmac_f32_e32 v14, 0x32a5705f, v60
	v_sub_f32_e32 v13, v13, v15
	v_add_f32_e32 v13, v13, v14
	v_exp_f32_e32 v13, v13
	v_cvt_i32_f32_e32 v14, v15
	v_cmp_ngt_f32_e32 vcc, 0xc2ce8ed0, v60
	v_ldexp_f32 v13, v13, v14
	s_nop 0
	v_cndmask_b32_e32 v13, 0, v13, vcc
	v_cmp_nlt_f32_e32 vcc, 0x42b17218, v60
	s_nop 1
	v_cndmask_b32_e32 v12, v16, v13, vcc
	v_bfe_u32 v24, v20, 16, 1
	v_add3_u32 v24, v20, v24, s99
	v_bfe_u32 v25, v21, 16, 1
	v_lshrrev_b32_e32 v24, 16, v24
	v_add3_u32 v25, v21, v25, s99
	v_and_or_b32 v24, v25, s100, v24
	global_store_dword v27, v24, s[6:7]
	v_add_u32_e32 v27, 0x40000, v27
	v_lshlrev_b32_e32 v22, 16, v40
	v_and_b32_e32 v23, 0xffff0000, v40
	v_fmac_f32_e32 v22, v12, v20
	v_fmac_f32_e32 v23, v12, v21
	v_min_u32_e32 v26, v26, v28
	global_load_dword v40, v26, s[6:7]
	v_add_u32_e32 v26, 0x40000, v26
	v_min_u32_e32 v30, v30, v31
	global_load_dword v60, v30, s[8:9]
	v_add_u32_e32 v30, 0x2000, v30
	s_waitcnt vmcnt(31)
	v_mul_f32_e32 v13, 0x3fb8aa3b, v61
	v_fma_f32 v14, v61, s101, -v13
	v_rndne_f32_e32 v15, v13
	v_fmac_f32_e32 v14, 0x32a5705f, v61
	v_sub_f32_e32 v13, v13, v15
	v_add_f32_e32 v13, v13, v14
	v_exp_f32_e32 v13, v13
	v_cvt_i32_f32_e32 v14, v15
	v_cmp_ngt_f32_e32 vcc, 0xc2ce8ed0, v61
	v_ldexp_f32 v13, v13, v14
	s_nop 0
	v_cndmask_b32_e32 v13, 0, v13, vcc
	v_cmp_nlt_f32_e32 vcc, 0x42b17218, v61
	s_nop 1
	v_cndmask_b32_e32 v12, v16, v13, vcc
	v_bfe_u32 v24, v22, 16, 1
	v_add3_u32 v24, v22, v24, s99
	v_bfe_u32 v25, v23, 16, 1
	v_lshrrev_b32_e32 v24, 16, v24
	v_add3_u32 v25, v23, v25, s99
	v_and_or_b32 v24, v25, s100, v24
	global_store_dword v27, v24, s[6:7]
	v_add_u32_e32 v27, 0x40000, v27
	v_lshlrev_b32_e32 v20, 16, v41
	v_and_b32_e32 v21, 0xffff0000, v41
	v_fmac_f32_e32 v20, v12, v22
	v_fmac_f32_e32 v21, v12, v23
	v_min_u32_e32 v26, v26, v28
	global_load_dword v41, v26, s[6:7]
	v_add_u32_e32 v26, 0x40000, v26
	v_min_u32_e32 v30, v30, v31
	global_load_dword v61, v30, s[8:9]
	v_add_u32_e32 v30, 0x2000, v30
	s_waitcnt vmcnt(32)
	v_mul_f32_e32 v13, 0x3fb8aa3b, v62
	v_fma_f32 v14, v62, s101, -v13
	v_rndne_f32_e32 v15, v13
	v_fmac_f32_e32 v14, 0x32a5705f, v62
	v_sub_f32_e32 v13, v13, v15
	v_add_f32_e32 v13, v13, v14
	v_exp_f32_e32 v13, v13
	v_cvt_i32_f32_e32 v14, v15
	v_cmp_ngt_f32_e32 vcc, 0xc2ce8ed0, v62
	v_ldexp_f32 v13, v13, v14
	s_nop 0
	v_cndmask_b32_e32 v13, 0, v13, vcc
	v_cmp_nlt_f32_e32 vcc, 0x42b17218, v62
	s_nop 1
	v_cndmask_b32_e32 v12, v16, v13, vcc
	v_bfe_u32 v24, v20, 16, 1
	v_add3_u32 v24, v20, v24, s99
	v_bfe_u32 v25, v21, 16, 1
	v_lshrrev_b32_e32 v24, 16, v24
	v_add3_u32 v25, v21, v25, s99
	v_and_or_b32 v24, v25, s100, v24
	global_store_dword v27, v24, s[6:7]
	v_add_u32_e32 v27, 0x40000, v27
	v_lshlrev_b32_e32 v22, 16, v42
	v_and_b32_e32 v23, 0xffff0000, v42
	v_fmac_f32_e32 v22, v12, v20
	v_fmac_f32_e32 v23, v12, v21
	v_min_u32_e32 v26, v26, v28
	global_load_dword v42, v26, s[6:7]
	v_add_u32_e32 v26, 0x40000, v26
	v_min_u32_e32 v30, v30, v31
	global_load_dword v62, v30, s[8:9]
	v_add_u32_e32 v30, 0x2000, v30
	s_waitcnt vmcnt(33)
; __device__ __forceinline__ unsigned pack2(float a, float b) { return (unsigned)f2bf(a) | ((unsigned)f2bf(b) << 16); }
; __device__ __forceinline__ float lo16(unsigned v) { return __uint_as_float(v << 16); }
; __device__ __forceinline__ float hi16(unsigned v) { return __uint_as_float(v & 0xffff0000u); }
; __device__ __forceinline__ void phase_scan(const Params& p, unsigned* st, int npairs, int pairs_per_head_shift, int mode) {
;     ...
;           v[i] = st[(size_t)c * npairs + e];
;           dc[i] = (mode == 0) ? expf(acs[((size_t)c * 16 + h) * 128 + 127]) : rdec;
;         } else { v[i] = 0; dc[i] = 0.f; }
;       }
; #pragma unroll
;       for (int i = 0; i < 8; i++) {
;         int c = c0 + i;
;         if (c < NCH) {
;           *(st + (size_t)c * npairs + e) = pack2(r0, r1);
;           r0 = r0 * dc[i] + lo16(v[i]);
;           r1 = r1 * dc[i] + hi16(v[i]);
	v_mul_f32_e32 v13, 0x3fb8aa3b, v63
	v_fma_f32 v14, v63, s101, -v13
	v_rndne_f32_e32 v15, v13
	v_fmac_f32_e32 v14, 0x32a5705f, v63
	v_sub_f32_e32 v13, v13, v15
	v_add_f32_e32 v13, v13, v14
	v_exp_f32_e32 v13, v13
	v_cvt_i32_f32_e32 v14, v15
	v_cmp_ngt_f32_e32 vcc, 0xc2ce8ed0, v63
	v_ldexp_f32 v13, v13, v14
	s_nop 0
	v_cndmask_b32_e32 v13, 0, v13, vcc
	v_cmp_nlt_f32_e32 vcc, 0x42b17218, v63
	s_nop 1
	v_cndmask_b32_e32 v12, v16, v13, vcc
	v_bfe_u32 v24, v22, 16, 1
	v_add3_u32 v24, v22, v24, s99
	v_bfe_u32 v25, v23, 16, 1
	v_lshrrev_b32_e32 v24, 16, v24
	v_add3_u32 v25, v23, v25, s99
	v_and_or_b32 v24, v25, s100, v24
	global_store_dword v27, v24, s[6:7]
	v_add_u32_e32 v27, 0x40000, v27
	v_lshlrev_b32_e32 v20, 16, v43
	v_and_b32_e32 v21, 0xffff0000, v43
	v_fmac_f32_e32 v20, v12, v22
	v_fmac_f32_e32 v21, v12, v23
	v_min_u32_e32 v26, v26, v28
	global_load_dword v43, v26, s[6:7]
	v_add_u32_e32 v26, 0x40000, v26
	v_min_u32_e32 v30, v30, v31
	global_load_dword v63, v30, s[8:9]
	v_add_u32_e32 v30, 0x2000, v30
	s_waitcnt vmcnt(34)
	v_mul_f32_e32 v13, 0x3fb8aa3b, v64
	v_fma_f32 v14, v64, s101, -v13
	v_rndne_f32_e32 v15, v13
	v_fmac_f32_e32 v14, 0x32a5705f, v64
	v_sub_f32_e32 v13, v13, v15
	v_add_f32_e32 v13, v13, v14
	v_exp_f32_e32 v13, v13
	v_cvt_i32_f32_e32 v14, v15
	v_cmp_ngt_f32_e32 vcc, 0xc2ce8ed0, v64
	v_ldexp_f32 v13, v13, v14
	s_nop 0
	v_cndmask_b32_e32 v13, 0, v13, vcc
	v_cmp_nlt_f32_e32 vcc, 0x42b17218, v64
	s_nop 1
	v_cndmask_b32_e32 v12, v16, v13, vcc
	v_bfe_u32 v24, v20, 16, 1
	v_add3_u32 v24, v20, v24, s99
	v_bfe_u32 v25, v21, 16, 1
	v_lshrrev_b32_e32 v24, 16, v24
	v_add3_u32 v25, v21, v25, s99
	v_and_or_b32 v24, v25, s100, v24
	global_store_dword v27, v24, s[6:7]
	v_add_u32_e32 v27, 0x40000, v27
	v_lshlrev_b32_e32 v22, 16, v44
	v_and_b32_e32 v23, 0xffff0000, v44
	v_fmac_f32_e32 v22, v12, v20
	v_fmac_f32_e32 v23, v12, v21
	v_min_u32_e32 v26, v26, v28
	global_load_dword v44, v26, s[6:7]
	v_add_u32_e32 v26, 0x40000, v26
	v_min_u32_e32 v30, v30, v31
	global_load_dword v64, v30, s[8:9]
	v_add_u32_e32 v30, 0x2000, v30
	s_waitcnt vmcnt(35)
	v_mul_f32_e32 v13, 0x3fb8aa3b, v65
	v_fma_f32 v14, v65, s101, -v13
	v_rndne_f32_e32 v15, v13
	v_fmac_f32_e32 v14, 0x32a5705f, v65
	v_sub_f32_e32 v13, v13, v15
	v_add_f32_e32 v13, v13, v14
	v_exp_f32_e32 v13, v13
	v_cvt_i32_f32_e32 v14, v15
	v_cmp_ngt_f32_e32 vcc, 0xc2ce8ed0, v65
	v_ldexp_f32 v13, v13, v14
	s_nop 0
	v_cndmask_b32_e32 v13, 0, v13, vcc
	v_cmp_nlt_f32_e32 vcc, 0x42b17218, v65
	s_nop 1
	v_cndmask_b32_e32 v12, v16, v13, vcc
	v_bfe_u32 v24, v22, 16, 1
	v_add3_u32 v24, v22, v24, s99
	v_bfe_u32 v25, v23, 16, 1
	v_lshrrev_b32_e32 v24, 16, v24
	v_add3_u32 v25, v23, v25, s99
	v_and_or_b32 v24, v25, s100, v24
	global_store_dword v27, v24, s[6:7]
	v_add_u32_e32 v27, 0x40000, v27
	v_lshlrev_b32_e32 v20, 16, v45
	v_and_b32_e32 v21, 0xffff0000, v45
	v_fmac_f32_e32 v20, v12, v22
	v_fmac_f32_e32 v21, v12, v23
	v_min_u32_e32 v26, v26, v28
	global_load_dword v45, v26, s[6:7]
	v_add_u32_e32 v26, 0x40000, v26
	v_min_u32_e32 v30, v30, v31
	global_load_dword v65, v30, s[8:9]
	v_add_u32_e32 v30, 0x2000, v30
	s_waitcnt vmcnt(36)
	v_mul_f32_e32 v13, 0x3fb8aa3b, v66
	v_fma_f32 v14, v66, s101, -v13
	v_rndne_f32_e32 v15, v13
	v_fmac_f32_e32 v14, 0x32a5705f, v66
	v_sub_f32_e32 v13, v13, v15
	v_add_f32_e32 v13, v13, v14
	v_exp_f32_e32 v13, v13
	v_cvt_i32_f32_e32 v14, v15
	v_cmp_ngt_f32_e32 vcc, 0xc2ce8ed0, v66
	v_ldexp_f32 v13, v13, v14
	s_nop 0
	v_cndmask_b32_e32 v13, 0, v13, vcc
	v_cmp_nlt_f32_e32 vcc, 0x42b17218, v66
	s_nop 1
	v_cndmask_b32_e32 v12, v16, v13, vcc
	v_bfe_u32 v24, v20, 16, 1
	v_add3_u32 v24, v20, v24, s99
	v_bfe_u32 v25, v21, 16, 1
	v_lshrrev_b32_e32 v24, 16, v24
	v_add3_u32 v25, v21, v25, s99
	v_and_or_b32 v24, v25, s100, v24
	global_store_dword v27, v24, s[6:7]
	v_add_u32_e32 v27, 0x40000, v27
	v_lshlrev_b32_e32 v22, 16, v46
	v_and_b32_e32 v23, 0xffff0000, v46
	v_fmac_f32_e32 v22, v12, v20
	v_fmac_f32_e32 v23, v12, v21
	v_min_u32_e32 v26, v26, v28
	global_load_dword v46, v26, s[6:7]
	v_add_u32_e32 v26, 0x40000, v26
	v_min_u32_e32 v30, v30, v31
	global_load_dword v66, v30, s[8:9]
	v_add_u32_e32 v30, 0x2000, v30
	s_waitcnt vmcnt(37)
	v_mul_f32_e32 v13, 0x3fb8aa3b, v67
	v_fma_f32 v14, v67, s101, -v13
	v_rndne_f32_e32 v15, v13
	v_fmac_f32_e32 v14, 0x32a5705f, v67
	v_sub_f32_e32 v13, v13, v15
	v_add_f32_e32 v13, v13, v14
	v_exp_f32_e32 v13, v13
	v_cvt_i32_f32_e32 v14, v15
	v_cmp_ngt_f32_e32 vcc, 0xc2ce8ed0, v67
	v_ldexp_f32 v13, v13, v14
	s_nop 0
	v_cndmask_b32_e32 v13, 0, v13, vcc
	v_cmp_nlt_f32_e32 vcc, 0x42b17218, v67
	s_nop 1
	v_cndmask_b32_e32 v12, v16, v13, vcc
	v_bfe_u32 v24, v22, 16, 1
	v_add3_u32 v24, v22, v24, s99
	v_bfe_u32 v25, v23, 16, 1
	v_lshrrev_b32_e32 v24, 16, v24
	v_add3_u32 v25, v23, v25, s99
	v_and_or_b32 v24, v25, s100, v24
	global_store_dword v27, v24, s[6:7]
	v_add_u32_e32 v27, 0x40000, v27
	v_lshlrev_b32_e32 v20, 16, v47
	v_and_b32_e32 v21, 0xffff0000, v47
	v_fmac_f32_e32 v20, v12, v22
	v_fmac_f32_e32 v21, v12, v23
	v_min_u32_e32 v26, v26, v28
	global_load_dword v47, v26, s[6:7]
	v_add_u32_e32 v26, 0x40000, v26
	v_min_u32_e32 v30, v30, v31
	global_load_dword v67, v30, s[8:9]
	v_add_u32_e32 v30, 0x2000, v30
	s_waitcnt vmcnt(38)
; __device__ __forceinline__ unsigned pack2(float a, float b) { return (unsigned)f2bf(a) | ((unsigned)f2bf(b) << 16); }
; __device__ __forceinline__ float lo16(unsigned v) { return __uint_as_float(v << 16); }
; __device__ __forceinline__ float hi16(unsigned v) { return __uint_as_float(v & 0xffff0000u); }
; __device__ __forceinline__ void phase_scan(const Params& p, unsigned* st, int npairs, int pairs_per_head_shift, int mode) {
;     ...
;           v[i] = st[(size_t)c * npairs + e];
;           dc[i] = (mode == 0) ? expf(acs[((size_t)c * 16 + h) * 128 + 127]) : rdec;
;         } else { v[i] = 0; dc[i] = 0.f; }
;       }
; #pragma unroll
;       for (int i = 0; i < 8; i++) {
;         int c = c0 + i;
;         if (c < NCH) {
;           *(st + (size_t)c * npairs + e) = pack2(r0, r1);
;           r0 = r0 * dc[i] + lo16(v[i]);
;           r1 = r1 * dc[i] + hi16(v[i]);
	v_mul_f32_e32 v13, 0x3fb8aa3b, v68
	v_fma_f32 v14, v68, s101, -v13
	v_rndne_f32_e32 v15, v13
	v_fmac_f32_e32 v14, 0x32a5705f, v68
	v_sub_f32_e32 v13, v13, v15
	v_add_f32_e32 v13, v13, v14
	v_exp_f32_e32 v13, v13
	v_cvt_i32_f32_e32 v14, v15
	v_cmp_ngt_f32_e32 vcc, 0xc2ce8ed0, v68
	v_ldexp_f32 v13, v13, v14
	s_nop 0
	v_cndmask_b32_e32 v13, 0, v13, vcc
	v_cmp_nlt_f32_e32 vcc, 0x42b17218, v68
	s_nop 1
	v_cndmask_b32_e32 v12, v16, v13, vcc
	v_bfe_u32 v24, v20, 16, 1
	v_add3_u32 v24, v20, v24, s99
	v_bfe_u32 v25, v21, 16, 1
	v_lshrrev_b32_e32 v24, 16, v24
	v_add3_u32 v25, v21, v25, s99
	v_and_or_b32 v24, v25, s100, v24
	global_store_dword v27, v24, s[6:7]
	v_add_u32_e32 v27, 0x40000, v27
	v_lshlrev_b32_e32 v22, 16, v48
	v_and_b32_e32 v23, 0xffff0000, v48
	v_fmac_f32_e32 v22, v12, v20
	v_fmac_f32_e32 v23, v12, v21
	v_min_u32_e32 v26, v26, v28
	global_load_dword v48, v26, s[6:7]
	v_add_u32_e32 v26, 0x40000, v26
	v_min_u32_e32 v30, v30, v31
	global_load_dword v68, v30, s[8:9]
	v_add_u32_e32 v30, 0x2000, v30
	s_waitcnt vmcnt(39)
	v_mul_f32_e32 v13, 0x3fb8aa3b, v69
	v_fma_f32 v14, v69, s101, -v13
	v_rndne_f32_e32 v15, v13
	v_fmac_f32_e32 v14, 0x32a5705f, v69
	v_sub_f32_e32 v13, v13, v15
	v_add_f32_e32 v13, v13, v14
	v_exp_f32_e32 v13, v13
	v_cvt_i32_f32_e32 v14, v15
	v_cmp_ngt_f32_e32 vcc, 0xc2ce8ed0, v69
	v_ldexp_f32 v13, v13, v14
	s_nop 0
	v_cndmask_b32_e32 v13, 0, v13, vcc
	v_cmp_nlt_f32_e32 vcc, 0x42b17218, v69
	s_nop 1
	v_cndmask_b32_e32 v12, v16, v13, vcc
	v_bfe_u32 v24, v22, 16, 1
	v_add3_u32 v24, v22, v24, s99
	v_bfe_u32 v25, v23, 16, 1
	v_lshrrev_b32_e32 v24, 16, v24
	v_add3_u32 v25, v23, v25, s99
	v_and_or_b32 v24, v25, s100, v24
	global_store_dword v27, v24, s[6:7]
	v_add_u32_e32 v27, 0x40000, v27
	v_lshlrev_b32_e32 v20, 16, v49
	v_and_b32_e32 v21, 0xffff0000, v49
	v_fmac_f32_e32 v20, v12, v22
	v_fmac_f32_e32 v21, v12, v23
	v_min_u32_e32 v26, v26, v28
	global_load_dword v49, v26, s[6:7]
	v_add_u32_e32 v26, 0x40000, v26
	v_min_u32_e32 v30, v30, v31
	global_load_dword v69, v30, s[8:9]
	v_add_u32_e32 v30, 0x2000, v30
	s_waitcnt vmcnt(40)
	v_mul_f32_e32 v13, 0x3fb8aa3b, v70
	v_fma_f32 v14, v70, s101, -v13
	v_rndne_f32_e32 v15, v13
	v_fmac_f32_e32 v14, 0x32a5705f, v70
	v_sub_f32_e32 v13, v13, v15
	v_add_f32_e32 v13, v13, v14
	v_exp_f32_e32 v13, v13
	v_cvt_i32_f32_e32 v14, v15
	v_cmp_ngt_f32_e32 vcc, 0xc2ce8ed0, v70
	v_ldexp_f32 v13, v13, v14
	s_nop 0
	v_cndmask_b32_e32 v13, 0, v13, vcc
	v_cmp_nlt_f32_e32 vcc, 0x42b17218, v70
	s_nop 1
	v_cndmask_b32_e32 v12, v16, v13, vcc
	v_bfe_u32 v24, v20, 16, 1
	v_add3_u32 v24, v20, v24, s99
	v_bfe_u32 v25, v21, 16, 1
	v_lshrrev_b32_e32 v24, 16, v24
	v_add3_u32 v25, v21, v25, s99
	v_and_or_b32 v24, v25, s100, v24
	global_store_dword v27, v24, s[6:7]
	v_add_u32_e32 v27, 0x40000, v27
	v_lshlrev_b32_e32 v22, 16, v50
	v_and_b32_e32 v23, 0xffff0000, v50
	v_fmac_f32_e32 v22, v12, v20
	v_fmac_f32_e32 v23, v12, v21
	v_min_u32_e32 v26, v26, v28
	global_load_dword v50, v26, s[6:7]
	v_add_u32_e32 v26, 0x40000, v26
	v_min_u32_e32 v30, v30, v31
	global_load_dword v70, v30, s[8:9]
	v_add_u32_e32 v30, 0x2000, v30
	s_waitcnt vmcnt(41)
	v_mul_f32_e32 v13, 0x3fb8aa3b, v71
	v_fma_f32 v14, v71, s101, -v13
	v_rndne_f32_e32 v15, v13
	v_fmac_f32_e32 v14, 0x32a5705f, v71
	v_sub_f32_e32 v13, v13, v15
	v_add_f32_e32 v13, v13, v14
	v_exp_f32_e32 v13, v13
	v_cvt_i32_f32_e32 v14, v15
	v_cmp_ngt_f32_e32 vcc, 0xc2ce8ed0, v71
	v_ldexp_f32 v13, v13, v14
	s_nop 0
	v_cndmask_b32_e32 v13, 0, v13, vcc
	v_cmp_nlt_f32_e32 vcc, 0x42b17218, v71
	s_nop 1
	v_cndmask_b32_e32 v12, v16, v13, vcc
	v_bfe_u32 v24, v22, 16, 1
	v_add3_u32 v24, v22, v24, s99
	v_bfe_u32 v25, v23, 16, 1
	v_lshrrev_b32_e32 v24, 16, v24
	v_add3_u32 v25, v23, v25, s99
	v_and_or_b32 v24, v25, s100, v24
	global_store_dword v27, v24, s[6:7]
	v_add_u32_e32 v27, 0x40000, v27
	v_lshlrev_b32_e32 v20, 16, v51
	v_and_b32_e32 v21, 0xffff0000, v51
	v_fmac_f32_e32 v20, v12, v22
	v_fmac_f32_e32 v21, v12, v23
	v_min_u32_e32 v26, v26, v28
	global_load_dword v51, v26, s[6:7]
	v_add_u32_e32 v26, 0x40000, v26
	v_min_u32_e32 v30, v30, v31
	global_load_dword v71, v30, s[8:9]
	v_add_u32_e32 v30, 0x2000, v30
	s_waitcnt vmcnt(42)
	v_mul_f32_e32 v13, 0x3fb8aa3b, v72
	v_fma_f32 v14, v72, s101, -v13
	v_rndne_f32_e32 v15, v13
	v_fmac_f32_e32 v14, 0x32a5705f, v72
	v_sub_f32_e32 v13, v13, v15
	v_add_f32_e32 v13, v13, v14
	v_exp_f32_e32 v13, v13
	v_cvt_i32_f32_e32 v14, v15
	v_cmp_ngt_f32_e32 vcc, 0xc2ce8ed0, v72
	v_ldexp_f32 v13, v13, v14
	s_nop 0
	v_cndmask_b32_e32 v13, 0, v13, vcc
	v_cmp_nlt_f32_e32 vcc, 0x42b17218, v72
	s_nop 1
	v_cndmask_b32_e32 v12, v16, v13, vcc
	v_bfe_u32 v24, v20, 16, 1
	v_add3_u32 v24, v20, v24, s99
	v_bfe_u32 v25, v21, 16, 1
	v_lshrrev_b32_e32 v24, 16, v24
	v_add3_u32 v25, v21, v25, s99
	v_and_or_b32 v24, v25, s100, v24
	global_store_dword v27, v24, s[6:7]
	v_add_u32_e32 v27, 0x40000, v27
	v_lshlrev_b32_e32 v22, 16, v52
	v_and_b32_e32 v23, 0xffff0000, v52
	v_fmac_f32_e32 v22, v12, v20
	v_fmac_f32_e32 v23, v12, v21
	v_min_u32_e32 v26, v26, v28
	global_load_dword v52, v26, s[6:7]
	v_add_u32_e32 v26, 0x40000, v26
	v_min_u32_e32 v30, v30, v31
	global_load_dword v72, v30, s[8:9]
	v_add_u32_e32 v30, 0x2000, v30
	s_waitcnt vmcnt(43)
; __device__ __forceinline__ unsigned pack2(float a, float b) { return (unsigned)f2bf(a) | ((unsigned)f2bf(b) << 16); }
; __device__ __forceinline__ float lo16(unsigned v) { return __uint_as_float(v << 16); }
; __device__ __forceinline__ float hi16(unsigned v) { return __uint_as_float(v & 0xffff0000u); }
; __device__ __forceinline__ void phase_scan(const Params& p, unsigned* st, int npairs, int pairs_per_head_shift, int mode) {
;     ...
;     for (int c0 = 0; c0 < NCH; c0 += 8) {
;       unsigned v[8];
;       float dc[8];
; #pragma unroll
;       for (int i = 0; i < 8; i++) {
;         int c = c0 + i;
;         if (c < NCH) {
;           v[i] = st[(size_t)c * npairs + e];
;           dc[i] = (mode == 0) ? expf(acs[((size_t)c * 16 + h) * 128 + 127]) : rdec;
;         } else { v[i] = 0; dc[i] = 0.f; }
;       }
; #pragma unroll
;       for (int i = 0; i < 8; i++) {
;         int c = c0 + i;
;         if (c < NCH) {
;           *(st + (size_t)c * npairs + e) = pack2(r0, r1);
;           r0 = r0 * dc[i] + lo16(v[i]);
;           r1 = r1 * dc[i] + hi16(v[i]);
	v_mul_f32_e32 v13, 0x3fb8aa3b, v73
	v_fma_f32 v14, v73, s101, -v13
	v_rndne_f32_e32 v15, v13
	v_fmac_f32_e32 v14, 0x32a5705f, v73
	v_sub_f32_e32 v13, v13, v15
	v_add_f32_e32 v13, v13, v14
	v_exp_f32_e32 v13, v13
	v_cvt_i32_f32_e32 v14, v15
	v_cmp_ngt_f32_e32 vcc, 0xc2ce8ed0, v73
	v_ldexp_f32 v13, v13, v14
	s_nop 0
	v_cndmask_b32_e32 v13, 0, v13, vcc
	v_cmp_nlt_f32_e32 vcc, 0x42b17218, v73
	s_nop 1
	v_cndmask_b32_e32 v12, v16, v13, vcc
	v_bfe_u32 v24, v22, 16, 1
	v_add3_u32 v24, v22, v24, s99
	v_bfe_u32 v25, v23, 16, 1
	v_lshrrev_b32_e32 v24, 16, v24
	v_add3_u32 v25, v23, v25, s99
	v_and_or_b32 v24, v25, s100, v24
	global_store_dword v27, v24, s[6:7]
	v_add_u32_e32 v27, 0x40000, v27
	v_lshlrev_b32_e32 v20, 16, v53
	v_and_b32_e32 v21, 0xffff0000, v53
	v_fmac_f32_e32 v20, v12, v22
	v_fmac_f32_e32 v21, v12, v23
	v_min_u32_e32 v26, v26, v28
	global_load_dword v53, v26, s[6:7]
	v_add_u32_e32 v26, 0x40000, v26
	v_min_u32_e32 v30, v30, v31
	global_load_dword v73, v30, s[8:9]
	v_add_u32_e32 v30, 0x2000, v30
	s_waitcnt vmcnt(44)
	v_mul_f32_e32 v13, 0x3fb8aa3b, v74
	v_fma_f32 v14, v74, s101, -v13
	v_rndne_f32_e32 v15, v13
	v_fmac_f32_e32 v14, 0x32a5705f, v74
	v_sub_f32_e32 v13, v13, v15
	v_add_f32_e32 v13, v13, v14
	v_exp_f32_e32 v13, v13
	v_cvt_i32_f32_e32 v14, v15
	v_cmp_ngt_f32_e32 vcc, 0xc2ce8ed0, v74
	v_ldexp_f32 v13, v13, v14
	s_nop 0
	v_cndmask_b32_e32 v13, 0, v13, vcc
	v_cmp_nlt_f32_e32 vcc, 0x42b17218, v74
	s_nop 1
	v_cndmask_b32_e32 v12, v16, v13, vcc
	v_bfe_u32 v24, v20, 16, 1
	v_add3_u32 v24, v20, v24, s99
	v_bfe_u32 v25, v21, 16, 1
	v_lshrrev_b32_e32 v24, 16, v24
	v_add3_u32 v25, v21, v25, s99
	v_and_or_b32 v24, v25, s100, v24
	global_store_dword v27, v24, s[6:7]
	v_add_u32_e32 v27, 0x40000, v27
	v_lshlrev_b32_e32 v22, 16, v54
	v_and_b32_e32 v23, 0xffff0000, v54
	v_fmac_f32_e32 v22, v12, v20
	v_fmac_f32_e32 v23, v12, v21
	v_min_u32_e32 v26, v26, v28
	global_load_dword v54, v26, s[6:7]
	v_add_u32_e32 v26, 0x40000, v26
	v_min_u32_e32 v30, v30, v31
	global_load_dword v74, v30, s[8:9]
	v_add_u32_e32 v30, 0x2000, v30
	s_waitcnt vmcnt(45)
	v_mul_f32_e32 v13, 0x3fb8aa3b, v75
	v_fma_f32 v14, v75, s101, -v13
	v_rndne_f32_e32 v15, v13
	v_fmac_f32_e32 v14, 0x32a5705f, v75
	v_sub_f32_e32 v13, v13, v15
	v_add_f32_e32 v13, v13, v14
	v_exp_f32_e32 v13, v13
	v_cvt_i32_f32_e32 v14, v15
	v_cmp_ngt_f32_e32 vcc, 0xc2ce8ed0, v75
	v_ldexp_f32 v13, v13, v14
	s_nop 0
	v_cndmask_b32_e32 v13, 0, v13, vcc
	v_cmp_nlt_f32_e32 vcc, 0x42b17218, v75
	s_nop 1
	v_cndmask_b32_e32 v12, v16, v13, vcc
	v_bfe_u32 v24, v22, 16, 1
	v_add3_u32 v24, v22, v24, s99
	v_bfe_u32 v25, v23, 16, 1
	v_lshrrev_b32_e32 v24, 16, v24
	v_add3_u32 v25, v23, v25, s99
	v_and_or_b32 v24, v25, s100, v24
	global_store_dword v27, v24, s[6:7]
	v_add_u32_e32 v27, 0x40000, v27
	v_lshlrev_b32_e32 v20, 16, v55
	v_and_b32_e32 v21, 0xffff0000, v55
	v_fmac_f32_e32 v20, v12, v22
	v_fmac_f32_e32 v21, v12, v23
	v_min_u32_e32 v26, v26, v28
	global_load_dword v55, v26, s[6:7]
	v_add_u32_e32 v26, 0x40000, v26
	v_min_u32_e32 v30, v30, v31
	global_load_dword v75, v30, s[8:9]
	v_add_u32_e32 v30, 0x2000, v30
	s_mov_b32 s98, 7
.Lscan_ssd0_loop:
	s_waitcnt vmcnt(45)
	v_mul_f32_e32 v13, 0x3fb8aa3b, v60
	v_fma_f32 v14, v60, s101, -v13
	v_rndne_f32_e32 v15, v13
	v_fmac_f32_e32 v14, 0x32a5705f, v60
	v_sub_f32_e32 v13, v13, v15
	v_add_f32_e32 v13, v13, v14
	v_exp_f32_e32 v13, v13
	v_cvt_i32_f32_e32 v14, v15
	v_cmp_ngt_f32_e32 vcc, 0xc2ce8ed0, v60
	v_ldexp_f32 v13, v13, v14
	s_nop 0
	v_cndmask_b32_e32 v13, 0, v13, vcc
	v_cmp_nlt_f32_e32 vcc, 0x42b17218, v60
	s_nop 1
	v_cndmask_b32_e32 v12, v16, v13, vcc
	v_bfe_u32 v24, v20, 16, 1
	v_add3_u32 v24, v20, v24, s99
	v_bfe_u32 v25, v21, 16, 1
	v_lshrrev_b32_e32 v24, 16, v24
	v_add3_u32 v25, v21, v25, s99
	v_and_or_b32 v24, v25, s100, v24
	global_store_dword v27, v24, s[6:7]
	v_add_u32_e32 v27, 0x40000, v27
	v_lshlrev_b32_e32 v22, 16, v40
	v_and_b32_e32 v23, 0xffff0000, v40
	v_fmac_f32_e32 v22, v12, v20
	v_fmac_f32_e32 v23, v12, v21
	v_min_u32_e32 v26, v26, v28
	global_load_dword v40, v26, s[6:7]
	v_add_u32_e32 v26, 0x40000, v26
	v_min_u32_e32 v30, v30, v31
	global_load_dword v60, v30, s[8:9]
	v_add_u32_e32 v30, 0x2000, v30
	s_waitcnt vmcnt(45)
	v_mul_f32_e32 v13, 0x3fb8aa3b, v61
	v_fma_f32 v14, v61, s101, -v13
	v_rndne_f32_e32 v15, v13
	v_fmac_f32_e32 v14, 0x32a5705f, v61
	v_sub_f32_e32 v13, v13, v15
	v_add_f32_e32 v13, v13, v14
	v_exp_f32_e32 v13, v13
	v_cvt_i32_f32_e32 v14, v15
	v_cmp_ngt_f32_e32 vcc, 0xc2ce8ed0, v61
	v_ldexp_f32 v13, v13, v14
	s_nop 0
	v_cndmask_b32_e32 v13, 0, v13, vcc
	v_cmp_nlt_f32_e32 vcc, 0x42b17218, v61
	s_nop 1
	v_cndmask_b32_e32 v12, v16, v13, vcc
	v_bfe_u32 v24, v22, 16, 1
	v_add3_u32 v24, v22, v24, s99
	v_bfe_u32 v25, v23, 16, 1
	v_lshrrev_b32_e32 v24, 16, v24
	v_add3_u32 v25, v23, v25, s99
	v_and_or_b32 v24, v25, s100, v24
	global_store_dword v27, v24, s[6:7]
	v_add_u32_e32 v27, 0x40000, v27
	v_lshlrev_b32_e32 v20, 16, v41
	v_and_b32_e32 v21, 0xffff0000, v41
	v_fmac_f32_e32 v20, v12, v22
	v_fmac_f32_e32 v21, v12, v23
	v_min_u32_e32 v26, v26, v28
	global_load_dword v41, v26, s[6:7]
	v_add_u32_e32 v26, 0x40000, v26
	v_min_u32_e32 v30, v30, v31
	global_load_dword v61, v30, s[8:9]
	v_add_u32_e32 v30, 0x2000, v30
	s_waitcnt vmcnt(45)
; __device__ __forceinline__ unsigned pack2(float a, float b) { return (unsigned)f2bf(a) | ((unsigned)f2bf(b) << 16); }
; __device__ __forceinline__ float lo16(unsigned v) { return __uint_as_float(v << 16); }
; __device__ __forceinline__ float hi16(unsigned v) { return __uint_as_float(v & 0xffff0000u); }
; __device__ __forceinline__ void phase_scan(const Params& p, unsigned* st, int npairs, int pairs_per_head_shift, int mode) {
;     ...
;           v[i] = st[(size_t)c * npairs + e];
;           dc[i] = (mode == 0) ? expf(acs[((size_t)c * 16 + h) * 128 + 127]) : rdec;
;         } else { v[i] = 0; dc[i] = 0.f; }
;       }
; #pragma unroll
;       for (int i = 0; i < 8; i++) {
;         int c = c0 + i;
;         if (c < NCH) {
;           *(st + (size_t)c * npairs + e) = pack2(r0, r1);
;           r0 = r0 * dc[i] + lo16(v[i]);
;           r1 = r1 * dc[i] + hi16(v[i]);
	v_mul_f32_e32 v13, 0x3fb8aa3b, v62
	v_fma_f32 v14, v62, s101, -v13
	v_rndne_f32_e32 v15, v13
	v_fmac_f32_e32 v14, 0x32a5705f, v62
	v_sub_f32_e32 v13, v13, v15
	v_add_f32_e32 v13, v13, v14
	v_exp_f32_e32 v13, v13
	v_cvt_i32_f32_e32 v14, v15
	v_cmp_ngt_f32_e32 vcc, 0xc2ce8ed0, v62
	v_ldexp_f32 v13, v13, v14
	s_nop 0
	v_cndmask_b32_e32 v13, 0, v13, vcc
	v_cmp_nlt_f32_e32 vcc, 0x42b17218, v62
	s_nop 1
	v_cndmask_b32_e32 v12, v16, v13, vcc
	v_bfe_u32 v24, v20, 16, 1
	v_add3_u32 v24, v20, v24, s99
	v_bfe_u32 v25, v21, 16, 1
	v_lshrrev_b32_e32 v24, 16, v24
	v_add3_u32 v25, v21, v25, s99
	v_and_or_b32 v24, v25, s100, v24
	global_store_dword v27, v24, s[6:7]
	v_add_u32_e32 v27, 0x40000, v27
	v_lshlrev_b32_e32 v22, 16, v42
	v_and_b32_e32 v23, 0xffff0000, v42
	v_fmac_f32_e32 v22, v12, v20
	v_fmac_f32_e32 v23, v12, v21
	v_min_u32_e32 v26, v26, v28
	global_load_dword v42, v26, s[6:7]
	v_add_u32_e32 v26, 0x40000, v26
	v_min_u32_e32 v30, v30, v31
	global_load_dword v62, v30, s[8:9]
	v_add_u32_e32 v30, 0x2000, v30
	s_waitcnt vmcnt(45)
	v_mul_f32_e32 v13, 0x3fb8aa3b, v63
	v_fma_f32 v14, v63, s101, -v13
	v_rndne_f32_e32 v15, v13
	v_fmac_f32_e32 v14, 0x32a5705f, v63
	v_sub_f32_e32 v13, v13, v15
	v_add_f32_e32 v13, v13, v14
	v_exp_f32_e32 v13, v13
	v_cvt_i32_f32_e32 v14, v15
	v_cmp_ngt_f32_e32 vcc, 0xc2ce8ed0, v63
	v_ldexp_f32 v13, v13, v14
	s_nop 0
	v_cndmask_b32_e32 v13, 0, v13, vcc
	v_cmp_nlt_f32_e32 vcc, 0x42b17218, v63
	s_nop 1
	v_cndmask_b32_e32 v12, v16, v13, vcc
	v_bfe_u32 v24, v22, 16, 1
	v_add3_u32 v24, v22, v24, s99
	v_bfe_u32 v25, v23, 16, 1
	v_lshrrev_b32_e32 v24, 16, v24
	v_add3_u32 v25, v23, v25, s99
	v_and_or_b32 v24, v25, s100, v24
	global_store_dword v27, v24, s[6:7]
	v_add_u32_e32 v27, 0x40000, v27
	v_lshlrev_b32_e32 v20, 16, v43
	v_and_b32_e32 v21, 0xffff0000, v43
	v_fmac_f32_e32 v20, v12, v22
	v_fmac_f32_e32 v21, v12, v23
	v_min_u32_e32 v26, v26, v28
	global_load_dword v43, v26, s[6:7]
	v_add_u32_e32 v26, 0x40000, v26
	v_min_u32_e32 v30, v30, v31
	global_load_dword v63, v30, s[8:9]
	v_add_u32_e32 v30, 0x2000, v30
	s_waitcnt vmcnt(45)
	v_mul_f32_e32 v13, 0x3fb8aa3b, v64
	v_fma_f32 v14, v64, s101, -v13
	v_rndne_f32_e32 v15, v13
	v_fmac_f32_e32 v14, 0x32a5705f, v64
	v_sub_f32_e32 v13, v13, v15
	v_add_f32_e32 v13, v13, v14
	v_exp_f32_e32 v13, v13
	v_cvt_i32_f32_e32 v14, v15
	v_cmp_ngt_f32_e32 vcc, 0xc2ce8ed0, v64
	v_ldexp_f32 v13, v13, v14
	s_nop 0
	v_cndmask_b32_e32 v13, 0, v13, vcc
	v_cmp_nlt_f32_e32 vcc, 0x42b17218, v64
	s_nop 1
	v_cndmask_b32_e32 v12, v16, v13, vcc
	v_bfe_u32 v24, v20, 16, 1
	v_add3_u32 v24, v20, v24, s99
	v_bfe_u32 v25, v21, 16, 1
	v_lshrrev_b32_e32 v24, 16, v24
	v_add3_u32 v25, v21, v25, s99
	v_and_or_b32 v24, v25, s100, v24
	global_store_dword v27, v24, s[6:7]
	v_add_u32_e32 v27, 0x40000, v27
	v_lshlrev_b32_e32 v22, 16, v44
	v_and_b32_e32 v23, 0xffff0000, v44
	v_fmac_f32_e32 v22, v12, v20
	v_fmac_f32_e32 v23, v12, v21
	v_min_u32_e32 v26, v26, v28
	global_load_dword v44, v26, s[6:7]
	v_add_u32_e32 v26, 0x40000, v26
	v_min_u32_e32 v30, v30, v31
	global_load_dword v64, v30, s[8:9]
	v_add_u32_e32 v30, 0x2000, v30
	s_waitcnt vmcnt(45)
	v_mul_f32_e32 v13, 0x3fb8aa3b, v65
	v_fma_f32 v14, v65, s101, -v13
	v_rndne_f32_e32 v15, v13
	v_fmac_f32_e32 v14, 0x32a5705f, v65
	v_sub_f32_e32 v13, v13, v15
	v_add_f32_e32 v13, v13, v14
	v_exp_f32_e32 v13, v13
	v_cvt_i32_f32_e32 v14, v15
	v_cmp_ngt_f32_e32 vcc, 0xc2ce8ed0, v65
	v_ldexp_f32 v13, v13, v14
	s_nop 0
	v_cndmask_b32_e32 v13, 0, v13, vcc
	v_cmp_nlt_f32_e32 vcc, 0x42b17218, v65
	s_nop 1
	v_cndmask_b32_e32 v12, v16, v13, vcc
	v_bfe_u32 v24, v22, 16, 1
	v_add3_u32 v24, v22, v24, s99
	v_bfe_u32 v25, v23, 16, 1
	v_lshrrev_b32_e32 v24, 16, v24
	v_add3_u32 v25, v23, v25, s99
	v_and_or_b32 v24, v25, s100, v24
	global_store_dword v27, v24, s[6:7]
	v_add_u32_e32 v27, 0x40000, v27
	v_lshlrev_b32_e32 v20, 16, v45
	v_and_b32_e32 v21, 0xffff0000, v45
	v_fmac_f32_e32 v20, v12, v22
	v_fmac_f32_e32 v21, v12, v23
	v_min_u32_e32 v26, v26, v28
	global_load_dword v45, v26, s[6:7]
	v_add_u32_e32 v26, 0x40000, v26
	v_min_u32_e32 v30, v30, v31
	global_load_dword v65, v30, s[8:9]
	v_add_u32_e32 v30, 0x2000, v30
	s_waitcnt vmcnt(45)
	v_mul_f32_e32 v13, 0x3fb8aa3b, v66
	v_fma_f32 v14, v66, s101, -v13
	v_rndne_f32_e32 v15, v13
	v_fmac_f32_e32 v14, 0x32a5705f, v66
	v_sub_f32_e32 v13, v13, v15
	v_add_f32_e32 v13, v13, v14
	v_exp_f32_e32 v13, v13
	v_cvt_i32_f32_e32 v14, v15
	v_cmp_ngt_f32_e32 vcc, 0xc2ce8ed0, v66
	v_ldexp_f32 v13, v13, v14
	s_nop 0
	v_cndmask_b32_e32 v13, 0, v13, vcc
	v_cmp_nlt_f32_e32 vcc, 0x42b17218, v66
	s_nop 1
	v_cndmask_b32_e32 v12, v16, v13, vcc
	v_bfe_u32 v24, v20, 16, 1
	v_add3_u32 v24, v20, v24, s99
	v_bfe_u32 v25, v21, 16, 1
	v_lshrrev_b32_e32 v24, 16, v24
	v_add3_u32 v25, v21, v25, s99
	v_and_or_b32 v24, v25, s100, v24
	global_store_dword v27, v24, s[6:7]
	v_add_u32_e32 v27, 0x40000, v27
	v_lshlrev_b32_e32 v22, 16, v46
	v_and_b32_e32 v23, 0xffff0000, v46
	v_fmac_f32_e32 v22, v12, v20
	v_fmac_f32_e32 v23, v12, v21
	v_min_u32_e32 v26, v26, v28
	global_load_dword v46, v26, s[6:7]
	v_add_u32_e32 v26, 0x40000, v26
	v_min_u32_e32 v30, v30, v31
	global_load_dword v66, v30, s[8:9]
	v_add_u32_e32 v30, 0x2000, v30
	s_waitcnt vmcnt(45)
; __device__ __forceinline__ unsigned pack2(float a, float b) { return (unsigned)f2bf(a) | ((unsigned)f2bf(b) << 16); }
; __device__ __forceinline__ float lo16(unsigned v) { return __uint_as_float(v << 16); }
; __device__ __forceinline__ float hi16(unsigned v) { return __uint_as_float(v & 0xffff0000u); }
; __device__ __forceinline__ void phase_scan(const Params& p, unsigned* st, int npairs, int pairs_per_head_shift, int mode) {
;     ...
;           v[i] = st[(size_t)c * npairs + e];
;           dc[i] = (mode == 0) ? expf(acs[((size_t)c * 16 + h) * 128 + 127]) : rdec;
;         } else { v[i] = 0; dc[i] = 0.f; }
;       }
; #pragma unroll
;       for (int i = 0; i < 8; i++) {
;         int c = c0 + i;
;         if (c < NCH) {
;           *(st + (size_t)c * npairs + e) = pack2(r0, r1);
;           r0 = r0 * dc[i] + lo16(v[i]);
;           r1 = r1 * dc[i] + hi16(v[i]);
	v_mul_f32_e32 v13, 0x3fb8aa3b, v67
	v_fma_f32 v14, v67, s101, -v13
	v_rndne_f32_e32 v15, v13
	v_fmac_f32_e32 v14, 0x32a5705f, v67
	v_sub_f32_e32 v13, v13, v15
	v_add_f32_e32 v13, v13, v14
	v_exp_f32_e32 v13, v13
	v_cvt_i32_f32_e32 v14, v15
	v_cmp_ngt_f32_e32 vcc, 0xc2ce8ed0, v67
	v_ldexp_f32 v13, v13, v14
	s_nop 0
	v_cndmask_b32_e32 v13, 0, v13, vcc
	v_cmp_nlt_f32_e32 vcc, 0x42b17218, v67
	s_nop 1
	v_cndmask_b32_e32 v12, v16, v13, vcc
	v_bfe_u32 v24, v22, 16, 1
	v_add3_u32 v24, v22, v24, s99
	v_bfe_u32 v25, v23, 16, 1
	v_lshrrev_b32_e32 v24, 16, v24
	v_add3_u32 v25, v23, v25, s99
	v_and_or_b32 v24, v25, s100, v24
	global_store_dword v27, v24, s[6:7]
	v_add_u32_e32 v27, 0x40000, v27
	v_lshlrev_b32_e32 v20, 16, v47
	v_and_b32_e32 v21, 0xffff0000, v47
	v_fmac_f32_e32 v20, v12, v22
	v_fmac_f32_e32 v21, v12, v23
	v_min_u32_e32 v26, v26, v28
	global_load_dword v47, v26, s[6:7]
	v_add_u32_e32 v26, 0x40000, v26
	v_min_u32_e32 v30, v30, v31
	global_load_dword v67, v30, s[8:9]
	v_add_u32_e32 v30, 0x2000, v30
	s_waitcnt vmcnt(45)
	v_mul_f32_e32 v13, 0x3fb8aa3b, v68
	v_fma_f32 v14, v68, s101, -v13
	v_rndne_f32_e32 v15, v13
	v_fmac_f32_e32 v14, 0x32a5705f, v68
	v_sub_f32_e32 v13, v13, v15
	v_add_f32_e32 v13, v13, v14
	v_exp_f32_e32 v13, v13
	v_cvt_i32_f32_e32 v14, v15
	v_cmp_ngt_f32_e32 vcc, 0xc2ce8ed0, v68
	v_ldexp_f32 v13, v13, v14
	s_nop 0
	v_cndmask_b32_e32 v13, 0, v13, vcc
	v_cmp_nlt_f32_e32 vcc, 0x42b17218, v68
	s_nop 1
	v_cndmask_b32_e32 v12, v16, v13, vcc
	v_bfe_u32 v24, v20, 16, 1
	v_add3_u32 v24, v20, v24, s99
	v_bfe_u32 v25, v21, 16, 1
	v_lshrrev_b32_e32 v24, 16, v24
	v_add3_u32 v25, v21, v25, s99
	v_and_or_b32 v24, v25, s100, v24
	global_store_dword v27, v24, s[6:7]
	v_add_u32_e32 v27, 0x40000, v27
	v_lshlrev_b32_e32 v22, 16, v48
	v_and_b32_e32 v23, 0xffff0000, v48
	v_fmac_f32_e32 v22, v12, v20
	v_fmac_f32_e32 v23, v12, v21
	v_min_u32_e32 v26, v26, v28
	global_load_dword v48, v26, s[6:7]
	v_add_u32_e32 v26, 0x40000, v26
	v_min_u32_e32 v30, v30, v31
	global_load_dword v68, v30, s[8:9]
	v_add_u32_e32 v30, 0x2000, v30
	s_waitcnt vmcnt(45)
	v_mul_f32_e32 v13, 0x3fb8aa3b, v69
	v_fma_f32 v14, v69, s101, -v13
	v_rndne_f32_e32 v15, v13
	v_fmac_f32_e32 v14, 0x32a5705f, v69
	v_sub_f32_e32 v13, v13, v15
	v_add_f32_e32 v13, v13, v14
	v_exp_f32_e32 v13, v13
	v_cvt_i32_f32_e32 v14, v15
	v_cmp_ngt_f32_e32 vcc, 0xc2ce8ed0, v69
	v_ldexp_f32 v13, v13, v14
	s_nop 0
	v_cndmask_b32_e32 v13, 0, v13, vcc
	v_cmp_nlt_f32_e32 vcc, 0x42b17218, v69
	s_nop 1
	v_cndmask_b32_e32 v12, v16, v13, vcc
	v_bfe_u32 v24, v22, 16, 1
	v_add3_u32 v24, v22, v24, s99
	v_bfe_u32 v25, v23, 16, 1
	v_lshrrev_b32_e32 v24, 16, v24
	v_add3_u32 v25, v23, v25, s99
	v_and_or_b32 v24, v25, s100, v24
	global_store_dword v27, v24, s[6:7]
	v_add_u32_e32 v27, 0x40000, v27
	v_lshlrev_b32_e32 v20, 16, v49
	v_and_b32_e32 v21, 0xffff0000, v49
	v_fmac_f32_e32 v20, v12, v22
	v_fmac_f32_e32 v21, v12, v23
	v_min_u32_e32 v26, v26, v28
	global_load_dword v49, v26, s[6:7]
	v_add_u32_e32 v26, 0x40000, v26
	v_min_u32_e32 v30, v30, v31
	global_load_dword v69, v30, s[8:9]
	v_add_u32_e32 v30, 0x2000, v30
	s_waitcnt vmcnt(45)
	v_mul_f32_e32 v13, 0x3fb8aa3b, v70
	v_fma_f32 v14, v70, s101, -v13
	v_rndne_f32_e32 v15, v13
	v_fmac_f32_e32 v14, 0x32a5705f, v70
	v_sub_f32_e32 v13, v13, v15
	v_add_f32_e32 v13, v13, v14
	v_exp_f32_e32 v13, v13
	v_cvt_i32_f32_e32 v14, v15
	v_cmp_ngt_f32_e32 vcc, 0xc2ce8ed0, v70
	v_ldexp_f32 v13, v13, v14
	s_nop 0
	v_cndmask_b32_e32 v13, 0, v13, vcc
	v_cmp_nlt_f32_e32 vcc, 0x42b17218, v70
	s_nop 1
	v_cndmask_b32_e32 v12, v16, v13, vcc
	v_bfe_u32 v24, v20, 16, 1
	v_add3_u32 v24, v20, v24, s99
	v_bfe_u32 v25, v21, 16, 1
	v_lshrrev_b32_e32 v24, 16, v24
	v_add3_u32 v25, v21, v25, s99
	v_and_or_b32 v24, v25, s100, v24
	global_store_dword v27, v24, s[6:7]
	v_add_u32_e32 v27, 0x40000, v27
	v_lshlrev_b32_e32 v22, 16, v50
	v_and_b32_e32 v23, 0xffff0000, v50
	v_fmac_f32_e32 v22, v12, v20
	v_fmac_f32_e32 v23, v12, v21
	v_min_u32_e32 v26, v26, v28
	global_load_dword v50, v26, s[6:7]
	v_add_u32_e32 v26, 0x40000, v26
	v_min_u32_e32 v30, v30, v31
	global_load_dword v70, v30, s[8:9]
	v_add_u32_e32 v30, 0x2000, v30
	s_waitcnt vmcnt(45)
	v_mul_f32_e32 v13, 0x3fb8aa3b, v71
	v_fma_f32 v14, v71, s101, -v13
	v_rndne_f32_e32 v15, v13
	v_fmac_f32_e32 v14, 0x32a5705f, v71
	v_sub_f32_e32 v13, v13, v15
	v_add_f32_e32 v13, v13, v14
	v_exp_f32_e32 v13, v13
	v_cvt_i32_f32_e32 v14, v15
	v_cmp_ngt_f32_e32 vcc, 0xc2ce8ed0, v71
	v_ldexp_f32 v13, v13, v14
	s_nop 0
	v_cndmask_b32_e32 v13, 0, v13, vcc
	v_cmp_nlt_f32_e32 vcc, 0x42b17218, v71
	s_nop 1
	v_cndmask_b32_e32 v12, v16, v13, vcc
	v_bfe_u32 v24, v22, 16, 1
	v_add3_u32 v24, v22, v24, s99
	v_bfe_u32 v25, v23, 16, 1
	v_lshrrev_b32_e32 v24, 16, v24
	v_add3_u32 v25, v23, v25, s99
	v_and_or_b32 v24, v25, s100, v24
	global_store_dword v27, v24, s[6:7]
	v_add_u32_e32 v27, 0x40000, v27
	v_lshlrev_b32_e32 v20, 16, v51
	v_and_b32_e32 v21, 0xffff0000, v51
	v_fmac_f32_e32 v20, v12, v22
	v_fmac_f32_e32 v21, v12, v23
	v_min_u32_e32 v26, v26, v28
	global_load_dword v51, v26, s[6:7]
	v_add_u32_e32 v26, 0x40000, v26
	v_min_u32_e32 v30, v30, v31
	global_load_dword v71, v30, s[8:9]
	v_add_u32_e32 v30, 0x2000, v30
	s_waitcnt vmcnt(45)
; __device__ __forceinline__ unsigned pack2(float a, float b) { return (unsigned)f2bf(a) | ((unsigned)f2bf(b) << 16); }
; __device__ __forceinline__ float lo16(unsigned v) { return __uint_as_float(v << 16); }
; __device__ __forceinline__ float hi16(unsigned v) { return __uint_as_float(v & 0xffff0000u); }
; __device__ __forceinline__ void phase_scan(const Params& p, unsigned* st, int npairs, int pairs_per_head_shift, int mode) {
;     ...
;           v[i] = st[(size_t)c * npairs + e];
;           dc[i] = (mode == 0) ? expf(acs[((size_t)c * 16 + h) * 128 + 127]) : rdec;
;         } else { v[i] = 0; dc[i] = 0.f; }
;       }
; #pragma unroll
;       for (int i = 0; i < 8; i++) {
;         int c = c0 + i;
;         if (c < NCH) {
;           *(st + (size_t)c * npairs + e) = pack2(r0, r1);
;           r0 = r0 * dc[i] + lo16(v[i]);
;           r1 = r1 * dc[i] + hi16(v[i]);
;         }
;       }
;     }
;   }
	v_mul_f32_e32 v13, 0x3fb8aa3b, v72
	v_fma_f32 v14, v72, s101, -v13
	v_rndne_f32_e32 v15, v13
	v_fmac_f32_e32 v14, 0x32a5705f, v72
	v_sub_f32_e32 v13, v13, v15
	v_add_f32_e32 v13, v13, v14
	v_exp_f32_e32 v13, v13
	v_cvt_i32_f32_e32 v14, v15
	v_cmp_ngt_f32_e32 vcc, 0xc2ce8ed0, v72
	v_ldexp_f32 v13, v13, v14
	s_nop 0
	v_cndmask_b32_e32 v13, 0, v13, vcc
	v_cmp_nlt_f32_e32 vcc, 0x42b17218, v72
	s_nop 1
	v_cndmask_b32_e32 v12, v16, v13, vcc
	v_bfe_u32 v24, v20, 16, 1
	v_add3_u32 v24, v20, v24, s99
	v_bfe_u32 v25, v21, 16, 1
	v_lshrrev_b32_e32 v24, 16, v24
	v_add3_u32 v25, v21, v25, s99
	v_and_or_b32 v24, v25, s100, v24
	global_store_dword v27, v24, s[6:7]
	v_add_u32_e32 v27, 0x40000, v27
	v_lshlrev_b32_e32 v22, 16, v52
	v_and_b32_e32 v23, 0xffff0000, v52
	v_fmac_f32_e32 v22, v12, v20
	v_fmac_f32_e32 v23, v12, v21
	v_min_u32_e32 v26, v26, v28
	global_load_dword v52, v26, s[6:7]
	v_add_u32_e32 v26, 0x40000, v26
	v_min_u32_e32 v30, v30, v31
	global_load_dword v72, v30, s[8:9]
	v_add_u32_e32 v30, 0x2000, v30
	s_waitcnt vmcnt(45)
	v_mul_f32_e32 v13, 0x3fb8aa3b, v73
	v_fma_f32 v14, v73, s101, -v13
	v_rndne_f32_e32 v15, v13
	v_fmac_f32_e32 v14, 0x32a5705f, v73
	v_sub_f32_e32 v13, v13, v15
	v_add_f32_e32 v13, v13, v14
	v_exp_f32_e32 v13, v13
	v_cvt_i32_f32_e32 v14, v15
	v_cmp_ngt_f32_e32 vcc, 0xc2ce8ed0, v73
	v_ldexp_f32 v13, v13, v14
	s_nop 0
	v_cndmask_b32_e32 v13, 0, v13, vcc
	v_cmp_nlt_f32_e32 vcc, 0x42b17218, v73
	s_nop 1
	v_cndmask_b32_e32 v12, v16, v13, vcc
	v_bfe_u32 v24, v22, 16, 1
	v_add3_u32 v24, v22, v24, s99
	v_bfe_u32 v25, v23, 16, 1
	v_lshrrev_b32_e32 v24, 16, v24
	v_add3_u32 v25, v23, v25, s99
	v_and_or_b32 v24, v25, s100, v24
	global_store_dword v27, v24, s[6:7]
	v_add_u32_e32 v27, 0x40000, v27
	v_lshlrev_b32_e32 v20, 16, v53
	v_and_b32_e32 v21, 0xffff0000, v53
	v_fmac_f32_e32 v20, v12, v22
	v_fmac_f32_e32 v21, v12, v23
	v_min_u32_e32 v26, v26, v28
	global_load_dword v53, v26, s[6:7]
	v_add_u32_e32 v26, 0x40000, v26
	v_min_u32_e32 v30, v30, v31
	global_load_dword v73, v30, s[8:9]
	v_add_u32_e32 v30, 0x2000, v30
	s_waitcnt vmcnt(45)
	v_mul_f32_e32 v13, 0x3fb8aa3b, v74
	v_fma_f32 v14, v74, s101, -v13
	v_rndne_f32_e32 v15, v13
	v_fmac_f32_e32 v14, 0x32a5705f, v74
	v_sub_f32_e32 v13, v13, v15
	v_add_f32_e32 v13, v13, v14
	v_exp_f32_e32 v13, v13
	v_cvt_i32_f32_e32 v14, v15
	v_cmp_ngt_f32_e32 vcc, 0xc2ce8ed0, v74
	v_ldexp_f32 v13, v13, v14
	s_nop 0
	v_cndmask_b32_e32 v13, 0, v13, vcc
	v_cmp_nlt_f32_e32 vcc, 0x42b17218, v74
	s_nop 1
	v_cndmask_b32_e32 v12, v16, v13, vcc
	v_bfe_u32 v24, v20, 16, 1
	v_add3_u32 v24, v20, v24, s99
	v_bfe_u32 v25, v21, 16, 1
	v_lshrrev_b32_e32 v24, 16, v24
	v_add3_u32 v25, v21, v25, s99
	v_and_or_b32 v24, v25, s100, v24
	global_store_dword v27, v24, s[6:7]
	v_add_u32_e32 v27, 0x40000, v27
	v_lshlrev_b32_e32 v22, 16, v54
	v_and_b32_e32 v23, 0xffff0000, v54
	v_fmac_f32_e32 v22, v12, v20
	v_fmac_f32_e32 v23, v12, v21
	v_min_u32_e32 v26, v26, v28
	global_load_dword v54, v26, s[6:7]
	v_add_u32_e32 v26, 0x40000, v26
	v_min_u32_e32 v30, v30, v31
	global_load_dword v74, v30, s[8:9]
	v_add_u32_e32 v30, 0x2000, v30
	s_waitcnt vmcnt(45)
	v_mul_f32_e32 v13, 0x3fb8aa3b, v75
	v_fma_f32 v14, v75, s101, -v13
	v_rndne_f32_e32 v15, v13
	v_fmac_f32_e32 v14, 0x32a5705f, v75
	v_sub_f32_e32 v13, v13, v15
	v_add_f32_e32 v13, v13, v14
	v_exp_f32_e32 v13, v13
	v_cvt_i32_f32_e32 v14, v15
	v_cmp_ngt_f32_e32 vcc, 0xc2ce8ed0, v75
	v_ldexp_f32 v13, v13, v14
	s_nop 0
	v_cndmask_b32_e32 v13, 0, v13, vcc
	v_cmp_nlt_f32_e32 vcc, 0x42b17218, v75
	s_nop 1
	v_cndmask_b32_e32 v12, v16, v13, vcc
	v_bfe_u32 v24, v22, 16, 1
	v_add3_u32 v24, v22, v24, s99
	v_bfe_u32 v25, v23, 16, 1
	v_lshrrev_b32_e32 v24, 16, v24
	v_add3_u32 v25, v23, v25, s99
	v_and_or_b32 v24, v25, s100, v24
	global_store_dword v27, v24, s[6:7]
	v_add_u32_e32 v27, 0x40000, v27
	v_lshlrev_b32_e32 v20, 16, v55
	v_and_b32_e32 v21, 0xffff0000, v55
	v_fmac_f32_e32 v20, v12, v22
	v_fmac_f32_e32 v21, v12, v23
	v_min_u32_e32 v26, v26, v28
	global_load_dword v55, v26, s[6:7]
	v_add_u32_e32 v26, 0x40000, v26
	v_min_u32_e32 v30, v30, v31
	global_load_dword v75, v30, s[8:9]
	v_add_u32_e32 v30, 0x2000, v30
	s_add_i32 s98, s98, -1
	s_cmp_lg_u32 s98, 0
	s_cbranch_scc1 .Lscan_ssd0_loop
	v_bfe_u32 v24, v20, 16, 1
	v_add3_u32 v24, v20, v24, s99
	v_bfe_u32 v25, v21, 16, 1
	v_lshrrev_b32_e32 v24, 16, v24
	v_add3_u32 v25, v21, v25, s99
	v_and_or_b32 v24, v25, s100, v24
	global_store_dword v27, v24, s[6:7]
	s_waitcnt vmcnt(0)
	v_add_u32_e32 v0, s1, v0
	v_cmp_lt_i32_e32 vcc, s90, v0
	s_or_b64 s[10:11], vcc, s[10:11]
	s_andn2_b64 exec, exec, s[10:11]
	s_cbranch_execnz .LBB0_1190

; __device__ __forceinline__ void phase_ssd_out(const Params& p, int layer, unsigned char* smem) {
;     ...
;           if (wn == ks) {
;             const int t2 = relaunder(tid);
;             const int lane = t2 & 63, hi = lane >> 5, cl = lane & 31, wm = t2 >> 7;
; #pragma unroll
;             for (int mt = 0; mt < 2; mt++)
; #pragma unroll
;               for (int nt = 0; nt < 2; nt++)
; #pragma unroll
;                 for (int i = 0; i < 16; i++) {
;                   int row = wm * 64 + mt * 32 + (i & 3) + 8 * (i >> 2) + 4 * hi;
;                   int cloc = nt * 32 + cl;
;                   int s = ks * 64 + cloc;
;                   float val = 0.f;
;                   if (row >= s) val = cb[mt][nt][i] * __expf(sAcs[row] - sAcs[s]) * sDt[s];
;                   if (row == s) val += Dh;
;                   sA[row * LDK + cloc] = f2bf(val);
;                   if ((i & 7) == 7) __builtin_amdgcn_sched_barrier(0);
;                 }
.LBB0_1247:
	s_andn2_b64 vcc, exec, s[18:19]
	s_cbranch_vccnz .LBB0_1244
	v_cmp_eq_u32_e32 vcc, s1, v164
	s_and_saveexec_b64 s[18:19], vcc
	s_cbranch_execz .LBB0_1243
	v_mov_b32_e32 v96, v112
	v_mov_b32_e32 v100, 0
	v_and_b32_e32 v101, 31, v96
	v_ashrrev_i32_e32 v99, 1, v96
	v_lshrrev_b32_e32 v96, 3, v96
	v_and_b32_e32 v96, 4, v96
	v_or_b32_e32 v98, v101, v113
	v_and_or_b32 v99, v99, s29, v96
	v_lshlrev_b32_e32 v97, 2, v98
	v_cmp_ge_i32_e32 vcc, v99, v98
	v_lshlrev_b32_e32 v96, 2, v99
	v_mov_b32_e32 v103, 0
	ds_read_b128 v[208:211], v96 offset:36864
	ds_read_b128 v[212:215], v96 offset:36896
	ds_read_b128 v[216:219], v96 offset:36928
	ds_read_b128 v[220:223], v96 offset:36960
	ds_read_b128 v[224:227], v96 offset:36992
	ds_read_b128 v[232:235], v96 offset:37024
	ds_read_b128 v[236:239], v96 offset:37056
	ds_read_b128 v[240:243], v96 offset:37088
	ds_read2st64_b32 v[244:245], v97 offset0:144 offset1:146
	s_waitcnt lgkmcnt(0)
	s_and_saveexec_b64 s[20:21], vcc
	s_cbranch_execz .LBB0_1251
	v_mov_b32_e32 v104, v208
	v_mov_b32_e32 v102, v244
	v_mov_b32_e32 v103, v245
	v_sub_f32_e32 v102, v104, v102
	v_mul_f32_e32 v102, 0x3fb8aa3b, v102
	v_exp_f32_e32 v102, v102
	s_nop 0
	v_mul_f32_e32 v102, v0, v102
	v_mul_f32_e32 v103, v103, v102
.LBB0_1251:
	s_or_b64 exec, exec, s[20:21]
	s_waitcnt vmcnt(0)
	v_add_f32_e32 v104, v183, v103
	v_cmp_eq_u32_e32 vcc, v99, v98
	v_lshlrev_b32_e32 v102, 1, v101
	s_nop 0
	v_cndmask_b32_e32 v103, v103, v104, vcc
	v_bfe_u32 v104, v103, 16, 1
	v_add3_u32 v104, v103, v104, s28
	v_mul_lo_u32 v103, v99, s25
	v_add_u32_e32 v103, v102, v103
	ds_write_b16_d16_hi v103, v104
	v_or_b32_e32 v104, 1, v99
	v_cmp_ge_i32_e32 vcc, v104, v98
	s_and_saveexec_b64 s[20:21], vcc
	s_cbranch_execz .LBB0_1253
	v_mov_b32_e32 v100, v209
	v_mov_b32_e32 v106, v244
	v_mov_b32_e32 v107, v245
	v_sub_f32_e32 v100, v100, v106
	v_mul_f32_e32 v100, 0x3fb8aa3b, v100
	v_exp_f32_e32 v100, v100
	s_nop 0
	v_mul_f32_e32 v100, v1, v100
	v_mul_f32_e32 v100, v107, v100
.LBB0_1253:
	s_or_b64 exec, exec, s[20:21]
	v_add_f32_e32 v105, v183, v100
	v_cmp_eq_u32_e32 vcc, v104, v98
	v_mov_b32_e32 v106, 0
	s_nop 0
	v_cndmask_b32_e32 v100, v100, v105, vcc
	v_bfe_u32 v105, v100, 16, 1
	v_add3_u32 v100, v100, v105, s28
	v_or_b32_e32 v105, 2, v99
	ds_write_b16_d16_hi v103, v100 offset:144
	v_cmp_ge_i32_e32 vcc, v105, v98
	v_mov_b32_e32 v100, 0
	s_and_saveexec_b64 s[20:21], vcc
	s_cbranch_execz .LBB0_1255
	v_mov_b32_e32 v108, v210
	v_mov_b32_e32 v106, v244
	v_mov_b32_e32 v107, v245
	v_sub_f32_e32 v106, v108, v106
	v_mul_f32_e32 v106, 0x3fb8aa3b, v106
	v_exp_f32_e32 v106, v106
	s_nop 0
	v_mul_f32_e32 v106, v2, v106
	v_mul_f32_e32 v106, v107, v106
.LBB0_1255:
	s_or_b64 exec, exec, s[20:21]
	v_add_f32_e32 v107, v183, v106
	v_cmp_eq_u32_e32 vcc, v105, v98
	s_nop 1
	v_cndmask_b32_e32 v106, v106, v107, vcc
	v_bfe_u32 v107, v106, 16, 1
	v_add3_u32 v106, v106, v107, s28
	ds_write_b16_d16_hi v103, v106 offset:288
	v_or_b32_e32 v106, 3, v99
	v_cmp_ge_i32_e32 vcc, v106, v98
	s_and_saveexec_b64 s[20:21], vcc
	s_cbranch_execz .LBB0_1257
	v_mov_b32_e32 v100, v211
	v_mov_b32_e32 v108, v244
	v_mov_b32_e32 v109, v245
	v_sub_f32_e32 v100, v100, v108
	v_mul_f32_e32 v100, 0x3fb8aa3b, v100
	v_exp_f32_e32 v100, v100
	s_nop 0
	v_mul_f32_e32 v100, v3, v100
	v_mul_f32_e32 v100, v109, v100
.LBB0_1257:
	s_or_b64 exec, exec, s[20:21]
	v_add_f32_e32 v107, v183, v100
	v_cmp_eq_u32_e32 vcc, v106, v98
	v_mov_b32_e32 v108, 0
	s_nop 0
	v_cndmask_b32_e32 v100, v100, v107, vcc
	v_bfe_u32 v107, v100, 16, 1
	v_add3_u32 v100, v100, v107, s28
	v_or_b32_e32 v107, 8, v99
	ds_write_b16_d16_hi v103, v100 offset:432
	v_cmp_ge_i32_e32 vcc, v107, v98
	v_mov_b32_e32 v100, 0
	s_and_saveexec_b64 s[20:21], vcc
	s_cbranch_execz .LBB0_1259
	v_mov_b32_e32 v110, v212
	v_mov_b32_e32 v108, v244
	v_mov_b32_e32 v109, v245
	v_sub_f32_e32 v108, v110, v108
	v_mul_f32_e32 v108, 0x3fb8aa3b, v108
	v_exp_f32_e32 v108, v108
	s_nop 0
	v_mul_f32_e32 v108, v4, v108
	v_mul_f32_e32 v108, v109, v108
.LBB0_1259:
	s_or_b64 exec, exec, s[20:21]
	v_add_f32_e32 v109, v183, v108
	v_cmp_eq_u32_e32 vcc, v107, v98
	s_nop 1
	v_cndmask_b32_e32 v108, v108, v109, vcc
	v_bfe_u32 v109, v108, 16, 1
	v_add3_u32 v108, v108, v109, s28
	ds_write_b16_d16_hi v103, v108 offset:1152
	v_or_b32_e32 v108, 9, v99
	v_cmp_ge_i32_e32 vcc, v108, v98
	s_and_saveexec_b64 s[20:21], vcc
	s_cbranch_execz .LBB0_1261
	v_mov_b32_e32 v100, v213
	v_mov_b32_e32 v110, v244
	v_mov_b32_e32 v111, v245
	v_sub_f32_e32 v100, v100, v110
	v_mul_f32_e32 v100, 0x3fb8aa3b, v100
	v_exp_f32_e32 v100, v100
	s_nop 0
	v_mul_f32_e32 v100, v5, v100
	v_mul_f32_e32 v100, v111, v100
.LBB0_1261:
	s_or_b64 exec, exec, s[20:21]
	v_add_f32_e32 v109, v183, v100
	v_cmp_eq_u32_e32 vcc, v108, v98
	v_mov_b32_e32 v110, 0
	s_nop 0
	v_cndmask_b32_e32 v100, v100, v109, vcc
	v_bfe_u32 v109, v100, 16, 1
	v_add3_u32 v100, v100, v109, s28
	v_or_b32_e32 v109, 10, v99
	ds_write_b16_d16_hi v103, v100 offset:1296
	v_cmp_ge_i32_e32 vcc, v109, v98
	v_mov_b32_e32 v100, 0
	s_and_saveexec_b64 s[20:21], vcc
	s_cbranch_execz .LBB0_1263
	v_mov_b32_e32 v114, v214
	v_mov_b32_e32 v110, v244
	v_mov_b32_e32 v111, v245
	v_sub_f32_e32 v110, v114, v110
	v_mul_f32_e32 v110, 0x3fb8aa3b, v110
	v_exp_f32_e32 v110, v110
	s_nop 0
	v_mul_f32_e32 v110, v6, v110
	v_mul_f32_e32 v110, v111, v110
.LBB0_1263:
	s_or_b64 exec, exec, s[20:21]
	v_add_f32_e32 v111, v183, v110
	v_cmp_eq_u32_e32 vcc, v109, v98
	s_nop 1
	v_cndmask_b32_e32 v110, v110, v111, vcc
	v_bfe_u32 v111, v110, 16, 1
	v_add3_u32 v110, v110, v111, s28
	ds_write_b16_d16_hi v103, v110 offset:1440
	v_or_b32_e32 v110, 11, v99
	v_cmp_ge_i32_e32 vcc, v110, v98
	s_and_saveexec_b64 s[20:21], vcc
	s_cbranch_execz .LBB0_1265
	v_mov_b32_e32 v100, v215
	v_mov_b32_e32 v184, v244
	v_mov_b32_e32 v185, v245
	v_sub_f32_e32 v100, v100, v184
	v_mul_f32_e32 v100, 0x3fb8aa3b, v100
	v_exp_f32_e32 v100, v100
	s_nop 0
	v_mul_f32_e32 v100, v7, v100
	v_mul_f32_e32 v100, v185, v100
; __device__ __forceinline__ void phase_ssd_out(const Params& p, int layer, unsigned char* smem) {
;     ...
;           if (wn == ks) {
;             const int t2 = relaunder(tid);
;             const int lane = t2 & 63, hi = lane >> 5, cl = lane & 31, wm = t2 >> 7;
; #pragma unroll
;             for (int mt = 0; mt < 2; mt++)
; #pragma unroll
;               for (int nt = 0; nt < 2; nt++)
; #pragma unroll
;                 for (int i = 0; i < 16; i++) {
;                   int row = wm * 64 + mt * 32 + (i & 3) + 8 * (i >> 2) + 4 * hi;
;                   int cloc = nt * 32 + cl;
;                   int s = ks * 64 + cloc;
;                   float val = 0.f;
;                   if (row >= s) val = cb[mt][nt][i] * __expf(sAcs[row] - sAcs[s]) * sDt[s];
;                   if (row == s) val += Dh;
;                   sA[row * LDK + cloc] = f2bf(val);
;                   if ((i & 7) == 7) __builtin_amdgcn_sched_barrier(0);
;                 }
.LBB0_1265:
	s_or_b64 exec, exec, s[20:21]
	v_add_f32_e32 v111, v183, v100
	v_cmp_eq_u32_e32 vcc, v110, v98
	s_nop 1
	v_cndmask_b32_e32 v100, v100, v111, vcc
	v_bfe_u32 v111, v100, 16, 1
	v_add3_u32 v100, v100, v111, s28
	ds_write_b16_d16_hi v103, v100 offset:1584
	v_or_b32_e32 v111, 16, v99
	v_cmp_ge_i32_e32 vcc, v111, v98
	v_mov_b32_e32 v100, 0
	v_mov_b32_e32 v114, 0
	s_and_saveexec_b64 s[20:21], vcc
	s_cbranch_execz .LBB0_1267
	v_mov_b32_e32 v114, v216
	v_mov_b32_e32 v184, v244
	v_mov_b32_e32 v185, v245
	v_sub_f32_e32 v114, v114, v184
	v_mul_f32_e32 v114, 0x3fb8aa3b, v114
	v_exp_f32_e32 v114, v114
	s_nop 0
	v_mul_f32_e32 v114, v8, v114
	v_mul_f32_e32 v114, v185, v114
.LBB0_1267:
	s_or_b64 exec, exec, s[20:21]
	v_add_f32_e32 v184, v183, v114
	v_cmp_eq_u32_e32 vcc, v111, v98
	s_nop 1
	v_cndmask_b32_e32 v114, v114, v184, vcc
	v_bfe_u32 v184, v114, 16, 1
	v_add3_u32 v114, v114, v184, s28
	ds_write_b16_d16_hi v103, v114 offset:2304
	v_or_b32_e32 v114, 17, v99
	v_cmp_ge_i32_e32 vcc, v114, v98
	s_and_saveexec_b64 s[20:21], vcc
	s_cbranch_execz .LBB0_1269
	v_mov_b32_e32 v100, v217
	v_mov_b32_e32 v184, v244
	v_mov_b32_e32 v185, v245
	v_sub_f32_e32 v100, v100, v184
	v_mul_f32_e32 v100, 0x3fb8aa3b, v100
	v_exp_f32_e32 v100, v100
	s_nop 0
	v_mul_f32_e32 v100, v9, v100
	v_mul_f32_e32 v100, v185, v100
.LBB0_1269:
	s_or_b64 exec, exec, s[20:21]
	v_add_f32_e32 v184, v183, v100
	v_cmp_eq_u32_e32 vcc, v114, v98
	v_mov_b32_e32 v185, 0
	s_nop 0
	v_cndmask_b32_e32 v100, v100, v184, vcc
	v_bfe_u32 v184, v100, 16, 1
	v_add3_u32 v100, v100, v184, s28
	v_or_b32_e32 v184, 18, v99
	ds_write_b16_d16_hi v103, v100 offset:2448
	v_cmp_ge_i32_e32 vcc, v184, v98
	v_mov_b32_e32 v100, 0
	s_and_saveexec_b64 s[20:21], vcc
	s_cbranch_execz .LBB0_1271
	v_mov_b32_e32 v185, v218
	v_mov_b32_e32 v186, v244
	v_mov_b32_e32 v187, v245
	v_sub_f32_e32 v185, v185, v186
	v_mul_f32_e32 v185, 0x3fb8aa3b, v185
	v_exp_f32_e32 v185, v185
	s_nop 0
	v_mul_f32_e32 v185, v10, v185
	v_mul_f32_e32 v185, v187, v185
.LBB0_1271:
	s_or_b64 exec, exec, s[20:21]
	v_add_f32_e32 v186, v183, v185
	v_cmp_eq_u32_e32 vcc, v184, v98
	s_nop 1
	v_cndmask_b32_e32 v185, v185, v186, vcc
	v_bfe_u32 v186, v185, 16, 1
	v_add3_u32 v185, v185, v186, s28
	ds_write_b16_d16_hi v103, v185 offset:2592
	v_or_b32_e32 v185, 19, v99
	v_cmp_ge_i32_e32 vcc, v185, v98
	s_and_saveexec_b64 s[20:21], vcc
	s_cbranch_execz .LBB0_1273
	v_mov_b32_e32 v100, v219
	v_mov_b32_e32 v186, v244
	v_mov_b32_e32 v187, v245
	v_sub_f32_e32 v100, v100, v186
	v_mul_f32_e32 v100, 0x3fb8aa3b, v100
	v_exp_f32_e32 v100, v100
	s_nop 0
	v_mul_f32_e32 v100, v11, v100
	v_mul_f32_e32 v100, v187, v100
.LBB0_1273:
	s_or_b64 exec, exec, s[20:21]
	v_add_f32_e32 v186, v183, v100
	v_cmp_eq_u32_e32 vcc, v185, v98
	v_mov_b32_e32 v187, 0
	s_nop 0
	v_cndmask_b32_e32 v100, v100, v186, vcc
	v_bfe_u32 v186, v100, 16, 1
	v_add3_u32 v100, v100, v186, s28
	v_or_b32_e32 v186, 24, v99
	ds_write_b16_d16_hi v103, v100 offset:2736
	v_cmp_ge_i32_e32 vcc, v186, v98
	v_mov_b32_e32 v100, 0
	s_and_saveexec_b64 s[20:21], vcc
	s_cbranch_execz .LBB0_1275
	v_mov_b32_e32 v187, v220
	v_mov_b32_e32 v188, v244
	v_mov_b32_e32 v189, v245
	v_sub_f32_e32 v187, v187, v188
	v_mul_f32_e32 v187, 0x3fb8aa3b, v187
	v_exp_f32_e32 v187, v187
	s_nop 0
	v_mul_f32_e32 v187, v12, v187
	v_mul_f32_e32 v187, v189, v187
.LBB0_1275:
	s_or_b64 exec, exec, s[20:21]
	v_add_f32_e32 v188, v183, v187
	v_cmp_eq_u32_e32 vcc, v186, v98
	s_nop 1
	v_cndmask_b32_e32 v187, v187, v188, vcc
	v_bfe_u32 v188, v187, 16, 1
	v_add3_u32 v187, v187, v188, s28
	ds_write_b16_d16_hi v103, v187 offset:3456
	v_or_b32_e32 v187, 25, v99
	v_cmp_ge_i32_e32 vcc, v187, v98
	s_and_saveexec_b64 s[20:21], vcc
	s_cbranch_execz .LBB0_1277
	v_mov_b32_e32 v100, v221
	v_mov_b32_e32 v188, v244
	v_mov_b32_e32 v189, v245
	v_sub_f32_e32 v100, v100, v188
	v_mul_f32_e32 v100, 0x3fb8aa3b, v100
	v_exp_f32_e32 v100, v100
	s_nop 0
	v_mul_f32_e32 v100, v13, v100
	v_mul_f32_e32 v100, v189, v100
.LBB0_1277:
	s_or_b64 exec, exec, s[20:21]
	v_add_f32_e32 v188, v183, v100
	v_cmp_eq_u32_e32 vcc, v187, v98
	v_mov_b32_e32 v189, 0
	s_nop 0
	v_cndmask_b32_e32 v100, v100, v188, vcc
	v_bfe_u32 v188, v100, 16, 1
	v_add3_u32 v100, v100, v188, s28
	v_or_b32_e32 v188, 26, v99
	ds_write_b16_d16_hi v103, v100 offset:3600
	v_cmp_ge_i32_e32 vcc, v188, v98
	v_mov_b32_e32 v100, 0
	s_and_saveexec_b64 s[20:21], vcc
	s_cbranch_execz .LBB0_1279
	v_mov_b32_e32 v189, v222
	v_mov_b32_e32 v190, v244
	v_mov_b32_e32 v191, v245
	v_sub_f32_e32 v189, v189, v190
	v_mul_f32_e32 v189, 0x3fb8aa3b, v189
	v_exp_f32_e32 v189, v189
	s_nop 0
	v_mul_f32_e32 v189, v14, v189
	v_mul_f32_e32 v189, v191, v189
.LBB0_1279:
	s_or_b64 exec, exec, s[20:21]
	v_add_f32_e32 v190, v183, v189
	v_cmp_eq_u32_e32 vcc, v188, v98
	s_nop 1
	v_cndmask_b32_e32 v189, v189, v190, vcc
	v_bfe_u32 v190, v189, 16, 1
	v_add3_u32 v189, v189, v190, s28
	ds_write_b16_d16_hi v103, v189 offset:3744
	v_or_b32_e32 v189, 27, v99
	v_cmp_ge_i32_e32 vcc, v189, v98
	s_and_saveexec_b64 s[20:21], vcc
	s_cbranch_execz .LBB0_1281
	v_mov_b32_e32 v100, v223
	v_mov_b32_e32 v190, v244
	v_mov_b32_e32 v191, v245
	v_sub_f32_e32 v100, v100, v190
	v_mul_f32_e32 v100, 0x3fb8aa3b, v100
	v_exp_f32_e32 v100, v100
	s_nop 0
	v_mul_f32_e32 v100, v15, v100
	v_mul_f32_e32 v100, v191, v100
; __device__ __forceinline__ void phase_ssd_out(const Params& p, int layer, unsigned char* smem) {
;     ...
;           if (wn == ks) {
;             const int t2 = relaunder(tid);
;             const int lane = t2 & 63, hi = lane >> 5, cl = lane & 31, wm = t2 >> 7;
; #pragma unroll
;             for (int mt = 0; mt < 2; mt++)
; #pragma unroll
;               for (int nt = 0; nt < 2; nt++)
; #pragma unroll
;                 for (int i = 0; i < 16; i++) {
;                   int row = wm * 64 + mt * 32 + (i & 3) + 8 * (i >> 2) + 4 * hi;
;                   int cloc = nt * 32 + cl;
;                   int s = ks * 64 + cloc;
;                   float val = 0.f;
;                   if (row >= s) val = cb[mt][nt][i] * __expf(sAcs[row] - sAcs[s]) * sDt[s];
;                   if (row == s) val += Dh;
;                   sA[row * LDK + cloc] = f2bf(val);
;                   if ((i & 7) == 7) __builtin_amdgcn_sched_barrier(0);
;                 }
.LBB0_1281:
	s_or_b64 exec, exec, s[20:21]
	v_add_f32_e32 v190, v183, v100
	v_cmp_eq_u32_e32 vcc, v189, v98
	s_nop 1
	v_cndmask_b32_e32 v100, v100, v190, vcc
	v_bfe_u32 v190, v100, 16, 1
	v_add3_u32 v100, v100, v190, s28
	ds_write_b16_d16_hi v103, v100 offset:3888
	v_or_b32_e32 v100, v101, v177
	v_add_lshl_u32 v101, v101, v113, 2
	v_cmp_ge_i32_e32 vcc, v99, v100
	v_mov_b32_e32 v190, 0
	v_add_u32_e32 v101, 0x80, v101
	v_mov_b32_e32 v191, 0
	ds_read2st64_b32 v[246:247], v101 offset0:144 offset1:146
	s_waitcnt lgkmcnt(0)
	s_and_saveexec_b64 s[20:21], vcc
	s_cbranch_execz .LBB0_1283
	v_mov_b32_e32 v191, v208
	v_mov_b32_e32 v192, v246
	v_mov_b32_e32 v193, v247
	v_sub_f32_e32 v191, v191, v192
	v_mul_f32_e32 v191, 0x3fb8aa3b, v191
	v_exp_f32_e32 v191, v191
	s_nop 0
	v_mul_f32_e32 v191, v16, v191
	v_mul_f32_e32 v191, v193, v191
.LBB0_1283:
	s_or_b64 exec, exec, s[20:21]
	v_bfe_u32 v192, v191, 16, 1
	v_add3_u32 v191, v191, v192, s28
	v_cmp_ge_i32_e32 vcc, v104, v100
	ds_write_b16_d16_hi v103, v191 offset:64
	s_and_saveexec_b64 s[20:21], vcc
	s_cbranch_execz .LBB0_1285
	v_mov_b32_e32 v104, v209
	v_mov_b32_e32 v190, v246
	v_mov_b32_e32 v191, v247
	v_sub_f32_e32 v104, v104, v190
	v_mul_f32_e32 v104, 0x3fb8aa3b, v104
	v_exp_f32_e32 v104, v104
	s_nop 0
	v_mul_f32_e32 v104, v17, v104
	v_mul_f32_e32 v190, v191, v104
.LBB0_1285:
	s_or_b64 exec, exec, s[20:21]
	v_bfe_u32 v104, v190, 16, 1
	v_add3_u32 v104, v190, v104, s28
	ds_write_b16_d16_hi v103, v104 offset:208
	v_cmp_ge_i32_e32 vcc, v105, v100
	v_mov_b32_e32 v104, 0
	v_mov_b32_e32 v105, 0
	s_and_saveexec_b64 s[20:21], vcc
	s_cbranch_execz .LBB0_1287
	v_mov_b32_e32 v105, v210
	v_mov_b32_e32 v190, v246
	v_mov_b32_e32 v191, v247
	v_sub_f32_e32 v105, v105, v190
	v_mul_f32_e32 v105, 0x3fb8aa3b, v105
	v_exp_f32_e32 v105, v105
	s_nop 0
	v_mul_f32_e32 v105, v18, v105
	v_mul_f32_e32 v105, v191, v105
.LBB0_1287:
	s_or_b64 exec, exec, s[20:21]
	v_bfe_u32 v190, v105, 16, 1
	v_add3_u32 v105, v105, v190, s28
	v_cmp_ge_i32_e32 vcc, v106, v100
	ds_write_b16_d16_hi v103, v105 offset:352
	s_and_saveexec_b64 s[20:21], vcc
	s_cbranch_execz .LBB0_1289
	v_mov_b32_e32 v106, v211
	v_mov_b32_e32 v104, v246
	v_mov_b32_e32 v105, v247
	v_sub_f32_e32 v104, v106, v104
	v_mul_f32_e32 v104, 0x3fb8aa3b, v104
	v_exp_f32_e32 v104, v104
	s_nop 0
	v_mul_f32_e32 v104, v19, v104
	v_mul_f32_e32 v104, v105, v104
.LBB0_1289:
	s_or_b64 exec, exec, s[20:21]
	v_bfe_u32 v105, v104, 16, 1
	v_add3_u32 v104, v104, v105, s28
	ds_write_b16_d16_hi v103, v104 offset:496
	v_cmp_ge_i32_e32 vcc, v107, v100
	v_mov_b32_e32 v104, 0
	v_mov_b32_e32 v105, 0
	s_and_saveexec_b64 s[20:21], vcc
	s_cbranch_execz .LBB0_1291
	v_mov_b32_e32 v105, v212
	v_mov_b32_e32 v106, v246
	v_mov_b32_e32 v107, v247
	v_sub_f32_e32 v105, v105, v106
	v_mul_f32_e32 v105, 0x3fb8aa3b, v105
	v_exp_f32_e32 v105, v105
	s_nop 0
	v_mul_f32_e32 v105, v20, v105
	v_mul_f32_e32 v105, v107, v105
.LBB0_1291:
	s_or_b64 exec, exec, s[20:21]
	v_bfe_u32 v106, v105, 16, 1
	v_add3_u32 v105, v105, v106, s28
	v_cmp_ge_i32_e32 vcc, v108, v100
	ds_write_b16_d16_hi v103, v105 offset:1216
	s_and_saveexec_b64 s[20:21], vcc
	s_cbranch_execz .LBB0_1293
	v_mov_b32_e32 v106, v213
	v_mov_b32_e32 v104, v246
	v_mov_b32_e32 v105, v247
	v_sub_f32_e32 v104, v106, v104
	v_mul_f32_e32 v104, 0x3fb8aa3b, v104
	v_exp_f32_e32 v104, v104
	s_nop 0
	v_mul_f32_e32 v104, v21, v104
	v_mul_f32_e32 v104, v105, v104
.LBB0_1293:
	s_or_b64 exec, exec, s[20:21]
	v_bfe_u32 v105, v104, 16, 1
	v_add3_u32 v104, v104, v105, s28
	ds_write_b16_d16_hi v103, v104 offset:1360
	v_cmp_ge_i32_e32 vcc, v109, v100
	v_mov_b32_e32 v104, 0
	v_mov_b32_e32 v105, 0
	s_and_saveexec_b64 s[20:21], vcc
	s_cbranch_execz .LBB0_1295
	v_mov_b32_e32 v105, v214
	v_mov_b32_e32 v106, v246
	v_mov_b32_e32 v107, v247
	v_sub_f32_e32 v105, v105, v106
	v_mul_f32_e32 v105, 0x3fb8aa3b, v105
	v_exp_f32_e32 v105, v105
	s_nop 0
	v_mul_f32_e32 v105, v22, v105
	v_mul_f32_e32 v105, v107, v105
.LBB0_1295:
	s_or_b64 exec, exec, s[20:21]
	v_bfe_u32 v106, v105, 16, 1
	v_add3_u32 v105, v105, v106, s28
	v_cmp_ge_i32_e32 vcc, v110, v100
	ds_write_b16_d16_hi v103, v105 offset:1504
	s_and_saveexec_b64 s[20:21], vcc
	s_cbranch_execz .LBB0_1297
	v_mov_b32_e32 v106, v215
	v_mov_b32_e32 v104, v246
	v_mov_b32_e32 v105, v247
	v_sub_f32_e32 v104, v106, v104
	v_mul_f32_e32 v104, 0x3fb8aa3b, v104
	v_exp_f32_e32 v104, v104
	s_nop 0
	v_mul_f32_e32 v104, v23, v104
	v_mul_f32_e32 v104, v105, v104
.LBB0_1297:
	s_or_b64 exec, exec, s[20:21]
	v_bfe_u32 v105, v104, 16, 1
	v_add3_u32 v104, v104, v105, s28
	ds_write_b16_d16_hi v103, v104 offset:1648
	v_cmp_ge_i32_e32 vcc, v111, v100
	v_mov_b32_e32 v104, 0
	v_mov_b32_e32 v105, 0
	s_and_saveexec_b64 s[20:21], vcc
	s_cbranch_execz .LBB0_1299
	v_mov_b32_e32 v105, v216
	v_mov_b32_e32 v106, v246
	v_mov_b32_e32 v107, v247
	v_sub_f32_e32 v105, v105, v106
	v_mul_f32_e32 v105, 0x3fb8aa3b, v105
	v_exp_f32_e32 v105, v105
	s_nop 0
	v_mul_f32_e32 v105, v24, v105
	v_mul_f32_e32 v105, v107, v105
.LBB0_1299:
	s_or_b64 exec, exec, s[20:21]
	v_bfe_u32 v106, v105, 16, 1
	v_add3_u32 v105, v105, v106, s28
	v_cmp_ge_i32_e32 vcc, v114, v100
	ds_write_b16_d16_hi v103, v105 offset:2368
	s_and_saveexec_b64 s[20:21], vcc
	s_cbranch_execz .LBB0_1301
	v_mov_b32_e32 v106, v217
	v_mov_b32_e32 v104, v246
	v_mov_b32_e32 v105, v247
	v_sub_f32_e32 v104, v106, v104
	v_mul_f32_e32 v104, 0x3fb8aa3b, v104
	v_exp_f32_e32 v104, v104
	s_nop 0
	v_mul_f32_e32 v104, v25, v104
	v_mul_f32_e32 v104, v105, v104
; __device__ __forceinline__ void phase_ssd_out(const Params& p, int layer, unsigned char* smem) {
;     ...
;           if (wn == ks) {
;             const int t2 = relaunder(tid);
;             const int lane = t2 & 63, hi = lane >> 5, cl = lane & 31, wm = t2 >> 7;
; #pragma unroll
;             for (int mt = 0; mt < 2; mt++)
; #pragma unroll
;               for (int nt = 0; nt < 2; nt++)
; #pragma unroll
;                 for (int i = 0; i < 16; i++) {
;                   int row = wm * 64 + mt * 32 + (i & 3) + 8 * (i >> 2) + 4 * hi;
;                   int cloc = nt * 32 + cl;
;                   int s = ks * 64 + cloc;
;                   float val = 0.f;
;                   if (row >= s) val = cb[mt][nt][i] * __expf(sAcs[row] - sAcs[s]) * sDt[s];
;                   if (row == s) val += Dh;
;                   sA[row * LDK + cloc] = f2bf(val);
;                   if ((i & 7) == 7) __builtin_amdgcn_sched_barrier(0);
;                 }
.LBB0_1301:
	s_or_b64 exec, exec, s[20:21]
	v_bfe_u32 v105, v104, 16, 1
	v_add3_u32 v104, v104, v105, s28
	ds_write_b16_d16_hi v103, v104 offset:2512
	v_cmp_ge_i32_e32 vcc, v184, v100
	v_mov_b32_e32 v104, 0
	v_mov_b32_e32 v105, 0
	s_and_saveexec_b64 s[20:21], vcc
	s_cbranch_execz .LBB0_1303
	v_mov_b32_e32 v105, v218
	v_mov_b32_e32 v106, v246
	v_mov_b32_e32 v107, v247
	v_sub_f32_e32 v105, v105, v106
	v_mul_f32_e32 v105, 0x3fb8aa3b, v105
	v_exp_f32_e32 v105, v105
	s_nop 0
	v_mul_f32_e32 v105, v26, v105
	v_mul_f32_e32 v105, v107, v105
.LBB0_1303:
	s_or_b64 exec, exec, s[20:21]
	v_bfe_u32 v106, v105, 16, 1
	v_add3_u32 v105, v105, v106, s28
	v_cmp_ge_i32_e32 vcc, v185, v100
	ds_write_b16_d16_hi v103, v105 offset:2656
	s_and_saveexec_b64 s[20:21], vcc
	s_cbranch_execz .LBB0_1305
	v_mov_b32_e32 v106, v219
	v_mov_b32_e32 v104, v246
	v_mov_b32_e32 v105, v247
	v_sub_f32_e32 v104, v106, v104
	v_mul_f32_e32 v104, 0x3fb8aa3b, v104
	v_exp_f32_e32 v104, v104
	s_nop 0
	v_mul_f32_e32 v104, v27, v104
	v_mul_f32_e32 v104, v105, v104
.LBB0_1305:
	s_or_b64 exec, exec, s[20:21]
	v_bfe_u32 v105, v104, 16, 1
	v_add3_u32 v104, v104, v105, s28
	ds_write_b16_d16_hi v103, v104 offset:2800
	v_cmp_ge_i32_e32 vcc, v186, v100
	v_mov_b32_e32 v104, 0
	v_mov_b32_e32 v105, 0
	s_and_saveexec_b64 s[20:21], vcc
	s_cbranch_execz .LBB0_1307
	v_mov_b32_e32 v105, v220
	v_mov_b32_e32 v106, v246
	v_mov_b32_e32 v107, v247
	v_sub_f32_e32 v105, v105, v106
	v_mul_f32_e32 v105, 0x3fb8aa3b, v105
	v_exp_f32_e32 v105, v105
	s_nop 0
	v_mul_f32_e32 v105, v28, v105
	v_mul_f32_e32 v105, v107, v105
.LBB0_1307:
	s_or_b64 exec, exec, s[20:21]
	v_bfe_u32 v106, v105, 16, 1
	v_add3_u32 v105, v105, v106, s28
	v_cmp_ge_i32_e32 vcc, v187, v100
	ds_write_b16_d16_hi v103, v105 offset:3520
	s_and_saveexec_b64 s[20:21], vcc
	s_cbranch_execz .LBB0_1309
	v_mov_b32_e32 v106, v221
	v_mov_b32_e32 v104, v246
	v_mov_b32_e32 v105, v247
	v_sub_f32_e32 v104, v106, v104
	v_mul_f32_e32 v104, 0x3fb8aa3b, v104
	v_exp_f32_e32 v104, v104
	s_nop 0
	v_mul_f32_e32 v104, v29, v104
	v_mul_f32_e32 v104, v105, v104
.LBB0_1309:
	s_or_b64 exec, exec, s[20:21]
	v_bfe_u32 v105, v104, 16, 1
	v_add3_u32 v104, v104, v105, s28
	ds_write_b16_d16_hi v103, v104 offset:3664
	v_cmp_ge_i32_e32 vcc, v188, v100
	v_mov_b32_e32 v104, 0
	v_mov_b32_e32 v105, 0
	s_and_saveexec_b64 s[20:21], vcc
	s_cbranch_execz .LBB0_1311
	v_mov_b32_e32 v105, v222
	v_mov_b32_e32 v106, v246
	v_mov_b32_e32 v107, v247
	v_sub_f32_e32 v105, v105, v106
	v_mul_f32_e32 v105, 0x3fb8aa3b, v105
	v_exp_f32_e32 v105, v105
	s_nop 0
	v_mul_f32_e32 v105, v30, v105
	v_mul_f32_e32 v105, v107, v105
.LBB0_1311:
	s_or_b64 exec, exec, s[20:21]
	v_bfe_u32 v106, v105, 16, 1
	v_add3_u32 v105, v105, v106, s28
	v_cmp_ge_i32_e32 vcc, v189, v100
	ds_write_b16_d16_hi v103, v105 offset:3808
	s_and_saveexec_b64 s[20:21], vcc
	s_cbranch_execz .LBB0_1313
	v_mov_b32_e32 v106, v223
	v_mov_b32_e32 v104, v246
	v_mov_b32_e32 v105, v247
	v_sub_f32_e32 v104, v106, v104
	v_mul_f32_e32 v104, 0x3fb8aa3b, v104
	v_exp_f32_e32 v104, v104
	s_nop 0
	v_mul_f32_e32 v104, v31, v104
	v_mul_f32_e32 v104, v105, v104
.LBB0_1313:
	s_or_b64 exec, exec, s[20:21]
	v_bfe_u32 v105, v104, 16, 1
	v_add3_u32 v104, v104, v105, s28
	ds_write_b16_d16_hi v103, v104 offset:3952
	v_or_b32_e32 v187, 32, v99
	v_cmp_ge_i32_e32 vcc, v187, v98
	v_mov_b32_e32 v103, 0
	v_mov_b32_e32 v104, 0
	s_and_saveexec_b64 s[20:21], vcc
	s_cbranch_execz .LBB0_1315
	v_mov_b32_e32 v106, v224
	v_mov_b32_e32 v104, v244
	v_mov_b32_e32 v105, v245
	v_sub_f32_e32 v104, v106, v104
	v_mul_f32_e32 v104, 0x3fb8aa3b, v104
	v_exp_f32_e32 v104, v104
	s_nop 0
	v_mul_f32_e32 v104, v32, v104
	v_mul_f32_e32 v104, v105, v104
.LBB0_1315:
	s_or_b64 exec, exec, s[20:21]
	v_bfe_u32 v105, v104, 16, 1
	v_add3_u32 v104, v104, v105, s28
	v_mul_lo_u32 v105, v187, s25
	v_or_b32_e32 v188, 33, v99
	v_add_u32_e32 v102, v102, v105
	v_cmp_ge_i32_e32 vcc, v188, v98
	ds_write_b16_d16_hi v102, v104
	s_and_saveexec_b64 s[20:21], vcc
	s_cbranch_execz .LBB0_1317
	v_mov_b32_e32 v103, v225
	v_mov_b32_e32 v104, v244
	v_mov_b32_e32 v105, v245
	v_sub_f32_e32 v103, v103, v104
	v_mul_f32_e32 v103, 0x3fb8aa3b, v103
	v_exp_f32_e32 v103, v103
	s_nop 0
	v_mul_f32_e32 v103, v33, v103
	v_mul_f32_e32 v103, v105, v103
.LBB0_1317:
	s_or_b64 exec, exec, s[20:21]
	v_bfe_u32 v104, v103, 16, 1
	v_add3_u32 v103, v103, v104, s28
	v_or_b32_e32 v186, 34, v99
	ds_write_b16_d16_hi v102, v103 offset:144
	v_cmp_ge_i32_e32 vcc, v186, v98
	v_mov_b32_e32 v103, 0
	v_mov_b32_e32 v104, 0
	s_and_saveexec_b64 s[20:21], vcc
	s_cbranch_execz .LBB0_1319
	v_mov_b32_e32 v106, v226
	v_mov_b32_e32 v104, v244
	v_mov_b32_e32 v105, v245
	v_sub_f32_e32 v104, v106, v104
	v_mul_f32_e32 v104, 0x3fb8aa3b, v104
	v_exp_f32_e32 v104, v104
	s_nop 0
	v_mul_f32_e32 v104, v34, v104
	v_mul_f32_e32 v104, v105, v104
.LBB0_1319:
	s_or_b64 exec, exec, s[20:21]
	v_bfe_u32 v105, v104, 16, 1
	v_or_b32_e32 v185, 35, v99
	v_add3_u32 v104, v104, v105, s28
	v_cmp_ge_i32_e32 vcc, v185, v98
	ds_write_b16_d16_hi v102, v104 offset:288
	s_and_saveexec_b64 s[20:21], vcc
	s_cbranch_execz .LBB0_1321
	v_mov_b32_e32 v103, v227
	v_mov_b32_e32 v104, v244
	v_mov_b32_e32 v105, v245
	v_sub_f32_e32 v103, v103, v104
	v_mul_f32_e32 v103, 0x3fb8aa3b, v103
	v_exp_f32_e32 v103, v103
	s_nop 0
	v_mul_f32_e32 v103, v35, v103
	v_mul_f32_e32 v103, v105, v103
.LBB0_1321:
	s_or_b64 exec, exec, s[20:21]
	v_bfe_u32 v104, v103, 16, 1
	v_add3_u32 v103, v103, v104, s28
	v_or_b32_e32 v184, 40, v99
	ds_write_b16_d16_hi v102, v103 offset:432
	v_cmp_ge_i32_e32 vcc, v184, v98
	v_mov_b32_e32 v103, 0
	v_mov_b32_e32 v104, 0
	s_and_saveexec_b64 s[20:21], vcc
	s_cbranch_execz .LBB0_1323
	v_mov_b32_e32 v106, v232
	v_mov_b32_e32 v104, v244
	v_mov_b32_e32 v105, v245
	v_sub_f32_e32 v104, v106, v104
	v_mul_f32_e32 v104, 0x3fb8aa3b, v104
	v_exp_f32_e32 v104, v104
	s_nop 0
	v_mul_f32_e32 v104, v36, v104
	v_mul_f32_e32 v104, v105, v104
; __device__ __forceinline__ void phase_ssd_out(const Params& p, int layer, unsigned char* smem) {
;     ...
;           if (wn == ks) {
;             const int t2 = relaunder(tid);
;             const int lane = t2 & 63, hi = lane >> 5, cl = lane & 31, wm = t2 >> 7;
; #pragma unroll
;             for (int mt = 0; mt < 2; mt++)
; #pragma unroll
;               for (int nt = 0; nt < 2; nt++)
; #pragma unroll
;                 for (int i = 0; i < 16; i++) {
;                   int row = wm * 64 + mt * 32 + (i & 3) + 8 * (i >> 2) + 4 * hi;
;                   int cloc = nt * 32 + cl;
;                   int s = ks * 64 + cloc;
;                   float val = 0.f;
;                   if (row >= s) val = cb[mt][nt][i] * __expf(sAcs[row] - sAcs[s]) * sDt[s];
;                   if (row == s) val += Dh;
;                   sA[row * LDK + cloc] = f2bf(val);
;                   if ((i & 7) == 7) __builtin_amdgcn_sched_barrier(0);
;                 }
.LBB0_1323:
	s_or_b64 exec, exec, s[20:21]
	v_bfe_u32 v105, v104, 16, 1
	v_or_b32_e32 v114, 41, v99
	v_add3_u32 v104, v104, v105, s28
	v_cmp_ge_i32_e32 vcc, v114, v98
	ds_write_b16_d16_hi v102, v104 offset:1152
	s_and_saveexec_b64 s[20:21], vcc
	s_cbranch_execz .LBB0_1325
	v_mov_b32_e32 v103, v233
	v_mov_b32_e32 v104, v244
	v_mov_b32_e32 v105, v245
	v_sub_f32_e32 v103, v103, v104
	v_mul_f32_e32 v103, 0x3fb8aa3b, v103
	v_exp_f32_e32 v103, v103
	s_nop 0
	v_mul_f32_e32 v103, v37, v103
	v_mul_f32_e32 v103, v105, v103
.LBB0_1325:
	s_or_b64 exec, exec, s[20:21]
	v_bfe_u32 v104, v103, 16, 1
	v_add3_u32 v103, v103, v104, s28
	v_or_b32_e32 v111, 42, v99
	ds_write_b16_d16_hi v102, v103 offset:1296
	v_cmp_ge_i32_e32 vcc, v111, v98
	v_mov_b32_e32 v103, 0
	v_mov_b32_e32 v104, 0
	s_and_saveexec_b64 s[20:21], vcc
	s_cbranch_execz .LBB0_1327
	v_mov_b32_e32 v106, v234
	v_mov_b32_e32 v104, v244
	v_mov_b32_e32 v105, v245
	v_sub_f32_e32 v104, v106, v104
	v_mul_f32_e32 v104, 0x3fb8aa3b, v104
	v_exp_f32_e32 v104, v104
	s_nop 0
	v_mul_f32_e32 v104, v38, v104
	v_mul_f32_e32 v104, v105, v104
.LBB0_1327:
	s_or_b64 exec, exec, s[20:21]
	v_bfe_u32 v105, v104, 16, 1
	v_or_b32_e32 v110, 43, v99
	v_add3_u32 v104, v104, v105, s28
	v_cmp_ge_i32_e32 vcc, v110, v98
	ds_write_b16_d16_hi v102, v104 offset:1440
	s_and_saveexec_b64 s[20:21], vcc
	s_cbranch_execz .LBB0_1329
	v_mov_b32_e32 v103, v235
	v_mov_b32_e32 v104, v244
	v_mov_b32_e32 v105, v245
	v_sub_f32_e32 v103, v103, v104
	v_mul_f32_e32 v103, 0x3fb8aa3b, v103
	v_exp_f32_e32 v103, v103
	s_nop 0
	v_mul_f32_e32 v103, v39, v103
	v_mul_f32_e32 v103, v105, v103
.LBB0_1329:
	s_or_b64 exec, exec, s[20:21]
	v_bfe_u32 v104, v103, 16, 1
	v_add3_u32 v103, v103, v104, s28
	ds_write_b16_d16_hi v102, v103 offset:1584
	v_or_b32_e32 v109, 48, v99
	v_cmp_ge_i32_e32 vcc, v109, v98
	v_mov_b32_e32 v103, 0
	v_mov_b32_e32 v104, 0
	s_and_saveexec_b64 s[20:21], vcc
	s_cbranch_execz .LBB0_1331
	v_mov_b32_e32 v106, v236
	v_mov_b32_e32 v104, v244
	v_mov_b32_e32 v105, v245
	v_sub_f32_e32 v104, v106, v104
	v_mul_f32_e32 v104, 0x3fb8aa3b, v104
	v_exp_f32_e32 v104, v104
	s_nop 0
	v_mul_f32_e32 v104, v40, v104
	v_mul_f32_e32 v104, v105, v104
.LBB0_1331:
	s_or_b64 exec, exec, s[20:21]
	v_bfe_u32 v105, v104, 16, 1
	v_or_b32_e32 v108, 49, v99
	v_add3_u32 v104, v104, v105, s28
	v_cmp_ge_i32_e32 vcc, v108, v98
	ds_write_b16_d16_hi v102, v104 offset:2304
	s_and_saveexec_b64 s[20:21], vcc
	s_cbranch_execz .LBB0_1333
	v_mov_b32_e32 v103, v237
	v_mov_b32_e32 v104, v244
	v_mov_b32_e32 v105, v245
	v_sub_f32_e32 v103, v103, v104
	v_mul_f32_e32 v103, 0x3fb8aa3b, v103
	v_exp_f32_e32 v103, v103
	s_nop 0
	v_mul_f32_e32 v103, v41, v103
	v_mul_f32_e32 v103, v105, v103
.LBB0_1333:
	s_or_b64 exec, exec, s[20:21]
	v_bfe_u32 v104, v103, 16, 1
	v_add3_u32 v103, v103, v104, s28
	v_or_b32_e32 v107, 50, v99
	ds_write_b16_d16_hi v102, v103 offset:2448
	v_cmp_ge_i32_e32 vcc, v107, v98
	v_mov_b32_e32 v103, 0
	v_mov_b32_e32 v104, 0
	s_and_saveexec_b64 s[20:21], vcc
	s_cbranch_execz .LBB0_1335
	v_mov_b32_e32 v106, v238
	v_mov_b32_e32 v104, v244
	v_mov_b32_e32 v105, v245
	v_sub_f32_e32 v104, v106, v104
	v_mul_f32_e32 v104, 0x3fb8aa3b, v104
	v_exp_f32_e32 v104, v104
	s_nop 0
	v_mul_f32_e32 v104, v42, v104
	v_mul_f32_e32 v104, v105, v104
.LBB0_1335:
	s_or_b64 exec, exec, s[20:21]
	v_bfe_u32 v105, v104, 16, 1
	v_or_b32_e32 v106, 51, v99
	v_add3_u32 v104, v104, v105, s28
	v_cmp_ge_i32_e32 vcc, v106, v98
	ds_write_b16_d16_hi v102, v104 offset:2592
	s_and_saveexec_b64 s[20:21], vcc
	s_cbranch_execz .LBB0_1337
	v_mov_b32_e32 v103, v239
	v_mov_b32_e32 v104, v244
	v_mov_b32_e32 v105, v245
	v_sub_f32_e32 v103, v103, v104
	v_mul_f32_e32 v103, 0x3fb8aa3b, v103
	v_exp_f32_e32 v103, v103
	s_nop 0
	v_mul_f32_e32 v103, v43, v103
	v_mul_f32_e32 v103, v105, v103
.LBB0_1337:
	s_or_b64 exec, exec, s[20:21]
	v_bfe_u32 v104, v103, 16, 1
	v_add3_u32 v103, v103, v104, s28
	v_or_b32_e32 v105, 56, v99
	ds_write_b16_d16_hi v102, v103 offset:2736
	v_cmp_ge_i32_e32 vcc, v105, v98
	v_mov_b32_e32 v103, 0
	v_mov_b32_e32 v104, 0
	s_and_saveexec_b64 s[20:21], vcc
	s_cbranch_execz .LBB0_1339
	v_mov_b32_e32 v104, v240
	v_mov_b32_e32 v190, v244
	v_mov_b32_e32 v191, v245
	v_sub_f32_e32 v104, v104, v190
	v_mul_f32_e32 v104, 0x3fb8aa3b, v104
	v_exp_f32_e32 v104, v104
	s_nop 0
	v_mul_f32_e32 v104, v44, v104
	v_mul_f32_e32 v104, v191, v104
.LBB0_1339:
	s_or_b64 exec, exec, s[20:21]
	v_bfe_u32 v189, v104, 16, 1
	v_add3_u32 v104, v104, v189, s28
	ds_write_b16_d16_hi v102, v104 offset:3456
	v_or_b32_e32 v104, 57, v99
	v_cmp_ge_i32_e32 vcc, v104, v98
	s_and_saveexec_b64 s[20:21], vcc
	s_cbranch_execz .LBB0_1341
	v_mov_b32_e32 v103, v241
	v_mov_b32_e32 v190, v244
	v_mov_b32_e32 v191, v245
	v_sub_f32_e32 v103, v103, v190
	v_mul_f32_e32 v103, 0x3fb8aa3b, v103
	v_exp_f32_e32 v103, v103
	s_nop 0
	v_mul_f32_e32 v103, v45, v103
	v_mul_f32_e32 v103, v191, v103
.LBB0_1341:
	s_or_b64 exec, exec, s[20:21]
	v_bfe_u32 v189, v103, 16, 1
	v_add3_u32 v103, v103, v189, s28
	ds_write_b16_d16_hi v102, v103 offset:3600
	v_or_b32_e32 v103, 58, v99
	v_cmp_ge_i32_e32 vcc, v103, v98
	v_mov_b32_e32 v189, 0
	v_mov_b32_e32 v190, 0
	s_and_saveexec_b64 s[20:21], vcc
	s_cbranch_execz .LBB0_1343
	v_mov_b32_e32 v192, v242
	v_mov_b32_e32 v190, v244
	v_mov_b32_e32 v191, v245
	v_sub_f32_e32 v190, v192, v190
	v_mul_f32_e32 v190, 0x3fb8aa3b, v190
	v_exp_f32_e32 v190, v190
	s_nop 0
	v_mul_f32_e32 v190, v46, v190
	v_mul_f32_e32 v190, v191, v190
; __device__ __forceinline__ void phase_ssd_out(const Params& p, int layer, unsigned char* smem) {
;     ...
;           if (wn == ks) {
;             const int t2 = relaunder(tid);
;             const int lane = t2 & 63, hi = lane >> 5, cl = lane & 31, wm = t2 >> 7;
; #pragma unroll
;             for (int mt = 0; mt < 2; mt++)
; #pragma unroll
;               for (int nt = 0; nt < 2; nt++)
; #pragma unroll
;                 for (int i = 0; i < 16; i++) {
;                   int row = wm * 64 + mt * 32 + (i & 3) + 8 * (i >> 2) + 4 * hi;
;                   int cloc = nt * 32 + cl;
;                   int s = ks * 64 + cloc;
;                   float val = 0.f;
;                   if (row >= s) val = cb[mt][nt][i] * __expf(sAcs[row] - sAcs[s]) * sDt[s];
;                   if (row == s) val += Dh;
;                   sA[row * LDK + cloc] = f2bf(val);
;                   if ((i & 7) == 7) __builtin_amdgcn_sched_barrier(0);
;                 }
.LBB0_1343:
	s_or_b64 exec, exec, s[20:21]
	v_bfe_u32 v191, v190, 16, 1
	v_or_b32_e32 v99, 59, v99
	v_add3_u32 v190, v190, v191, s28
	v_cmp_ge_i32_e32 vcc, v99, v98
	ds_write_b16_d16_hi v102, v190 offset:3744
	s_and_saveexec_b64 s[20:21], vcc
	s_cbranch_execz .LBB0_1345
	v_mov_b32_e32 v98, v243
	v_mov_b32_e32 v190, v244
	v_mov_b32_e32 v191, v245
	v_sub_f32_e32 v97, v98, v190
	v_mul_f32_e32 v97, 0x3fb8aa3b, v97
	v_exp_f32_e32 v97, v97
	s_nop 0
	v_mul_f32_e32 v97, v47, v97
	v_mul_f32_e32 v189, v191, v97
.LBB0_1345:
	s_or_b64 exec, exec, s[20:21]
	v_bfe_u32 v97, v189, 16, 1
	v_add3_u32 v97, v189, v97, s28
	ds_write_b16_d16_hi v102, v97 offset:3888
	v_cmp_ge_i32_e32 vcc, v187, v100
	v_mov_b32_e32 v97, 0
	v_mov_b32_e32 v98, 0
	s_and_saveexec_b64 s[20:21], vcc
	s_cbranch_execz .LBB0_1347
	v_mov_b32_e32 v98, v224
	v_mov_b32_e32 v190, v246
	v_mov_b32_e32 v191, v247
	v_sub_f32_e32 v98, v98, v190
	v_mul_f32_e32 v98, 0x3fb8aa3b, v98
	v_exp_f32_e32 v98, v98
	s_nop 0
	v_mul_f32_e32 v98, v48, v98
	v_mul_f32_e32 v98, v191, v98
.LBB0_1347:
	s_or_b64 exec, exec, s[20:21]
	v_add_f32_e32 v189, v183, v98
	v_cmp_eq_u32_e32 vcc, v187, v100
	s_nop 1
	v_cndmask_b32_e32 v98, v98, v189, vcc
	v_bfe_u32 v187, v98, 16, 1
	v_add3_u32 v98, v98, v187, s28
	v_cmp_ge_i32_e32 vcc, v188, v100
	ds_write_b16_d16_hi v102, v98 offset:64
	s_and_saveexec_b64 s[20:21], vcc
	s_cbranch_execz .LBB0_1349
	v_mov_b32_e32 v97, v225
	v_mov_b32_e32 v190, v246
	v_mov_b32_e32 v191, v247
	v_sub_f32_e32 v97, v97, v190
	v_mul_f32_e32 v97, 0x3fb8aa3b, v97
	v_exp_f32_e32 v97, v97
	s_nop 0
	v_mul_f32_e32 v97, v49, v97
	v_mul_f32_e32 v97, v191, v97
.LBB0_1349:
	s_or_b64 exec, exec, s[20:21]
	v_add_f32_e32 v98, v183, v97
	v_cmp_eq_u32_e32 vcc, v188, v100
	s_nop 1
	v_cndmask_b32_e32 v97, v97, v98, vcc
	v_bfe_u32 v98, v97, 16, 1
	v_add3_u32 v97, v97, v98, s28
	ds_write_b16_d16_hi v102, v97 offset:208
	v_cmp_ge_i32_e32 vcc, v186, v100
	v_mov_b32_e32 v97, 0
	v_mov_b32_e32 v98, 0
	s_and_saveexec_b64 s[20:21], vcc
	s_cbranch_execz .LBB0_1351
	v_mov_b32_e32 v98, v226
	v_mov_b32_e32 v188, v246
	v_mov_b32_e32 v189, v247
	v_sub_f32_e32 v98, v98, v188
	v_mul_f32_e32 v98, 0x3fb8aa3b, v98
	v_exp_f32_e32 v98, v98
	s_nop 0
	v_mul_f32_e32 v98, v50, v98
	v_mul_f32_e32 v98, v189, v98
.LBB0_1351:
	s_or_b64 exec, exec, s[20:21]
	v_add_f32_e32 v187, v183, v98
	v_cmp_eq_u32_e32 vcc, v186, v100
	s_nop 1
	v_cndmask_b32_e32 v98, v98, v187, vcc
	v_bfe_u32 v186, v98, 16, 1
	v_add3_u32 v98, v98, v186, s28
	v_cmp_ge_i32_e32 vcc, v185, v100
	ds_write_b16_d16_hi v102, v98 offset:352
	s_and_saveexec_b64 s[20:21], vcc
	s_cbranch_execz .LBB0_1353
	v_mov_b32_e32 v97, v227
	v_mov_b32_e32 v186, v246
	v_mov_b32_e32 v187, v247
	v_sub_f32_e32 v97, v97, v186
	v_mul_f32_e32 v97, 0x3fb8aa3b, v97
	v_exp_f32_e32 v97, v97
	s_nop 0
	v_mul_f32_e32 v97, v51, v97
	v_mul_f32_e32 v97, v187, v97
.LBB0_1353:
	s_or_b64 exec, exec, s[20:21]
	v_add_f32_e32 v98, v183, v97
	v_cmp_eq_u32_e32 vcc, v185, v100
	s_nop 1
	v_cndmask_b32_e32 v97, v97, v98, vcc
	v_bfe_u32 v98, v97, 16, 1
	v_add3_u32 v97, v97, v98, s28
	ds_write_b16_d16_hi v102, v97 offset:496
	v_cmp_ge_i32_e32 vcc, v184, v100
	v_mov_b32_e32 v97, 0
	v_mov_b32_e32 v98, 0
	s_and_saveexec_b64 s[20:21], vcc
	s_cbranch_execz .LBB0_1355
	v_mov_b32_e32 v98, v232
	v_mov_b32_e32 v186, v246
	v_mov_b32_e32 v187, v247
	v_sub_f32_e32 v98, v98, v186
	v_mul_f32_e32 v98, 0x3fb8aa3b, v98
	v_exp_f32_e32 v98, v98
	s_nop 0
	v_mul_f32_e32 v98, v52, v98
	v_mul_f32_e32 v98, v187, v98
.LBB0_1355:
	s_or_b64 exec, exec, s[20:21]
	v_add_f32_e32 v185, v183, v98
	v_cmp_eq_u32_e32 vcc, v184, v100
	s_nop 1
	v_cndmask_b32_e32 v98, v98, v185, vcc
	v_bfe_u32 v184, v98, 16, 1
	v_add3_u32 v98, v98, v184, s28
	v_cmp_ge_i32_e32 vcc, v114, v100
	ds_write_b16_d16_hi v102, v98 offset:1216
	s_and_saveexec_b64 s[20:21], vcc
	s_cbranch_execz .LBB0_1357
	v_mov_b32_e32 v97, v233
	v_mov_b32_e32 v184, v246
	v_mov_b32_e32 v185, v247
	v_sub_f32_e32 v97, v97, v184
	v_mul_f32_e32 v97, 0x3fb8aa3b, v97
	v_exp_f32_e32 v97, v97
	s_nop 0
	v_mul_f32_e32 v97, v53, v97
	v_mul_f32_e32 v97, v185, v97
.LBB0_1357:
	s_or_b64 exec, exec, s[20:21]
	v_add_f32_e32 v98, v183, v97
	v_cmp_eq_u32_e32 vcc, v114, v100
	s_nop 1
	v_cndmask_b32_e32 v97, v97, v98, vcc
	v_bfe_u32 v98, v97, 16, 1
	v_add3_u32 v97, v97, v98, s28
	ds_write_b16_d16_hi v102, v97 offset:1360
	v_cmp_ge_i32_e32 vcc, v111, v100
	v_mov_b32_e32 v97, 0
	v_mov_b32_e32 v98, 0
	s_and_saveexec_b64 s[20:21], vcc
	s_cbranch_execz .LBB0_1359
	v_mov_b32_e32 v98, v234
	v_mov_b32_e32 v184, v246
	v_mov_b32_e32 v185, v247
	v_sub_f32_e32 v98, v98, v184
	v_mul_f32_e32 v98, 0x3fb8aa3b, v98
	v_exp_f32_e32 v98, v98
	s_nop 0
	v_mul_f32_e32 v98, v54, v98
	v_mul_f32_e32 v98, v185, v98
.LBB0_1359:
	s_or_b64 exec, exec, s[20:21]
	v_add_f32_e32 v114, v183, v98
	v_cmp_eq_u32_e32 vcc, v111, v100
	s_nop 1
	v_cndmask_b32_e32 v98, v98, v114, vcc
	v_bfe_u32 v111, v98, 16, 1
	v_add3_u32 v98, v98, v111, s28
	v_cmp_ge_i32_e32 vcc, v110, v100
	ds_write_b16_d16_hi v102, v98 offset:1504
	s_and_saveexec_b64 s[20:21], vcc
	s_cbranch_execz .LBB0_1361
	v_mov_b32_e32 v97, v235
	v_mov_b32_e32 v184, v246
	v_mov_b32_e32 v185, v247
	v_sub_f32_e32 v97, v97, v184
	v_mul_f32_e32 v97, 0x3fb8aa3b, v97
	v_exp_f32_e32 v97, v97
	s_nop 0
	v_mul_f32_e32 v97, v55, v97
	v_mul_f32_e32 v97, v185, v97
; __device__ __forceinline__ void phase_ssd_out(const Params& p, int layer, unsigned char* smem) {
;     ...
;           if (wn == ks) {
;             const int t2 = relaunder(tid);
;             const int lane = t2 & 63, hi = lane >> 5, cl = lane & 31, wm = t2 >> 7;
; #pragma unroll
;             for (int mt = 0; mt < 2; mt++)
; #pragma unroll
;               for (int nt = 0; nt < 2; nt++)
; #pragma unroll
;                 for (int i = 0; i < 16; i++) {
;                   int row = wm * 64 + mt * 32 + (i & 3) + 8 * (i >> 2) + 4 * hi;
;                   int cloc = nt * 32 + cl;
;                   int s = ks * 64 + cloc;
;                   float val = 0.f;
;                   if (row >= s) val = cb[mt][nt][i] * __expf(sAcs[row] - sAcs[s]) * sDt[s];
;                   if (row == s) val += Dh;
;                   sA[row * LDK + cloc] = f2bf(val);
;                   if ((i & 7) == 7) __builtin_amdgcn_sched_barrier(0);
;                 }
.LBB0_1361:
	s_or_b64 exec, exec, s[20:21]
	v_add_f32_e32 v98, v183, v97
	v_cmp_eq_u32_e32 vcc, v110, v100
	s_nop 1
	v_cndmask_b32_e32 v97, v97, v98, vcc
	v_bfe_u32 v98, v97, 16, 1
	v_add3_u32 v97, v97, v98, s28
	ds_write_b16_d16_hi v102, v97 offset:1648
	v_cmp_ge_i32_e32 vcc, v109, v100
	v_mov_b32_e32 v97, 0
	v_mov_b32_e32 v98, 0
	s_and_saveexec_b64 s[20:21], vcc
	s_cbranch_execz .LBB0_1363
	v_mov_b32_e32 v98, v236
	v_mov_b32_e32 v110, v246
	v_mov_b32_e32 v111, v247
	v_sub_f32_e32 v98, v98, v110
	v_mul_f32_e32 v98, 0x3fb8aa3b, v98
	v_exp_f32_e32 v98, v98
	s_nop 0
	v_mul_f32_e32 v98, v56, v98
	v_mul_f32_e32 v98, v111, v98
.LBB0_1363:
	s_or_b64 exec, exec, s[20:21]
	v_add_f32_e32 v110, v183, v98
	v_cmp_eq_u32_e32 vcc, v109, v100
	s_nop 1
	v_cndmask_b32_e32 v98, v98, v110, vcc
	v_bfe_u32 v109, v98, 16, 1
	v_add3_u32 v98, v98, v109, s28
	v_cmp_ge_i32_e32 vcc, v108, v100
	ds_write_b16_d16_hi v102, v98 offset:2368
	s_and_saveexec_b64 s[20:21], vcc
	s_cbranch_execz .LBB0_1365
	v_mov_b32_e32 v97, v237
	v_mov_b32_e32 v110, v246
	v_mov_b32_e32 v111, v247
	v_sub_f32_e32 v97, v97, v110
	v_mul_f32_e32 v97, 0x3fb8aa3b, v97
	v_exp_f32_e32 v97, v97
	s_nop 0
	v_mul_f32_e32 v97, v57, v97
	v_mul_f32_e32 v97, v111, v97
.LBB0_1365:
	s_or_b64 exec, exec, s[20:21]
	v_add_f32_e32 v98, v183, v97
	v_cmp_eq_u32_e32 vcc, v108, v100
	s_nop 1
	v_cndmask_b32_e32 v97, v97, v98, vcc
	v_bfe_u32 v98, v97, 16, 1
	v_add3_u32 v97, v97, v98, s28
	ds_write_b16_d16_hi v102, v97 offset:2512
	v_cmp_ge_i32_e32 vcc, v107, v100
	v_mov_b32_e32 v97, 0
	v_mov_b32_e32 v98, 0
	s_and_saveexec_b64 s[20:21], vcc
	s_cbranch_execz .LBB0_1367
	v_mov_b32_e32 v98, v238
	v_mov_b32_e32 v108, v246
	v_mov_b32_e32 v109, v247
	v_sub_f32_e32 v98, v98, v108
	v_mul_f32_e32 v98, 0x3fb8aa3b, v98
	v_exp_f32_e32 v98, v98
	s_nop 0
	v_mul_f32_e32 v98, v58, v98
	v_mul_f32_e32 v98, v109, v98
.LBB0_1367:
	s_or_b64 exec, exec, s[20:21]
	v_add_f32_e32 v108, v183, v98
	v_cmp_eq_u32_e32 vcc, v107, v100
	s_nop 1
	v_cndmask_b32_e32 v98, v98, v108, vcc
	v_bfe_u32 v107, v98, 16, 1
	v_add3_u32 v98, v98, v107, s28
	v_cmp_ge_i32_e32 vcc, v106, v100
	ds_write_b16_d16_hi v102, v98 offset:2656
	s_and_saveexec_b64 s[20:21], vcc
	s_cbranch_execz .LBB0_1369
	v_mov_b32_e32 v97, v239
	v_mov_b32_e32 v108, v246
	v_mov_b32_e32 v109, v247
	v_sub_f32_e32 v97, v97, v108
	v_mul_f32_e32 v97, 0x3fb8aa3b, v97
	v_exp_f32_e32 v97, v97
	s_nop 0
	v_mul_f32_e32 v97, v59, v97
	v_mul_f32_e32 v97, v109, v97
.LBB0_1369:
	s_or_b64 exec, exec, s[20:21]
	v_add_f32_e32 v98, v183, v97
	v_cmp_eq_u32_e32 vcc, v106, v100
	s_nop 1
	v_cndmask_b32_e32 v97, v97, v98, vcc
	v_bfe_u32 v98, v97, 16, 1
	v_add3_u32 v97, v97, v98, s28
	ds_write_b16_d16_hi v102, v97 offset:2800
	v_cmp_ge_i32_e32 vcc, v105, v100
	v_mov_b32_e32 v97, 0
	v_mov_b32_e32 v98, 0
	s_and_saveexec_b64 s[20:21], vcc
	s_cbranch_execz .LBB0_1371
	v_mov_b32_e32 v98, v240
	v_mov_b32_e32 v106, v246
	v_mov_b32_e32 v107, v247
	v_sub_f32_e32 v98, v98, v106
	v_mul_f32_e32 v98, 0x3fb8aa3b, v98
	v_exp_f32_e32 v98, v98
	s_nop 0
	v_mul_f32_e32 v98, v60, v98
	v_mul_f32_e32 v98, v107, v98
.LBB0_1371:
	s_or_b64 exec, exec, s[20:21]
	v_add_f32_e32 v106, v183, v98
	v_cmp_eq_u32_e32 vcc, v105, v100
	s_nop 1
	v_cndmask_b32_e32 v98, v98, v106, vcc
	v_bfe_u32 v105, v98, 16, 1
	v_add3_u32 v98, v98, v105, s28
	v_cmp_ge_i32_e32 vcc, v104, v100
	ds_write_b16_d16_hi v102, v98 offset:3520
	s_and_saveexec_b64 s[20:21], vcc
	s_cbranch_execz .LBB0_1373
	v_mov_b32_e32 v97, v241
	v_mov_b32_e32 v106, v246
	v_mov_b32_e32 v107, v247
	v_sub_f32_e32 v97, v97, v106
	v_mul_f32_e32 v97, 0x3fb8aa3b, v97
	v_exp_f32_e32 v97, v97
	s_nop 0
	v_mul_f32_e32 v97, v61, v97
	v_mul_f32_e32 v97, v107, v97
.LBB0_1373:
	s_or_b64 exec, exec, s[20:21]
	v_add_f32_e32 v98, v183, v97
	v_cmp_eq_u32_e32 vcc, v104, v100
	s_nop 1
	v_cndmask_b32_e32 v97, v97, v98, vcc
	v_bfe_u32 v98, v97, 16, 1
	v_add3_u32 v97, v97, v98, s28
	ds_write_b16_d16_hi v102, v97 offset:3664
	v_cmp_ge_i32_e32 vcc, v103, v100
	v_mov_b32_e32 v97, 0
	v_mov_b32_e32 v98, 0
	s_and_saveexec_b64 s[20:21], vcc
	s_cbranch_execz .LBB0_1375
	v_mov_b32_e32 v98, v242
	v_mov_b32_e32 v104, v246
	v_mov_b32_e32 v105, v247
	v_sub_f32_e32 v98, v98, v104
	v_mul_f32_e32 v98, 0x3fb8aa3b, v98
	v_exp_f32_e32 v98, v98
	s_nop 0
	v_mul_f32_e32 v98, v62, v98
	v_mul_f32_e32 v98, v105, v98
.LBB0_1375:
	s_or_b64 exec, exec, s[20:21]
	v_add_f32_e32 v104, v183, v98
	v_cmp_eq_u32_e32 vcc, v103, v100
	s_nop 1
	v_cndmask_b32_e32 v98, v98, v104, vcc
	v_bfe_u32 v103, v98, 16, 1
	v_add3_u32 v98, v98, v103, s28
	v_cmp_ge_i32_e32 vcc, v99, v100
	ds_write_b16_d16_hi v102, v98 offset:3808
	s_and_saveexec_b64 s[20:21], vcc
	s_cbranch_execz .LBB0_1242
	v_mov_b32_e32 v98, v243
	v_mov_b32_e32 v96, v246
	v_mov_b32_e32 v97, v247
	v_sub_f32_e32 v96, v98, v96
	v_mul_f32_e32 v96, 0x3fb8aa3b, v96
	v_exp_f32_e32 v96, v96
	s_nop 0
	v_mul_f32_e32 v96, v63, v96
	v_mul_f32_e32 v97, v97, v96
	s_branch .LBB0_1242

; __device__ __forceinline__ unsigned pack2(float a, float b) { return (unsigned)f2bf(a) | ((unsigned)f2bf(b) << 16); }
; __device__ __forceinline__ float lo16(unsigned v) { return __uint_as_float(v << 16); }
; __device__ __forceinline__ float hi16(unsigned v) { return __uint_as_float(v & 0xffff0000u); }
; __device__ __forceinline__ void phase_scan(const Params& p, unsigned* st, int npairs, int pairs_per_head_shift, int mode) {
;     ...
;     int h = e >> pairs_per_head_shift;
;     float r0 = 0.f, r1 = 0.f;
;     float rdec = 1.f;
;     if (mode == 1) rdec = expf(128.f * logf(1.f - exp2f(-5.f - (float)h)));
;     for (int c0 = 0; c0 < NCH; c0 += 8) {
;       unsigned v[8];
;       float dc[8];
; #pragma unroll
;       for (int i = 0; i < 8; i++) {
;         int c = c0 + i;
;         if (c < NCH) {
;           v[i] = st[(size_t)c * npairs + e];
;           dc[i] = (mode == 0) ? expf(acs[((size_t)c * 16 + h) * 128 + 127]) : rdec;
;         } else { v[i] = 0; dc[i] = 0.f; }
;       }
; #pragma unroll
;       for (int i = 0; i < 8; i++) {
;         int c = c0 + i;
;         if (c < NCH) {
;           *(st + (size_t)c * npairs + e) = pack2(r0, r1);
;           r0 = r0 * dc[i] + lo16(v[i]);
;           r1 = r1 * dc[i] + hi16(v[i]);
;         }
;       }
;     }
.LBB0_1446:
	v_ashrrev_i32_e32 v1, 15, v0
	v_cvt_f32_i32_e32 v1, v1
	s_mov_b32 s2, 0xc2fc0000
	v_sub_f32_e32 v1, 0xc0a00000, v1
	v_cmp_gt_f32_e32 vcc, s2, v1
	s_mov_b32 s2, 0x3f317217
	s_nop 0
	v_cndmask_b32_e32 v2, 0, v6, vcc
	v_add_f32_e32 v1, v1, v2
	v_exp_f32_e32 v1, v1
	v_cndmask_b32_e32 v2, 0, v8, vcc
	v_ldexp_f32 v1, v1, v2
	v_sub_f32_e32 v1, 1.0, v1
	v_cmp_gt_f32_e32 vcc, s1, v1
	s_nop 1
	v_cndmask_b32_e64 v2, 0, 32, vcc
	v_ldexp_f32 v1, v1, v2
	v_log_f32_e32 v1, v1
	s_nop 0
	v_mul_f32_e32 v2, 0x3f317217, v1
	v_fma_f32 v2, v1, s2, -v2
	v_fmac_f32_e32 v2, 0x3377d1cf, v1
	s_mov_b32 s2, 0x7f800000
	v_fmac_f32_e32 v2, 0x3f317217, v1
	v_cmp_lt_f32_e64 s[4:5], |v1|, s2
	s_mov_b32 s2, 0x3fb8aa3b
	s_nop 0
	v_cndmask_b32_e64 v1, v1, v2, s[4:5]
	v_cndmask_b32_e32 v2, 0, v9, vcc
	v_sub_f32_e32 v1, v1, v2
	v_mul_f32_e32 v1, 0x43000000, v1
	v_mul_f32_e32 v2, 0x3fb8aa3b, v1
	v_fma_f32 v3, v1, s2, -v2
	v_rndne_f32_e32 v4, v2
	v_fmac_f32_e32 v3, 0x32a5705f, v1
	v_sub_f32_e32 v2, v2, v4
	v_add_f32_e32 v2, v2, v3
	v_exp_f32_e32 v2, v2
	v_cvt_i32_f32_e32 v3, v4
	s_mov_b32 s2, 0xc2ce8ed0
	v_cmp_ngt_f32_e32 vcc, s2, v1
	s_mov_b32 s2, 0x42b17218
	v_ldexp_f32 v2, v2, v3
	v_cndmask_b32_e32 v2, 0, v2, vcc
	v_cmp_nlt_f32_e32 vcc, s2, v1
	v_ashrrev_i32_e32 v1, 31, v0
	s_mov_b32 s2, 0x80000
	v_cndmask_b32_e32 v11, v10, v2, vcc
	s_movk_i32 s99, 0x7fff
	s_mov_b32 s100, 0xffff0000
	v_lshlrev_b32_e32 v26, 2, v0
	v_mov_b32_e32 v20, 0
	v_mov_b32_e32 v21, 0
	v_mov_b32_e32 v27, v26
	v_add_u32_e32 v28, 0x4000000, v26
	global_load_dword v40, v26, s[8:9]
	v_add_u32_e32 v26, 0x80000, v26
	global_load_dword v41, v26, s[8:9]
	v_add_u32_e32 v26, 0x80000, v26
	global_load_dword v42, v26, s[8:9]
	v_add_u32_e32 v26, 0x80000, v26
	global_load_dword v43, v26, s[8:9]
	v_add_u32_e32 v26, 0x80000, v26
	global_load_dword v44, v26, s[8:9]
	v_add_u32_e32 v26, 0x80000, v26
	global_load_dword v45, v26, s[8:9]
	v_add_u32_e32 v26, 0x80000, v26
	global_load_dword v46, v26, s[8:9]
	v_add_u32_e32 v26, 0x80000, v26
	global_load_dword v47, v26, s[8:9]
	v_add_u32_e32 v26, 0x80000, v26
	global_load_dword v48, v26, s[8:9]
	v_add_u32_e32 v26, 0x80000, v26
	global_load_dword v49, v26, s[8:9]
	v_add_u32_e32 v26, 0x80000, v26
	global_load_dword v50, v26, s[8:9]
	v_add_u32_e32 v26, 0x80000, v26
	global_load_dword v51, v26, s[8:9]
	v_add_u32_e32 v26, 0x80000, v26
	global_load_dword v52, v26, s[8:9]
	v_add_u32_e32 v26, 0x80000, v26
	global_load_dword v53, v26, s[8:9]
	v_add_u32_e32 v26, 0x80000, v26
	global_load_dword v54, v26, s[8:9]
	v_add_u32_e32 v26, 0x80000, v26
	global_load_dword v55, v26, s[8:9]
	v_add_u32_e32 v26, 0x80000, v26
	s_waitcnt vmcnt(15)
	v_bfe_u32 v24, v20, 16, 1
	v_add3_u32 v24, v20, v24, s99
	v_bfe_u32 v25, v21, 16, 1
	v_lshrrev_b32_e32 v24, 16, v24
	v_add3_u32 v25, v21, v25, s99
	v_and_or_b32 v24, v25, s100, v24
	global_store_dword v27, v24, s[8:9]
	v_add_u32_e32 v27, 0x80000, v27
	v_lshlrev_b32_e32 v22, 16, v40
	v_and_b32_e32 v23, 0xffff0000, v40
	v_fmac_f32_e32 v22, v11, v20
	v_fmac_f32_e32 v23, v11, v21
	v_min_u32_e32 v26, v26, v28
	global_load_dword v40, v26, s[8:9]
	v_add_u32_e32 v26, 0x80000, v26
	s_waitcnt vmcnt(16)
	v_bfe_u32 v24, v22, 16, 1
	v_add3_u32 v24, v22, v24, s99
	v_bfe_u32 v25, v23, 16, 1
	v_lshrrev_b32_e32 v24, 16, v24
	v_add3_u32 v25, v23, v25, s99
	v_and_or_b32 v24, v25, s100, v24
	global_store_dword v27, v24, s[8:9]
	v_add_u32_e32 v27, 0x80000, v27
	v_lshlrev_b32_e32 v20, 16, v41
	v_and_b32_e32 v21, 0xffff0000, v41
	v_fmac_f32_e32 v20, v11, v22
	v_fmac_f32_e32 v21, v11, v23
	v_min_u32_e32 v26, v26, v28
	global_load_dword v41, v26, s[8:9]
	v_add_u32_e32 v26, 0x80000, v26
	s_waitcnt vmcnt(17)
	v_bfe_u32 v24, v20, 16, 1
	v_add3_u32 v24, v20, v24, s99
	v_bfe_u32 v25, v21, 16, 1
	v_lshrrev_b32_e32 v24, 16, v24
	v_add3_u32 v25, v21, v25, s99
	v_and_or_b32 v24, v25, s100, v24
	global_store_dword v27, v24, s[8:9]
	v_add_u32_e32 v27, 0x80000, v27
	v_lshlrev_b32_e32 v22, 16, v42
	v_and_b32_e32 v23, 0xffff0000, v42
	v_fmac_f32_e32 v22, v11, v20
	v_fmac_f32_e32 v23, v11, v21
	v_min_u32_e32 v26, v26, v28
	global_load_dword v42, v26, s[8:9]
	v_add_u32_e32 v26, 0x80000, v26
	s_waitcnt vmcnt(18)
	v_bfe_u32 v24, v22, 16, 1
	v_add3_u32 v24, v22, v24, s99
	v_bfe_u32 v25, v23, 16, 1
	v_lshrrev_b32_e32 v24, 16, v24
	v_add3_u32 v25, v23, v25, s99
	v_and_or_b32 v24, v25, s100, v24
	global_store_dword v27, v24, s[8:9]
	v_add_u32_e32 v27, 0x80000, v27
	v_lshlrev_b32_e32 v20, 16, v43
	v_and_b32_e32 v21, 0xffff0000, v43
	v_fmac_f32_e32 v20, v11, v22
	v_fmac_f32_e32 v21, v11, v23
	v_min_u32_e32 v26, v26, v28
	global_load_dword v43, v26, s[8:9]
	v_add_u32_e32 v26, 0x80000, v26
	s_waitcnt vmcnt(19)
	v_bfe_u32 v24, v20, 16, 1
	v_add3_u32 v24, v20, v24, s99
	v_bfe_u32 v25, v21, 16, 1
	v_lshrrev_b32_e32 v24, 16, v24
	v_add3_u32 v25, v21, v25, s99
	v_and_or_b32 v24, v25, s100, v24
	global_store_dword v27, v24, s[8:9]
	v_add_u32_e32 v27, 0x80000, v27
	v_lshlrev_b32_e32 v22, 16, v44
	v_and_b32_e32 v23, 0xffff0000, v44
	v_fmac_f32_e32 v22, v11, v20
	v_fmac_f32_e32 v23, v11, v21
	v_min_u32_e32 v26, v26, v28
	global_load_dword v44, v26, s[8:9]
	v_add_u32_e32 v26, 0x80000, v26
	s_waitcnt vmcnt(20)
	v_bfe_u32 v24, v22, 16, 1
	v_add3_u32 v24, v22, v24, s99
	v_bfe_u32 v25, v23, 16, 1
	v_lshrrev_b32_e32 v24, 16, v24
	v_add3_u32 v25, v23, v25, s99
	v_and_or_b32 v24, v25, s100, v24
	global_store_dword v27, v24, s[8:9]
	v_add_u32_e32 v27, 0x80000, v27
	v_lshlrev_b32_e32 v20, 16, v45
	v_and_b32_e32 v21, 0xffff0000, v45
	v_fmac_f32_e32 v20, v11, v22
	v_fmac_f32_e32 v21, v11, v23
	v_min_u32_e32 v26, v26, v28
	global_load_dword v45, v26, s[8:9]
	v_add_u32_e32 v26, 0x80000, v26
	s_waitcnt vmcnt(21)
; __device__ __forceinline__ unsigned pack2(float a, float b) { return (unsigned)f2bf(a) | ((unsigned)f2bf(b) << 16); }
; __device__ __forceinline__ float lo16(unsigned v) { return __uint_as_float(v << 16); }
; __device__ __forceinline__ float hi16(unsigned v) { return __uint_as_float(v & 0xffff0000u); }
; __device__ __forceinline__ void phase_scan(const Params& p, unsigned* st, int npairs, int pairs_per_head_shift, int mode) {
;     ...
;           v[i] = st[(size_t)c * npairs + e];
;           dc[i] = (mode == 0) ? expf(acs[((size_t)c * 16 + h) * 128 + 127]) : rdec;
;         } else { v[i] = 0; dc[i] = 0.f; }
;       }
; #pragma unroll
;       for (int i = 0; i < 8; i++) {
;         int c = c0 + i;
;         if (c < NCH) {
;           *(st + (size_t)c * npairs + e) = pack2(r0, r1);
;           r0 = r0 * dc[i] + lo16(v[i]);
;           r1 = r1 * dc[i] + hi16(v[i]);
	v_bfe_u32 v24, v20, 16, 1
	v_add3_u32 v24, v20, v24, s99
	v_bfe_u32 v25, v21, 16, 1
	v_lshrrev_b32_e32 v24, 16, v24
	v_add3_u32 v25, v21, v25, s99
	v_and_or_b32 v24, v25, s100, v24
	global_store_dword v27, v24, s[8:9]
	v_add_u32_e32 v27, 0x80000, v27
	v_lshlrev_b32_e32 v22, 16, v46
	v_and_b32_e32 v23, 0xffff0000, v46
	v_fmac_f32_e32 v22, v11, v20
	v_fmac_f32_e32 v23, v11, v21
	v_min_u32_e32 v26, v26, v28
	global_load_dword v46, v26, s[8:9]
	v_add_u32_e32 v26, 0x80000, v26
	s_waitcnt vmcnt(22)
	v_bfe_u32 v24, v22, 16, 1
	v_add3_u32 v24, v22, v24, s99
	v_bfe_u32 v25, v23, 16, 1
	v_lshrrev_b32_e32 v24, 16, v24
	v_add3_u32 v25, v23, v25, s99
	v_and_or_b32 v24, v25, s100, v24
	global_store_dword v27, v24, s[8:9]
	v_add_u32_e32 v27, 0x80000, v27
	v_lshlrev_b32_e32 v20, 16, v47
	v_and_b32_e32 v21, 0xffff0000, v47
	v_fmac_f32_e32 v20, v11, v22
	v_fmac_f32_e32 v21, v11, v23
	v_min_u32_e32 v26, v26, v28
	global_load_dword v47, v26, s[8:9]
	v_add_u32_e32 v26, 0x80000, v26
	s_waitcnt vmcnt(23)
	v_bfe_u32 v24, v20, 16, 1
	v_add3_u32 v24, v20, v24, s99
	v_bfe_u32 v25, v21, 16, 1
	v_lshrrev_b32_e32 v24, 16, v24
	v_add3_u32 v25, v21, v25, s99
	v_and_or_b32 v24, v25, s100, v24
	global_store_dword v27, v24, s[8:9]
	v_add_u32_e32 v27, 0x80000, v27
	v_lshlrev_b32_e32 v22, 16, v48
	v_and_b32_e32 v23, 0xffff0000, v48
	v_fmac_f32_e32 v22, v11, v20
	v_fmac_f32_e32 v23, v11, v21
	v_min_u32_e32 v26, v26, v28
	global_load_dword v48, v26, s[8:9]
	v_add_u32_e32 v26, 0x80000, v26
	s_waitcnt vmcnt(24)
	v_bfe_u32 v24, v22, 16, 1
	v_add3_u32 v24, v22, v24, s99
	v_bfe_u32 v25, v23, 16, 1
	v_lshrrev_b32_e32 v24, 16, v24
	v_add3_u32 v25, v23, v25, s99
	v_and_or_b32 v24, v25, s100, v24
	global_store_dword v27, v24, s[8:9]
	v_add_u32_e32 v27, 0x80000, v27
	v_lshlrev_b32_e32 v20, 16, v49
	v_and_b32_e32 v21, 0xffff0000, v49
	v_fmac_f32_e32 v20, v11, v22
	v_fmac_f32_e32 v21, v11, v23
	v_min_u32_e32 v26, v26, v28
	global_load_dword v49, v26, s[8:9]
	v_add_u32_e32 v26, 0x80000, v26
	s_waitcnt vmcnt(25)
	v_bfe_u32 v24, v20, 16, 1
	v_add3_u32 v24, v20, v24, s99
	v_bfe_u32 v25, v21, 16, 1
	v_lshrrev_b32_e32 v24, 16, v24
	v_add3_u32 v25, v21, v25, s99
	v_and_or_b32 v24, v25, s100, v24
	global_store_dword v27, v24, s[8:9]
	v_add_u32_e32 v27, 0x80000, v27
	v_lshlrev_b32_e32 v22, 16, v50
	v_and_b32_e32 v23, 0xffff0000, v50
	v_fmac_f32_e32 v22, v11, v20
	v_fmac_f32_e32 v23, v11, v21
	v_min_u32_e32 v26, v26, v28
	global_load_dword v50, v26, s[8:9]
	v_add_u32_e32 v26, 0x80000, v26
	s_waitcnt vmcnt(26)
	v_bfe_u32 v24, v22, 16, 1
	v_add3_u32 v24, v22, v24, s99
	v_bfe_u32 v25, v23, 16, 1
	v_lshrrev_b32_e32 v24, 16, v24
	v_add3_u32 v25, v23, v25, s99
	v_and_or_b32 v24, v25, s100, v24
	global_store_dword v27, v24, s[8:9]
	v_add_u32_e32 v27, 0x80000, v27
	v_lshlrev_b32_e32 v20, 16, v51
	v_and_b32_e32 v21, 0xffff0000, v51
	v_fmac_f32_e32 v20, v11, v22
	v_fmac_f32_e32 v21, v11, v23
	v_min_u32_e32 v26, v26, v28
	global_load_dword v51, v26, s[8:9]
	v_add_u32_e32 v26, 0x80000, v26
	s_waitcnt vmcnt(27)
	v_bfe_u32 v24, v20, 16, 1
	v_add3_u32 v24, v20, v24, s99
	v_bfe_u32 v25, v21, 16, 1
	v_lshrrev_b32_e32 v24, 16, v24
	v_add3_u32 v25, v21, v25, s99
	v_and_or_b32 v24, v25, s100, v24
	global_store_dword v27, v24, s[8:9]
	v_add_u32_e32 v27, 0x80000, v27
	v_lshlrev_b32_e32 v22, 16, v52
	v_and_b32_e32 v23, 0xffff0000, v52
	v_fmac_f32_e32 v22, v11, v20
	v_fmac_f32_e32 v23, v11, v21
	v_min_u32_e32 v26, v26, v28
	global_load_dword v52, v26, s[8:9]
	v_add_u32_e32 v26, 0x80000, v26
	s_waitcnt vmcnt(28)
	v_bfe_u32 v24, v22, 16, 1
	v_add3_u32 v24, v22, v24, s99
	v_bfe_u32 v25, v23, 16, 1
	v_lshrrev_b32_e32 v24, 16, v24
	v_add3_u32 v25, v23, v25, s99
	v_and_or_b32 v24, v25, s100, v24
	global_store_dword v27, v24, s[8:9]
	v_add_u32_e32 v27, 0x80000, v27
	v_lshlrev_b32_e32 v20, 16, v53
	v_and_b32_e32 v21, 0xffff0000, v53
	v_fmac_f32_e32 v20, v11, v22
	v_fmac_f32_e32 v21, v11, v23
	v_min_u32_e32 v26, v26, v28
	global_load_dword v53, v26, s[8:9]
	v_add_u32_e32 v26, 0x80000, v26
	s_waitcnt vmcnt(29)
	v_bfe_u32 v24, v20, 16, 1
	v_add3_u32 v24, v20, v24, s99
	v_bfe_u32 v25, v21, 16, 1
	v_lshrrev_b32_e32 v24, 16, v24
	v_add3_u32 v25, v21, v25, s99
	v_and_or_b32 v24, v25, s100, v24
	global_store_dword v27, v24, s[8:9]
	v_add_u32_e32 v27, 0x80000, v27
	v_lshlrev_b32_e32 v22, 16, v54
	v_and_b32_e32 v23, 0xffff0000, v54
	v_fmac_f32_e32 v22, v11, v20
	v_fmac_f32_e32 v23, v11, v21
	v_min_u32_e32 v26, v26, v28
	global_load_dword v54, v26, s[8:9]
	v_add_u32_e32 v26, 0x80000, v26
	s_waitcnt vmcnt(30)
	v_bfe_u32 v24, v22, 16, 1
	v_add3_u32 v24, v22, v24, s99
	v_bfe_u32 v25, v23, 16, 1
	v_lshrrev_b32_e32 v24, 16, v24
	v_add3_u32 v25, v23, v25, s99
	v_and_or_b32 v24, v25, s100, v24
	global_store_dword v27, v24, s[8:9]
	v_add_u32_e32 v27, 0x80000, v27
	v_lshlrev_b32_e32 v20, 16, v55
	v_and_b32_e32 v21, 0xffff0000, v55
	v_fmac_f32_e32 v20, v11, v22
	v_fmac_f32_e32 v21, v11, v23
	v_min_u32_e32 v26, v26, v28
	global_load_dword v55, v26, s[8:9]
	v_add_u32_e32 v26, 0x80000, v26
	s_mov_b32 s98, 7
; __device__ __forceinline__ unsigned pack2(float a, float b) { return (unsigned)f2bf(a) | ((unsigned)f2bf(b) << 16); }
; __device__ __forceinline__ float lo16(unsigned v) { return __uint_as_float(v << 16); }
; __device__ __forceinline__ float hi16(unsigned v) { return __uint_as_float(v & 0xffff0000u); }
; __device__ __forceinline__ void phase_scan(const Params& p, unsigned* st, int npairs, int pairs_per_head_shift, int mode) {
;     ...
;           v[i] = st[(size_t)c * npairs + e];
;           dc[i] = (mode == 0) ? expf(acs[((size_t)c * 16 + h) * 128 + 127]) : rdec;
;         } else { v[i] = 0; dc[i] = 0.f; }
;       }
; #pragma unroll
;       for (int i = 0; i < 8; i++) {
;         int c = c0 + i;
;         if (c < NCH) {
;           *(st + (size_t)c * npairs + e) = pack2(r0, r1);
;           r0 = r0 * dc[i] + lo16(v[i]);
;           r1 = r1 * dc[i] + hi16(v[i]);
.Lscan_ret0_loop:
	s_waitcnt vmcnt(30)
	v_bfe_u32 v24, v20, 16, 1
	v_add3_u32 v24, v20, v24, s99
	v_bfe_u32 v25, v21, 16, 1
	v_lshrrev_b32_e32 v24, 16, v24
	v_add3_u32 v25, v21, v25, s99
	v_and_or_b32 v24, v25, s100, v24
	global_store_dword v27, v24, s[8:9]
	v_add_u32_e32 v27, 0x80000, v27
	v_lshlrev_b32_e32 v22, 16, v40
	v_and_b32_e32 v23, 0xffff0000, v40
	v_fmac_f32_e32 v22, v11, v20
	v_fmac_f32_e32 v23, v11, v21
	v_min_u32_e32 v26, v26, v28
	global_load_dword v40, v26, s[8:9]
	v_add_u32_e32 v26, 0x80000, v26
	s_waitcnt vmcnt(30)
	v_bfe_u32 v24, v22, 16, 1
	v_add3_u32 v24, v22, v24, s99
	v_bfe_u32 v25, v23, 16, 1
	v_lshrrev_b32_e32 v24, 16, v24
	v_add3_u32 v25, v23, v25, s99
	v_and_or_b32 v24, v25, s100, v24
	global_store_dword v27, v24, s[8:9]
	v_add_u32_e32 v27, 0x80000, v27
	v_lshlrev_b32_e32 v20, 16, v41
	v_and_b32_e32 v21, 0xffff0000, v41
	v_fmac_f32_e32 v20, v11, v22
	v_fmac_f32_e32 v21, v11, v23
	v_min_u32_e32 v26, v26, v28
	global_load_dword v41, v26, s[8:9]
	v_add_u32_e32 v26, 0x80000, v26
	s_waitcnt vmcnt(30)
	v_bfe_u32 v24, v20, 16, 1
	v_add3_u32 v24, v20, v24, s99
	v_bfe_u32 v25, v21, 16, 1
	v_lshrrev_b32_e32 v24, 16, v24
	v_add3_u32 v25, v21, v25, s99
	v_and_or_b32 v24, v25, s100, v24
	global_store_dword v27, v24, s[8:9]
	v_add_u32_e32 v27, 0x80000, v27
	v_lshlrev_b32_e32 v22, 16, v42
	v_and_b32_e32 v23, 0xffff0000, v42
	v_fmac_f32_e32 v22, v11, v20
	v_fmac_f32_e32 v23, v11, v21
	v_min_u32_e32 v26, v26, v28
	global_load_dword v42, v26, s[8:9]
	v_add_u32_e32 v26, 0x80000, v26
	s_waitcnt vmcnt(30)
	v_bfe_u32 v24, v22, 16, 1
	v_add3_u32 v24, v22, v24, s99
	v_bfe_u32 v25, v23, 16, 1
	v_lshrrev_b32_e32 v24, 16, v24
	v_add3_u32 v25, v23, v25, s99
	v_and_or_b32 v24, v25, s100, v24
	global_store_dword v27, v24, s[8:9]
	v_add_u32_e32 v27, 0x80000, v27
	v_lshlrev_b32_e32 v20, 16, v43
	v_and_b32_e32 v21, 0xffff0000, v43
	v_fmac_f32_e32 v20, v11, v22
	v_fmac_f32_e32 v21, v11, v23
	v_min_u32_e32 v26, v26, v28
	global_load_dword v43, v26, s[8:9]
	v_add_u32_e32 v26, 0x80000, v26
	s_waitcnt vmcnt(30)
	v_bfe_u32 v24, v20, 16, 1
	v_add3_u32 v24, v20, v24, s99
	v_bfe_u32 v25, v21, 16, 1
	v_lshrrev_b32_e32 v24, 16, v24
	v_add3_u32 v25, v21, v25, s99
	v_and_or_b32 v24, v25, s100, v24
	global_store_dword v27, v24, s[8:9]
	v_add_u32_e32 v27, 0x80000, v27
	v_lshlrev_b32_e32 v22, 16, v44
	v_and_b32_e32 v23, 0xffff0000, v44
	v_fmac_f32_e32 v22, v11, v20
	v_fmac_f32_e32 v23, v11, v21
	v_min_u32_e32 v26, v26, v28
	global_load_dword v44, v26, s[8:9]
	v_add_u32_e32 v26, 0x80000, v26
	s_waitcnt vmcnt(30)
	v_bfe_u32 v24, v22, 16, 1
	v_add3_u32 v24, v22, v24, s99
	v_bfe_u32 v25, v23, 16, 1
	v_lshrrev_b32_e32 v24, 16, v24
	v_add3_u32 v25, v23, v25, s99
	v_and_or_b32 v24, v25, s100, v24
	global_store_dword v27, v24, s[8:9]
	v_add_u32_e32 v27, 0x80000, v27
	v_lshlrev_b32_e32 v20, 16, v45
	v_and_b32_e32 v21, 0xffff0000, v45
	v_fmac_f32_e32 v20, v11, v22
	v_fmac_f32_e32 v21, v11, v23
	v_min_u32_e32 v26, v26, v28
	global_load_dword v45, v26, s[8:9]
	v_add_u32_e32 v26, 0x80000, v26
	s_waitcnt vmcnt(30)
	v_bfe_u32 v24, v20, 16, 1
	v_add3_u32 v24, v20, v24, s99
	v_bfe_u32 v25, v21, 16, 1
	v_lshrrev_b32_e32 v24, 16, v24
	v_add3_u32 v25, v21, v25, s99
	v_and_or_b32 v24, v25, s100, v24
	global_store_dword v27, v24, s[8:9]
	v_add_u32_e32 v27, 0x80000, v27
	v_lshlrev_b32_e32 v22, 16, v46
	v_and_b32_e32 v23, 0xffff0000, v46
	v_fmac_f32_e32 v22, v11, v20
	v_fmac_f32_e32 v23, v11, v21
	v_min_u32_e32 v26, v26, v28
	global_load_dword v46, v26, s[8:9]
	v_add_u32_e32 v26, 0x80000, v26
	s_waitcnt vmcnt(30)
	v_bfe_u32 v24, v22, 16, 1
	v_add3_u32 v24, v22, v24, s99
	v_bfe_u32 v25, v23, 16, 1
	v_lshrrev_b32_e32 v24, 16, v24
	v_add3_u32 v25, v23, v25, s99
	v_and_or_b32 v24, v25, s100, v24
	global_store_dword v27, v24, s[8:9]
	v_add_u32_e32 v27, 0x80000, v27
	v_lshlrev_b32_e32 v20, 16, v47
	v_and_b32_e32 v21, 0xffff0000, v47
	v_fmac_f32_e32 v20, v11, v22
	v_fmac_f32_e32 v21, v11, v23
	v_min_u32_e32 v26, v26, v28
	global_load_dword v47, v26, s[8:9]
	v_add_u32_e32 v26, 0x80000, v26
	s_waitcnt vmcnt(30)
; __device__ __forceinline__ unsigned pack2(float a, float b) { return (unsigned)f2bf(a) | ((unsigned)f2bf(b) << 16); }
; __device__ __forceinline__ float lo16(unsigned v) { return __uint_as_float(v << 16); }
; __device__ __forceinline__ float hi16(unsigned v) { return __uint_as_float(v & 0xffff0000u); }
; __device__ __forceinline__ void phase_scan(const Params& p, unsigned* st, int npairs, int pairs_per_head_shift, int mode) {
;     ...
;           v[i] = st[(size_t)c * npairs + e];
;           dc[i] = (mode == 0) ? expf(acs[((size_t)c * 16 + h) * 128 + 127]) : rdec;
;         } else { v[i] = 0; dc[i] = 0.f; }
;       }
; #pragma unroll
;       for (int i = 0; i < 8; i++) {
;         int c = c0 + i;
;         if (c < NCH) {
;           *(st + (size_t)c * npairs + e) = pack2(r0, r1);
;           r0 = r0 * dc[i] + lo16(v[i]);
;           r1 = r1 * dc[i] + hi16(v[i]);
;         }
;       }
;     }
;   }
	v_bfe_u32 v24, v20, 16, 1
	v_add3_u32 v24, v20, v24, s99
	v_bfe_u32 v25, v21, 16, 1
	v_lshrrev_b32_e32 v24, 16, v24
	v_add3_u32 v25, v21, v25, s99
	v_and_or_b32 v24, v25, s100, v24
	global_store_dword v27, v24, s[8:9]
	v_add_u32_e32 v27, 0x80000, v27
	v_lshlrev_b32_e32 v22, 16, v48
	v_and_b32_e32 v23, 0xffff0000, v48
	v_fmac_f32_e32 v22, v11, v20
	v_fmac_f32_e32 v23, v11, v21
	v_min_u32_e32 v26, v26, v28
	global_load_dword v48, v26, s[8:9]
	v_add_u32_e32 v26, 0x80000, v26
	s_waitcnt vmcnt(30)
	v_bfe_u32 v24, v22, 16, 1
	v_add3_u32 v24, v22, v24, s99
	v_bfe_u32 v25, v23, 16, 1
	v_lshrrev_b32_e32 v24, 16, v24
	v_add3_u32 v25, v23, v25, s99
	v_and_or_b32 v24, v25, s100, v24
	global_store_dword v27, v24, s[8:9]
	v_add_u32_e32 v27, 0x80000, v27
	v_lshlrev_b32_e32 v20, 16, v49
	v_and_b32_e32 v21, 0xffff0000, v49
	v_fmac_f32_e32 v20, v11, v22
	v_fmac_f32_e32 v21, v11, v23
	v_min_u32_e32 v26, v26, v28
	global_load_dword v49, v26, s[8:9]
	v_add_u32_e32 v26, 0x80000, v26
	s_waitcnt vmcnt(30)
	v_bfe_u32 v24, v20, 16, 1
	v_add3_u32 v24, v20, v24, s99
	v_bfe_u32 v25, v21, 16, 1
	v_lshrrev_b32_e32 v24, 16, v24
	v_add3_u32 v25, v21, v25, s99
	v_and_or_b32 v24, v25, s100, v24
	global_store_dword v27, v24, s[8:9]
	v_add_u32_e32 v27, 0x80000, v27
	v_lshlrev_b32_e32 v22, 16, v50
	v_and_b32_e32 v23, 0xffff0000, v50
	v_fmac_f32_e32 v22, v11, v20
	v_fmac_f32_e32 v23, v11, v21
	v_min_u32_e32 v26, v26, v28
	global_load_dword v50, v26, s[8:9]
	v_add_u32_e32 v26, 0x80000, v26
	s_waitcnt vmcnt(30)
	v_bfe_u32 v24, v22, 16, 1
	v_add3_u32 v24, v22, v24, s99
	v_bfe_u32 v25, v23, 16, 1
	v_lshrrev_b32_e32 v24, 16, v24
	v_add3_u32 v25, v23, v25, s99
	v_and_or_b32 v24, v25, s100, v24
	global_store_dword v27, v24, s[8:9]
	v_add_u32_e32 v27, 0x80000, v27
	v_lshlrev_b32_e32 v20, 16, v51
	v_and_b32_e32 v21, 0xffff0000, v51
	v_fmac_f32_e32 v20, v11, v22
	v_fmac_f32_e32 v21, v11, v23
	v_min_u32_e32 v26, v26, v28
	global_load_dword v51, v26, s[8:9]
	v_add_u32_e32 v26, 0x80000, v26
	s_waitcnt vmcnt(30)
	v_bfe_u32 v24, v20, 16, 1
	v_add3_u32 v24, v20, v24, s99
	v_bfe_u32 v25, v21, 16, 1
	v_lshrrev_b32_e32 v24, 16, v24
	v_add3_u32 v25, v21, v25, s99
	v_and_or_b32 v24, v25, s100, v24
	global_store_dword v27, v24, s[8:9]
	v_add_u32_e32 v27, 0x80000, v27
	v_lshlrev_b32_e32 v22, 16, v52
	v_and_b32_e32 v23, 0xffff0000, v52
	v_fmac_f32_e32 v22, v11, v20
	v_fmac_f32_e32 v23, v11, v21
	v_min_u32_e32 v26, v26, v28
	global_load_dword v52, v26, s[8:9]
	v_add_u32_e32 v26, 0x80000, v26
	s_waitcnt vmcnt(30)
	v_bfe_u32 v24, v22, 16, 1
	v_add3_u32 v24, v22, v24, s99
	v_bfe_u32 v25, v23, 16, 1
	v_lshrrev_b32_e32 v24, 16, v24
	v_add3_u32 v25, v23, v25, s99
	v_and_or_b32 v24, v25, s100, v24
	global_store_dword v27, v24, s[8:9]
	v_add_u32_e32 v27, 0x80000, v27
	v_lshlrev_b32_e32 v20, 16, v53
	v_and_b32_e32 v21, 0xffff0000, v53
	v_fmac_f32_e32 v20, v11, v22
	v_fmac_f32_e32 v21, v11, v23
	v_min_u32_e32 v26, v26, v28
	global_load_dword v53, v26, s[8:9]
	v_add_u32_e32 v26, 0x80000, v26
	s_waitcnt vmcnt(30)
	v_bfe_u32 v24, v20, 16, 1
	v_add3_u32 v24, v20, v24, s99
	v_bfe_u32 v25, v21, 16, 1
	v_lshrrev_b32_e32 v24, 16, v24
	v_add3_u32 v25, v21, v25, s99
	v_and_or_b32 v24, v25, s100, v24
	global_store_dword v27, v24, s[8:9]
	v_add_u32_e32 v27, 0x80000, v27
	v_lshlrev_b32_e32 v22, 16, v54
	v_and_b32_e32 v23, 0xffff0000, v54
	v_fmac_f32_e32 v22, v11, v20
	v_fmac_f32_e32 v23, v11, v21
	v_min_u32_e32 v26, v26, v28
	global_load_dword v54, v26, s[8:9]
	v_add_u32_e32 v26, 0x80000, v26
	s_waitcnt vmcnt(30)
	v_bfe_u32 v24, v22, 16, 1
	v_add3_u32 v24, v22, v24, s99
	v_bfe_u32 v25, v23, 16, 1
	v_lshrrev_b32_e32 v24, 16, v24
	v_add3_u32 v25, v23, v25, s99
	v_and_or_b32 v24, v25, s100, v24
	global_store_dword v27, v24, s[8:9]
	v_add_u32_e32 v27, 0x80000, v27
	v_lshlrev_b32_e32 v20, 16, v55
	v_and_b32_e32 v21, 0xffff0000, v55
	v_fmac_f32_e32 v20, v11, v22
	v_fmac_f32_e32 v21, v11, v23
	v_min_u32_e32 v26, v26, v28
	global_load_dword v55, v26, s[8:9]
	v_add_u32_e32 v26, 0x80000, v26
	s_add_i32 s98, s98, -1
	s_cmp_lg_u32 s98, 0
	s_cbranch_scc1 .Lscan_ret0_loop
	v_bfe_u32 v24, v20, 16, 1
	v_add3_u32 v24, v20, v24, s99
	v_bfe_u32 v25, v21, 16, 1
	v_lshrrev_b32_e32 v24, 16, v24
	v_add3_u32 v25, v21, v25, s99
	v_and_or_b32 v24, v25, s100, v24
	global_store_dword v27, v24, s[8:9]
	s_waitcnt vmcnt(0)
	v_add_u32_e32 v0, s0, v0
	v_cmp_lt_i32_e32 vcc, s92, v0
	s_or_b64 s[10:11], vcc, s[10:11]
	s_andn2_b64 exec, exec, s[10:11]
	s_cbranch_execnz .LBB0_1446

; __device__ __forceinline__ void phase_ssd_out(const Params& p, int layer, unsigned char* smem) {
;     ...
;           if (wn == ks) {
;             const int t2 = relaunder(tid);
;             const int lane = t2 & 63, hi = lane >> 5, cl = lane & 31, wm = t2 >> 7;
; #pragma unroll
;             for (int mt = 0; mt < 2; mt++)
; #pragma unroll
;               for (int nt = 0; nt < 2; nt++)
; #pragma unroll
;                 for (int i = 0; i < 16; i++) {
;                   int row = wm * 64 + mt * 32 + (i & 3) + 8 * (i >> 2) + 4 * hi;
;                   int cloc = nt * 32 + cl;
;                   int s = ks * 64 + cloc;
;                   float val = 0.f;
;                   if (row >= s) val = cb[mt][nt][i] * __expf(sAcs[row] - sAcs[s]) * sDt[s];
;                   if (row == s) val += Dh;
;                   sA[row * LDK + cloc] = f2bf(val);
;                   if ((i & 7) == 7) __builtin_amdgcn_sched_barrier(0);
;                 }
.LBB0_3755:
	s_andn2_b64 vcc, exec, s[18:19]
	s_cbranch_vccnz .LBB0_3752
	v_cmp_eq_u32_e32 vcc, s7, v148
	s_and_saveexec_b64 s[18:19], vcc
	s_cbranch_execz .LBB0_3751
	v_mov_b32_e32 v167, v96
	v_mov_b32_e32 v171, 0
	v_and_b32_e32 v172, 31, v167
	v_ashrrev_i32_e32 v170, 1, v167
	v_lshrrev_b32_e32 v167, 3, v167
	v_and_b32_e32 v167, 4, v167
	v_or_b32_e32 v169, v172, v97
	v_and_or_b32 v170, v170, s31, v167
	v_lshlrev_b32_e32 v168, 2, v169
	v_cmp_ge_i32_e32 vcc, v170, v169
	v_lshlrev_b32_e32 v167, 2, v170
	v_mov_b32_e32 v174, 0
	ds_read_b128 v[208:211], v167 offset:36864
	ds_read_b128 v[212:215], v167 offset:36896
	ds_read_b128 v[216:219], v167 offset:36928
	ds_read_b128 v[220:223], v167 offset:36960
	ds_read_b128 v[224:227], v167 offset:36992
	ds_read_b128 v[232:235], v167 offset:37024
	ds_read_b128 v[236:239], v167 offset:37056
	ds_read_b128 v[240:243], v167 offset:37088
	ds_read2st64_b32 v[244:245], v168 offset0:144 offset1:146
	s_waitcnt lgkmcnt(0)
	s_and_saveexec_b64 s[20:21], vcc
	s_cbranch_execz .LBB0_3759
	v_mov_b32_e32 v173, v208
	v_mov_b32_e32 v174, v244
	v_mov_b32_e32 v175, v245
	v_sub_f32_e32 v173, v173, v174
	v_mul_f32_e32 v173, 0x3fb8aa3b, v173
	v_exp_f32_e32 v173, v173
	s_nop 0
	v_mul_f32_e32 v173, v0, v173
	v_mul_f32_e32 v174, v175, v173
.LBB0_3759:
	s_or_b64 exec, exec, s[20:21]
	s_waitcnt vmcnt(0)
	v_add_f32_e32 v175, v98, v174
	v_cmp_eq_u32_e32 vcc, v170, v169
	v_lshlrev_b32_e32 v173, 1, v172
	s_nop 0
	v_cndmask_b32_e32 v174, v174, v175, vcc
	v_bfe_u32 v175, v174, 16, 1
	v_add3_u32 v175, v174, v175, s30
	v_mul_lo_u32 v174, v170, s24
	v_add_u32_e32 v174, v173, v174
	ds_write_b16_d16_hi v174, v175
	v_or_b32_e32 v175, 1, v170
	v_cmp_ge_i32_e32 vcc, v175, v169
	s_and_saveexec_b64 s[20:21], vcc
	s_cbranch_execz .LBB0_3761
	v_mov_b32_e32 v171, v209
	v_mov_b32_e32 v176, v244
	v_mov_b32_e32 v177, v245
	v_sub_f32_e32 v171, v171, v176
	v_mul_f32_e32 v171, 0x3fb8aa3b, v171
	v_exp_f32_e32 v171, v171
	s_nop 0
	v_mul_f32_e32 v171, v1, v171
	v_mul_f32_e32 v171, v177, v171
.LBB0_3761:
	s_or_b64 exec, exec, s[20:21]
	v_add_f32_e32 v176, v98, v171
	v_cmp_eq_u32_e32 vcc, v175, v169
	v_mov_b32_e32 v177, 0
	s_nop 0
	v_cndmask_b32_e32 v171, v171, v176, vcc
	v_bfe_u32 v176, v171, 16, 1
	v_add3_u32 v171, v171, v176, s30
	v_or_b32_e32 v176, 2, v170
	ds_write_b16_d16_hi v174, v171 offset:144
	v_cmp_ge_i32_e32 vcc, v176, v169
	v_mov_b32_e32 v171, 0
	s_and_saveexec_b64 s[20:21], vcc
	s_cbranch_execz .LBB0_3763
	v_mov_b32_e32 v177, v210
	v_mov_b32_e32 v178, v244
	v_mov_b32_e32 v179, v245
	v_sub_f32_e32 v177, v177, v178
	v_mul_f32_e32 v177, 0x3fb8aa3b, v177
	v_exp_f32_e32 v177, v177
	s_nop 0
	v_mul_f32_e32 v177, v2, v177
	v_mul_f32_e32 v177, v179, v177
.LBB0_3763:
	s_or_b64 exec, exec, s[20:21]
	v_add_f32_e32 v178, v98, v177
	v_cmp_eq_u32_e32 vcc, v176, v169
	s_nop 1
	v_cndmask_b32_e32 v177, v177, v178, vcc
	v_bfe_u32 v178, v177, 16, 1
	v_add3_u32 v177, v177, v178, s30
	ds_write_b16_d16_hi v174, v177 offset:288
	v_or_b32_e32 v177, 3, v170
	v_cmp_ge_i32_e32 vcc, v177, v169
	s_and_saveexec_b64 s[20:21], vcc
	s_cbranch_execz .LBB0_3765
	v_mov_b32_e32 v171, v211
	v_mov_b32_e32 v178, v244
	v_mov_b32_e32 v179, v245
	v_sub_f32_e32 v171, v171, v178
	v_mul_f32_e32 v171, 0x3fb8aa3b, v171
	v_exp_f32_e32 v171, v171
	s_nop 0
	v_mul_f32_e32 v171, v3, v171
	v_mul_f32_e32 v171, v179, v171
.LBB0_3765:
	s_or_b64 exec, exec, s[20:21]
	v_add_f32_e32 v178, v98, v171
	v_cmp_eq_u32_e32 vcc, v177, v169
	v_mov_b32_e32 v179, 0
	s_nop 0
	v_cndmask_b32_e32 v171, v171, v178, vcc
	v_bfe_u32 v178, v171, 16, 1
	v_add3_u32 v171, v171, v178, s30
	v_or_b32_e32 v178, 8, v170
	ds_write_b16_d16_hi v174, v171 offset:432
	v_cmp_ge_i32_e32 vcc, v178, v169
	v_mov_b32_e32 v171, 0
	s_and_saveexec_b64 s[20:21], vcc
	s_cbranch_execz .LBB0_3767
	v_mov_b32_e32 v179, v212
	v_mov_b32_e32 v180, v244
	v_mov_b32_e32 v181, v245
	v_sub_f32_e32 v179, v179, v180
	v_mul_f32_e32 v179, 0x3fb8aa3b, v179
	v_exp_f32_e32 v179, v179
	s_nop 0
	v_mul_f32_e32 v179, v4, v179
	v_mul_f32_e32 v179, v181, v179
.LBB0_3767:
	s_or_b64 exec, exec, s[20:21]
	v_add_f32_e32 v180, v98, v179
	v_cmp_eq_u32_e32 vcc, v178, v169
	s_nop 1
	v_cndmask_b32_e32 v179, v179, v180, vcc
	v_bfe_u32 v180, v179, 16, 1
	v_add3_u32 v179, v179, v180, s30
	ds_write_b16_d16_hi v174, v179 offset:1152
	v_or_b32_e32 v179, 9, v170
	v_cmp_ge_i32_e32 vcc, v179, v169
	s_and_saveexec_b64 s[20:21], vcc
	s_cbranch_execz .LBB0_3769
	v_mov_b32_e32 v171, v213
	v_mov_b32_e32 v180, v244
	v_mov_b32_e32 v181, v245
	v_sub_f32_e32 v171, v171, v180
	v_mul_f32_e32 v171, 0x3fb8aa3b, v171
	v_exp_f32_e32 v171, v171
	s_nop 0
	v_mul_f32_e32 v171, v5, v171
	v_mul_f32_e32 v171, v181, v171
.LBB0_3769:
	s_or_b64 exec, exec, s[20:21]
	v_add_f32_e32 v180, v98, v171
	v_cmp_eq_u32_e32 vcc, v179, v169
	v_mov_b32_e32 v181, 0
	s_nop 0
	v_cndmask_b32_e32 v171, v171, v180, vcc
	v_bfe_u32 v180, v171, 16, 1
	v_add3_u32 v171, v171, v180, s30
	v_or_b32_e32 v180, 10, v170
	ds_write_b16_d16_hi v174, v171 offset:1296
	v_cmp_ge_i32_e32 vcc, v180, v169
	v_mov_b32_e32 v171, 0
	s_and_saveexec_b64 s[20:21], vcc
	s_cbranch_execz .LBB0_3771
	v_mov_b32_e32 v181, v214
	v_mov_b32_e32 v182, v244
	v_mov_b32_e32 v183, v245
	v_sub_f32_e32 v181, v181, v182
	v_mul_f32_e32 v181, 0x3fb8aa3b, v181
	v_exp_f32_e32 v181, v181
	s_nop 0
	v_mul_f32_e32 v181, v6, v181
	v_mul_f32_e32 v181, v183, v181
.LBB0_3771:
	s_or_b64 exec, exec, s[20:21]
	v_add_f32_e32 v182, v98, v181
	v_cmp_eq_u32_e32 vcc, v180, v169
	s_nop 1
	v_cndmask_b32_e32 v181, v181, v182, vcc
	v_bfe_u32 v182, v181, 16, 1
	v_add3_u32 v181, v181, v182, s30
	ds_write_b16_d16_hi v174, v181 offset:1440
	v_or_b32_e32 v181, 11, v170
	v_cmp_ge_i32_e32 vcc, v181, v169
	s_and_saveexec_b64 s[20:21], vcc
	s_cbranch_execz .LBB0_3773
	v_mov_b32_e32 v171, v215
	v_mov_b32_e32 v182, v244
	v_mov_b32_e32 v183, v245
	v_sub_f32_e32 v171, v171, v182
	v_mul_f32_e32 v171, 0x3fb8aa3b, v171
	v_exp_f32_e32 v171, v171
	s_nop 0
	v_mul_f32_e32 v171, v7, v171
	v_mul_f32_e32 v171, v183, v171
; __device__ __forceinline__ void phase_ssd_out(const Params& p, int layer, unsigned char* smem) {
;     ...
;           if (wn == ks) {
;             const int t2 = relaunder(tid);
;             const int lane = t2 & 63, hi = lane >> 5, cl = lane & 31, wm = t2 >> 7;
; #pragma unroll
;             for (int mt = 0; mt < 2; mt++)
; #pragma unroll
;               for (int nt = 0; nt < 2; nt++)
; #pragma unroll
;                 for (int i = 0; i < 16; i++) {
;                   int row = wm * 64 + mt * 32 + (i & 3) + 8 * (i >> 2) + 4 * hi;
;                   int cloc = nt * 32 + cl;
;                   int s = ks * 64 + cloc;
;                   float val = 0.f;
;                   if (row >= s) val = cb[mt][nt][i] * __expf(sAcs[row] - sAcs[s]) * sDt[s];
;                   if (row == s) val += Dh;
;                   sA[row * LDK + cloc] = f2bf(val);
;                   if ((i & 7) == 7) __builtin_amdgcn_sched_barrier(0);
;                 }
.LBB0_3773:
	s_or_b64 exec, exec, s[20:21]
	v_add_f32_e32 v182, v98, v171
	v_cmp_eq_u32_e32 vcc, v181, v169
	s_nop 1
	v_cndmask_b32_e32 v171, v171, v182, vcc
	v_bfe_u32 v182, v171, 16, 1
	v_add3_u32 v171, v171, v182, s30
	ds_write_b16_d16_hi v174, v171 offset:1584
	v_or_b32_e32 v182, 16, v170
	v_cmp_ge_i32_e32 vcc, v182, v169
	v_mov_b32_e32 v171, 0
	v_mov_b32_e32 v183, 0
	s_and_saveexec_b64 s[20:21], vcc
	s_cbranch_execz .LBB0_3775
	v_mov_b32_e32 v183, v216
	v_mov_b32_e32 v184, v244
	v_mov_b32_e32 v185, v245
	v_sub_f32_e32 v183, v183, v184
	v_mul_f32_e32 v183, 0x3fb8aa3b, v183
	v_exp_f32_e32 v183, v183
	s_nop 0
	v_mul_f32_e32 v183, v8, v183
	v_mul_f32_e32 v183, v185, v183
.LBB0_3775:
	s_or_b64 exec, exec, s[20:21]
	v_add_f32_e32 v184, v98, v183
	v_cmp_eq_u32_e32 vcc, v182, v169
	s_nop 1
	v_cndmask_b32_e32 v183, v183, v184, vcc
	v_bfe_u32 v184, v183, 16, 1
	v_add3_u32 v183, v183, v184, s30
	ds_write_b16_d16_hi v174, v183 offset:2304
	v_or_b32_e32 v183, 17, v170
	v_cmp_ge_i32_e32 vcc, v183, v169
	s_and_saveexec_b64 s[20:21], vcc
	s_cbranch_execz .LBB0_3777
	v_mov_b32_e32 v171, v217
	v_mov_b32_e32 v184, v244
	v_mov_b32_e32 v185, v245
	v_sub_f32_e32 v171, v171, v184
	v_mul_f32_e32 v171, 0x3fb8aa3b, v171
	v_exp_f32_e32 v171, v171
	s_nop 0
	v_mul_f32_e32 v171, v9, v171
	v_mul_f32_e32 v171, v185, v171
.LBB0_3777:
	s_or_b64 exec, exec, s[20:21]
	v_add_f32_e32 v184, v98, v171
	v_cmp_eq_u32_e32 vcc, v183, v169
	v_mov_b32_e32 v185, 0
	s_nop 0
	v_cndmask_b32_e32 v171, v171, v184, vcc
	v_bfe_u32 v184, v171, 16, 1
	v_add3_u32 v171, v171, v184, s30
	v_or_b32_e32 v184, 18, v170
	ds_write_b16_d16_hi v174, v171 offset:2448
	v_cmp_ge_i32_e32 vcc, v184, v169
	v_mov_b32_e32 v171, 0
	s_and_saveexec_b64 s[20:21], vcc
	s_cbranch_execz .LBB0_3779
	v_mov_b32_e32 v185, v218
	v_mov_b32_e32 v186, v244
	v_mov_b32_e32 v187, v245
	v_sub_f32_e32 v185, v185, v186
	v_mul_f32_e32 v185, 0x3fb8aa3b, v185
	v_exp_f32_e32 v185, v185
	s_nop 0
	v_mul_f32_e32 v185, v10, v185
	v_mul_f32_e32 v185, v187, v185
.LBB0_3779:
	s_or_b64 exec, exec, s[20:21]
	v_add_f32_e32 v186, v98, v185
	v_cmp_eq_u32_e32 vcc, v184, v169
	s_nop 1
	v_cndmask_b32_e32 v185, v185, v186, vcc
	v_bfe_u32 v186, v185, 16, 1
	v_add3_u32 v185, v185, v186, s30
	ds_write_b16_d16_hi v174, v185 offset:2592
	v_or_b32_e32 v185, 19, v170
	v_cmp_ge_i32_e32 vcc, v185, v169
	s_and_saveexec_b64 s[20:21], vcc
	s_cbranch_execz .LBB0_3781
	v_mov_b32_e32 v171, v219
	v_mov_b32_e32 v186, v244
	v_mov_b32_e32 v187, v245
	v_sub_f32_e32 v171, v171, v186
	v_mul_f32_e32 v171, 0x3fb8aa3b, v171
	v_exp_f32_e32 v171, v171
	s_nop 0
	v_mul_f32_e32 v171, v11, v171
	v_mul_f32_e32 v171, v187, v171
.LBB0_3781:
	s_or_b64 exec, exec, s[20:21]
	v_add_f32_e32 v186, v98, v171
	v_cmp_eq_u32_e32 vcc, v185, v169
	v_mov_b32_e32 v187, 0
	s_nop 0
	v_cndmask_b32_e32 v171, v171, v186, vcc
	v_bfe_u32 v186, v171, 16, 1
	v_add3_u32 v171, v171, v186, s30
	v_or_b32_e32 v186, 24, v170
	ds_write_b16_d16_hi v174, v171 offset:2736
	v_cmp_ge_i32_e32 vcc, v186, v169
	v_mov_b32_e32 v171, 0
	s_and_saveexec_b64 s[20:21], vcc
	s_cbranch_execz .LBB0_3783
	v_mov_b32_e32 v187, v220
	v_mov_b32_e32 v188, v244
	v_mov_b32_e32 v189, v245
	v_sub_f32_e32 v187, v187, v188
	v_mul_f32_e32 v187, 0x3fb8aa3b, v187
	v_exp_f32_e32 v187, v187
	s_nop 0
	v_mul_f32_e32 v187, v12, v187
	v_mul_f32_e32 v187, v189, v187
.LBB0_3783:
	s_or_b64 exec, exec, s[20:21]
	v_add_f32_e32 v188, v98, v187
	v_cmp_eq_u32_e32 vcc, v186, v169
	s_nop 1
	v_cndmask_b32_e32 v187, v187, v188, vcc
	v_bfe_u32 v188, v187, 16, 1
	v_add3_u32 v187, v187, v188, s30
	ds_write_b16_d16_hi v174, v187 offset:3456
	v_or_b32_e32 v187, 25, v170
	v_cmp_ge_i32_e32 vcc, v187, v169
	s_and_saveexec_b64 s[20:21], vcc
	s_cbranch_execz .LBB0_3785
	v_mov_b32_e32 v171, v221
	v_mov_b32_e32 v188, v244
	v_mov_b32_e32 v189, v245
	v_sub_f32_e32 v171, v171, v188
	v_mul_f32_e32 v171, 0x3fb8aa3b, v171
	v_exp_f32_e32 v171, v171
	s_nop 0
	v_mul_f32_e32 v171, v13, v171
	v_mul_f32_e32 v171, v189, v171
.LBB0_3785:
	s_or_b64 exec, exec, s[20:21]
	v_add_f32_e32 v188, v98, v171
	v_cmp_eq_u32_e32 vcc, v187, v169
	v_mov_b32_e32 v189, 0
	s_nop 0
	v_cndmask_b32_e32 v171, v171, v188, vcc
	v_bfe_u32 v188, v171, 16, 1
	v_add3_u32 v171, v171, v188, s30
	v_or_b32_e32 v188, 26, v170
	ds_write_b16_d16_hi v174, v171 offset:3600
	v_cmp_ge_i32_e32 vcc, v188, v169
	v_mov_b32_e32 v171, 0
	s_and_saveexec_b64 s[20:21], vcc
	s_cbranch_execz .LBB0_3787
	v_mov_b32_e32 v189, v222
	v_mov_b32_e32 v190, v244
	v_mov_b32_e32 v191, v245
	v_sub_f32_e32 v189, v189, v190
	v_mul_f32_e32 v189, 0x3fb8aa3b, v189
	v_exp_f32_e32 v189, v189
	s_nop 0
	v_mul_f32_e32 v189, v14, v189
	v_mul_f32_e32 v189, v191, v189
.LBB0_3787:
	s_or_b64 exec, exec, s[20:21]
	v_add_f32_e32 v190, v98, v189
	v_cmp_eq_u32_e32 vcc, v188, v169
	s_nop 1
	v_cndmask_b32_e32 v189, v189, v190, vcc
	v_bfe_u32 v190, v189, 16, 1
	v_add3_u32 v189, v189, v190, s30
	ds_write_b16_d16_hi v174, v189 offset:3744
	v_or_b32_e32 v189, 27, v170
	v_cmp_ge_i32_e32 vcc, v189, v169
	s_and_saveexec_b64 s[20:21], vcc
	s_cbranch_execz .LBB0_3789
	v_mov_b32_e32 v171, v223
	v_mov_b32_e32 v190, v244
	v_mov_b32_e32 v191, v245
	v_sub_f32_e32 v171, v171, v190
	v_mul_f32_e32 v171, 0x3fb8aa3b, v171
	v_exp_f32_e32 v171, v171
	s_nop 0
	v_mul_f32_e32 v171, v15, v171
	v_mul_f32_e32 v171, v191, v171
; __device__ __forceinline__ void phase_ssd_out(const Params& p, int layer, unsigned char* smem) {
;     ...
; #pragma unroll
;             for (int mt = 0; mt < 2; mt++)
; #pragma unroll
;               for (int nt = 0; nt < 2; nt++)
; #pragma unroll
;                 for (int i = 0; i < 16; i++) {
;                   int row = wm * 64 + mt * 32 + (i & 3) + 8 * (i >> 2) + 4 * hi;
;                   int cloc = nt * 32 + cl;
;                   int s = ks * 64 + cloc;
;                   float val = 0.f;
;                   if (row >= s) val = cb[mt][nt][i] * __expf(sAcs[row] - sAcs[s]) * sDt[s];
;                   if (row == s) val += Dh;
;                   sA[row * LDK + cloc] = f2bf(val);
;                   if ((i & 7) == 7) __builtin_amdgcn_sched_barrier(0);
.LBB0_3789:
	s_or_b64 exec, exec, s[20:21]
	v_add_f32_e32 v190, v98, v171
	v_cmp_eq_u32_e32 vcc, v189, v169
	s_nop 1
	v_cndmask_b32_e32 v171, v171, v190, vcc
	v_bfe_u32 v190, v171, 16, 1
	v_add3_u32 v171, v171, v190, s30
	ds_write_b16_d16_hi v174, v171 offset:3888
	v_or_b32_e32 v171, v172, v161
	v_add_lshl_u32 v172, v172, v97, 2
	v_cmp_ge_i32_e32 vcc, v170, v171
	v_mov_b32_e32 v190, 0
	v_add_u32_e32 v172, 0x80, v172
	v_mov_b32_e32 v191, 0
	ds_read2st64_b32 v[246:247], v172 offset0:144 offset1:146
	s_waitcnt lgkmcnt(0)
	s_and_saveexec_b64 s[20:21], vcc
	s_cbranch_execz .LBB0_3791
	v_mov_b32_e32 v191, v208
	v_mov_b32_e32 v192, v246
	v_mov_b32_e32 v193, v247
	v_sub_f32_e32 v191, v191, v192
	v_mul_f32_e32 v191, 0x3fb8aa3b, v191
	v_exp_f32_e32 v191, v191
	s_nop 0
	v_mul_f32_e32 v191, v16, v191
	v_mul_f32_e32 v191, v193, v191
.LBB0_3791:
	s_or_b64 exec, exec, s[20:21]
	v_bfe_u32 v192, v191, 16, 1
	v_add3_u32 v191, v191, v192, s30
	v_cmp_ge_i32_e32 vcc, v175, v171
	ds_write_b16_d16_hi v174, v191 offset:64
	s_and_saveexec_b64 s[20:21], vcc
	s_cbranch_execz .LBB0_3793
	v_mov_b32_e32 v175, v209
	v_mov_b32_e32 v190, v246
	v_mov_b32_e32 v191, v247
	v_sub_f32_e32 v175, v175, v190
	v_mul_f32_e32 v175, 0x3fb8aa3b, v175
	v_exp_f32_e32 v175, v175
	s_nop 0
	v_mul_f32_e32 v175, v17, v175
	v_mul_f32_e32 v190, v191, v175
.LBB0_3793:
	s_or_b64 exec, exec, s[20:21]
	v_bfe_u32 v175, v190, 16, 1
	v_add3_u32 v175, v190, v175, s30
	ds_write_b16_d16_hi v174, v175 offset:208
	v_cmp_ge_i32_e32 vcc, v176, v171
	v_mov_b32_e32 v175, 0
	v_mov_b32_e32 v176, 0
	s_and_saveexec_b64 s[20:21], vcc
	s_cbranch_execz .LBB0_3795
	v_mov_b32_e32 v176, v210
	v_mov_b32_e32 v190, v246
	v_mov_b32_e32 v191, v247
	v_sub_f32_e32 v176, v176, v190
	v_mul_f32_e32 v176, 0x3fb8aa3b, v176
	v_exp_f32_e32 v176, v176
	s_nop 0
	v_mul_f32_e32 v176, v18, v176
	v_mul_f32_e32 v176, v191, v176
.LBB0_3795:
	s_or_b64 exec, exec, s[20:21]
	v_bfe_u32 v190, v176, 16, 1
	v_add3_u32 v176, v176, v190, s30
	v_cmp_ge_i32_e32 vcc, v177, v171
	ds_write_b16_d16_hi v174, v176 offset:352
	s_and_saveexec_b64 s[20:21], vcc
	s_cbranch_execz .LBB0_3797
	v_mov_b32_e32 v175, v211
	v_mov_b32_e32 v176, v246
	v_mov_b32_e32 v177, v247
	v_sub_f32_e32 v175, v175, v176
	v_mul_f32_e32 v175, 0x3fb8aa3b, v175
	v_exp_f32_e32 v175, v175
	s_nop 0
	v_mul_f32_e32 v175, v19, v175
	v_mul_f32_e32 v175, v177, v175
.LBB0_3797:
	s_or_b64 exec, exec, s[20:21]
	v_bfe_u32 v176, v175, 16, 1
	v_add3_u32 v175, v175, v176, s30
	ds_write_b16_d16_hi v174, v175 offset:496
	v_cmp_ge_i32_e32 vcc, v178, v171
	v_mov_b32_e32 v175, 0
	v_mov_b32_e32 v176, 0
	s_and_saveexec_b64 s[20:21], vcc
	s_cbranch_execz .LBB0_3799
	v_mov_b32_e32 v178, v212
	v_mov_b32_e32 v176, v246
	v_mov_b32_e32 v177, v247
	v_sub_f32_e32 v176, v178, v176
	v_mul_f32_e32 v176, 0x3fb8aa3b, v176
	v_exp_f32_e32 v176, v176
	s_nop 0
	v_mul_f32_e32 v176, v20, v176
	v_mul_f32_e32 v176, v177, v176
.LBB0_3799:
	s_or_b64 exec, exec, s[20:21]
	v_bfe_u32 v177, v176, 16, 1
	v_add3_u32 v176, v176, v177, s30
	v_cmp_ge_i32_e32 vcc, v179, v171
	ds_write_b16_d16_hi v174, v176 offset:1216
	s_and_saveexec_b64 s[20:21], vcc
	s_cbranch_execz .LBB0_3801
	v_mov_b32_e32 v175, v213
	v_mov_b32_e32 v176, v246
	v_mov_b32_e32 v177, v247
	v_sub_f32_e32 v175, v175, v176
	v_mul_f32_e32 v175, 0x3fb8aa3b, v175
	v_exp_f32_e32 v175, v175
	s_nop 0
	v_mul_f32_e32 v175, v21, v175
	v_mul_f32_e32 v175, v177, v175
.LBB0_3801:
	s_or_b64 exec, exec, s[20:21]
	v_bfe_u32 v176, v175, 16, 1
	v_add3_u32 v175, v175, v176, s30
	ds_write_b16_d16_hi v174, v175 offset:1360
	v_cmp_ge_i32_e32 vcc, v180, v171
	v_mov_b32_e32 v175, 0
	v_mov_b32_e32 v176, 0
	s_and_saveexec_b64 s[20:21], vcc
	s_cbranch_execz .LBB0_3803
	v_mov_b32_e32 v178, v214
	v_mov_b32_e32 v176, v246
	v_mov_b32_e32 v177, v247
	v_sub_f32_e32 v176, v178, v176
	v_mul_f32_e32 v176, 0x3fb8aa3b, v176
	v_exp_f32_e32 v176, v176
	s_nop 0
	v_mul_f32_e32 v176, v22, v176
	v_mul_f32_e32 v176, v177, v176
.LBB0_3803:
	s_or_b64 exec, exec, s[20:21]
	v_bfe_u32 v177, v176, 16, 1
	v_add3_u32 v176, v176, v177, s30
	v_cmp_ge_i32_e32 vcc, v181, v171
	ds_write_b16_d16_hi v174, v176 offset:1504
	s_and_saveexec_b64 s[20:21], vcc
	s_cbranch_execz .LBB0_3805
	v_mov_b32_e32 v175, v215
	v_mov_b32_e32 v176, v246
	v_mov_b32_e32 v177, v247
	v_sub_f32_e32 v175, v175, v176
	v_mul_f32_e32 v175, 0x3fb8aa3b, v175
	v_exp_f32_e32 v175, v175
	s_nop 0
	v_mul_f32_e32 v175, v23, v175
	v_mul_f32_e32 v175, v177, v175
.LBB0_3805:
	s_or_b64 exec, exec, s[20:21]
	v_bfe_u32 v176, v175, 16, 1
	v_add3_u32 v175, v175, v176, s30
	ds_write_b16_d16_hi v174, v175 offset:1648
	v_cmp_ge_i32_e32 vcc, v182, v171
	v_mov_b32_e32 v175, 0
	v_mov_b32_e32 v176, 0
	s_and_saveexec_b64 s[20:21], vcc
	s_cbranch_execz .LBB0_3807
	v_mov_b32_e32 v178, v216
	v_mov_b32_e32 v176, v246
	v_mov_b32_e32 v177, v247
	v_sub_f32_e32 v176, v178, v176
	v_mul_f32_e32 v176, 0x3fb8aa3b, v176
	v_exp_f32_e32 v176, v176
	s_nop 0
	v_mul_f32_e32 v176, v24, v176
	v_mul_f32_e32 v176, v177, v176
.LBB0_3807:
	s_or_b64 exec, exec, s[20:21]
	v_bfe_u32 v177, v176, 16, 1
	v_add3_u32 v176, v176, v177, s30
	v_cmp_ge_i32_e32 vcc, v183, v171
	ds_write_b16_d16_hi v174, v176 offset:2368
	s_and_saveexec_b64 s[20:21], vcc
	s_cbranch_execz .LBB0_3809
	v_mov_b32_e32 v175, v217
	v_mov_b32_e32 v176, v246
	v_mov_b32_e32 v177, v247
	v_sub_f32_e32 v175, v175, v176
	v_mul_f32_e32 v175, 0x3fb8aa3b, v175
	v_exp_f32_e32 v175, v175
	s_nop 0
	v_mul_f32_e32 v175, v25, v175
	v_mul_f32_e32 v175, v177, v175
; __device__ __forceinline__ void phase_ssd_out(const Params& p, int layer, unsigned char* smem) {
;     ...
; #pragma unroll
;             for (int mt = 0; mt < 2; mt++)
; #pragma unroll
;               for (int nt = 0; nt < 2; nt++)
; #pragma unroll
;                 for (int i = 0; i < 16; i++) {
;                   int row = wm * 64 + mt * 32 + (i & 3) + 8 * (i >> 2) + 4 * hi;
;                   int cloc = nt * 32 + cl;
;                   int s = ks * 64 + cloc;
;                   float val = 0.f;
;                   if (row >= s) val = cb[mt][nt][i] * __expf(sAcs[row] - sAcs[s]) * sDt[s];
;                   if (row == s) val += Dh;
;                   sA[row * LDK + cloc] = f2bf(val);
;                   if ((i & 7) == 7) __builtin_amdgcn_sched_barrier(0);
.LBB0_3809:
	s_or_b64 exec, exec, s[20:21]
	v_bfe_u32 v176, v175, 16, 1
	v_add3_u32 v175, v175, v176, s30
	ds_write_b16_d16_hi v174, v175 offset:2512
	v_cmp_ge_i32_e32 vcc, v184, v171
	v_mov_b32_e32 v175, 0
	v_mov_b32_e32 v176, 0
	s_and_saveexec_b64 s[20:21], vcc
	s_cbranch_execz .LBB0_3811
	v_mov_b32_e32 v178, v218
	v_mov_b32_e32 v176, v246
	v_mov_b32_e32 v177, v247
	v_sub_f32_e32 v176, v178, v176
	v_mul_f32_e32 v176, 0x3fb8aa3b, v176
	v_exp_f32_e32 v176, v176
	s_nop 0
	v_mul_f32_e32 v176, v26, v176
	v_mul_f32_e32 v176, v177, v176
.LBB0_3811:
	s_or_b64 exec, exec, s[20:21]
	v_bfe_u32 v177, v176, 16, 1
	v_add3_u32 v176, v176, v177, s30
	v_cmp_ge_i32_e32 vcc, v185, v171
	ds_write_b16_d16_hi v174, v176 offset:2656
	s_and_saveexec_b64 s[20:21], vcc
	s_cbranch_execz .LBB0_3813
	v_mov_b32_e32 v175, v219
	v_mov_b32_e32 v176, v246
	v_mov_b32_e32 v177, v247
	v_sub_f32_e32 v175, v175, v176
	v_mul_f32_e32 v175, 0x3fb8aa3b, v175
	v_exp_f32_e32 v175, v175
	s_nop 0
	v_mul_f32_e32 v175, v27, v175
	v_mul_f32_e32 v175, v177, v175
.LBB0_3813:
	s_or_b64 exec, exec, s[20:21]
	v_bfe_u32 v176, v175, 16, 1
	v_add3_u32 v175, v175, v176, s30
	ds_write_b16_d16_hi v174, v175 offset:2800
	v_cmp_ge_i32_e32 vcc, v186, v171
	v_mov_b32_e32 v175, 0
	v_mov_b32_e32 v176, 0
	s_and_saveexec_b64 s[20:21], vcc
	s_cbranch_execz .LBB0_3815
	v_mov_b32_e32 v178, v220
	v_mov_b32_e32 v176, v246
	v_mov_b32_e32 v177, v247
	v_sub_f32_e32 v176, v178, v176
	v_mul_f32_e32 v176, 0x3fb8aa3b, v176
	v_exp_f32_e32 v176, v176
	s_nop 0
	v_mul_f32_e32 v176, v28, v176
	v_mul_f32_e32 v176, v177, v176
.LBB0_3815:
	s_or_b64 exec, exec, s[20:21]
	v_bfe_u32 v177, v176, 16, 1
	v_add3_u32 v176, v176, v177, s30
	v_cmp_ge_i32_e32 vcc, v187, v171
	ds_write_b16_d16_hi v174, v176 offset:3520
	s_and_saveexec_b64 s[20:21], vcc
	s_cbranch_execz .LBB0_3817
	v_mov_b32_e32 v175, v221
	v_mov_b32_e32 v176, v246
	v_mov_b32_e32 v177, v247
	v_sub_f32_e32 v175, v175, v176
	v_mul_f32_e32 v175, 0x3fb8aa3b, v175
	v_exp_f32_e32 v175, v175
	s_nop 0
	v_mul_f32_e32 v175, v29, v175
	v_mul_f32_e32 v175, v177, v175
.LBB0_3817:
	s_or_b64 exec, exec, s[20:21]
	v_bfe_u32 v176, v175, 16, 1
	v_add3_u32 v175, v175, v176, s30
	ds_write_b16_d16_hi v174, v175 offset:3664
	v_cmp_ge_i32_e32 vcc, v188, v171
	v_mov_b32_e32 v175, 0
	v_mov_b32_e32 v176, 0
	s_and_saveexec_b64 s[20:21], vcc
	s_cbranch_execz .LBB0_3819
	v_mov_b32_e32 v178, v222
	v_mov_b32_e32 v176, v246
	v_mov_b32_e32 v177, v247
	v_sub_f32_e32 v176, v178, v176
	v_mul_f32_e32 v176, 0x3fb8aa3b, v176
	v_exp_f32_e32 v176, v176
	s_nop 0
	v_mul_f32_e32 v176, v30, v176
	v_mul_f32_e32 v176, v177, v176
.LBB0_3819:
	s_or_b64 exec, exec, s[20:21]
	v_bfe_u32 v177, v176, 16, 1
	v_add3_u32 v176, v176, v177, s30
	v_cmp_ge_i32_e32 vcc, v189, v171
	ds_write_b16_d16_hi v174, v176 offset:3808
	s_and_saveexec_b64 s[20:21], vcc
	s_cbranch_execz .LBB0_3821
	v_mov_b32_e32 v175, v223
	v_mov_b32_e32 v176, v246
	v_mov_b32_e32 v177, v247
	v_sub_f32_e32 v175, v175, v176
	v_mul_f32_e32 v175, 0x3fb8aa3b, v175
	v_exp_f32_e32 v175, v175
	s_nop 0
	v_mul_f32_e32 v175, v31, v175
	v_mul_f32_e32 v175, v177, v175
.LBB0_3821:
	s_or_b64 exec, exec, s[20:21]
	v_bfe_u32 v176, v175, 16, 1
	v_add3_u32 v175, v175, v176, s30
	ds_write_b16_d16_hi v174, v175 offset:3952
	v_or_b32_e32 v187, 32, v170
	v_cmp_ge_i32_e32 vcc, v187, v169
	v_mov_b32_e32 v174, 0
	v_mov_b32_e32 v175, 0
	s_and_saveexec_b64 s[20:21], vcc
	s_cbranch_execz .LBB0_3823
	v_mov_b32_e32 v175, v224
	v_mov_b32_e32 v176, v244
	v_mov_b32_e32 v177, v245
	v_sub_f32_e32 v175, v175, v176
	v_mul_f32_e32 v175, 0x3fb8aa3b, v175
	v_exp_f32_e32 v175, v175
	s_nop 0
	v_mul_f32_e32 v175, v32, v175
	v_mul_f32_e32 v175, v177, v175
.LBB0_3823:
	s_or_b64 exec, exec, s[20:21]
	v_bfe_u32 v176, v175, 16, 1
	v_add3_u32 v175, v175, v176, s30
	v_mul_lo_u32 v176, v187, s24
	v_or_b32_e32 v188, 33, v170
	v_add_u32_e32 v173, v173, v176
	v_cmp_ge_i32_e32 vcc, v188, v169
	ds_write_b16_d16_hi v173, v175
	s_and_saveexec_b64 s[20:21], vcc
	s_cbranch_execz .LBB0_3825
	v_mov_b32_e32 v176, v225
	v_mov_b32_e32 v174, v244
	v_mov_b32_e32 v175, v245
	v_sub_f32_e32 v174, v176, v174
	v_mul_f32_e32 v174, 0x3fb8aa3b, v174
	v_exp_f32_e32 v174, v174
	s_nop 0
	v_mul_f32_e32 v174, v33, v174
	v_mul_f32_e32 v174, v175, v174
.LBB0_3825:
	s_or_b64 exec, exec, s[20:21]
	v_bfe_u32 v175, v174, 16, 1
	v_add3_u32 v174, v174, v175, s30
	v_or_b32_e32 v186, 34, v170
	ds_write_b16_d16_hi v173, v174 offset:144
	v_cmp_ge_i32_e32 vcc, v186, v169
	v_mov_b32_e32 v174, 0
	v_mov_b32_e32 v175, 0
	s_and_saveexec_b64 s[20:21], vcc
	s_cbranch_execz .LBB0_3827
	v_mov_b32_e32 v175, v226
	v_mov_b32_e32 v176, v244
	v_mov_b32_e32 v177, v245
	v_sub_f32_e32 v175, v175, v176
	v_mul_f32_e32 v175, 0x3fb8aa3b, v175
	v_exp_f32_e32 v175, v175
	s_nop 0
	v_mul_f32_e32 v175, v34, v175
	v_mul_f32_e32 v175, v177, v175
.LBB0_3827:
	s_or_b64 exec, exec, s[20:21]
	v_bfe_u32 v176, v175, 16, 1
	v_or_b32_e32 v185, 35, v170
	v_add3_u32 v175, v175, v176, s30
	v_cmp_ge_i32_e32 vcc, v185, v169
	ds_write_b16_d16_hi v173, v175 offset:288
	s_and_saveexec_b64 s[20:21], vcc
	s_cbranch_execz .LBB0_3829
	v_mov_b32_e32 v176, v227
	v_mov_b32_e32 v174, v244
	v_mov_b32_e32 v175, v245
	v_sub_f32_e32 v174, v176, v174
	v_mul_f32_e32 v174, 0x3fb8aa3b, v174
	v_exp_f32_e32 v174, v174
	s_nop 0
	v_mul_f32_e32 v174, v35, v174
	v_mul_f32_e32 v174, v175, v174
.LBB0_3829:
	s_or_b64 exec, exec, s[20:21]
	v_bfe_u32 v175, v174, 16, 1
	v_add3_u32 v174, v174, v175, s30
	v_or_b32_e32 v184, 40, v170
	ds_write_b16_d16_hi v173, v174 offset:432
	v_cmp_ge_i32_e32 vcc, v184, v169
	v_mov_b32_e32 v174, 0
	v_mov_b32_e32 v175, 0
	s_and_saveexec_b64 s[20:21], vcc
	s_cbranch_execz .LBB0_3831
	v_mov_b32_e32 v175, v232
	v_mov_b32_e32 v176, v244
	v_mov_b32_e32 v177, v245
	v_sub_f32_e32 v175, v175, v176
	v_mul_f32_e32 v175, 0x3fb8aa3b, v175
	v_exp_f32_e32 v175, v175
	s_nop 0
	v_mul_f32_e32 v175, v36, v175
	v_mul_f32_e32 v175, v177, v175
; __device__ __forceinline__ void phase_ssd_out(const Params& p, int layer, unsigned char* smem) {
;     ...
; #pragma unroll
;             for (int mt = 0; mt < 2; mt++)
; #pragma unroll
;               for (int nt = 0; nt < 2; nt++)
; #pragma unroll
;                 for (int i = 0; i < 16; i++) {
;                   int row = wm * 64 + mt * 32 + (i & 3) + 8 * (i >> 2) + 4 * hi;
;                   int cloc = nt * 32 + cl;
;                   int s = ks * 64 + cloc;
;                   float val = 0.f;
;                   if (row >= s) val = cb[mt][nt][i] * __expf(sAcs[row] - sAcs[s]) * sDt[s];
;                   if (row == s) val += Dh;
;                   sA[row * LDK + cloc] = f2bf(val);
;                   if ((i & 7) == 7) __builtin_amdgcn_sched_barrier(0);
.LBB0_3831:
	s_or_b64 exec, exec, s[20:21]
	v_bfe_u32 v176, v175, 16, 1
	v_or_b32_e32 v183, 41, v170
	v_add3_u32 v175, v175, v176, s30
	v_cmp_ge_i32_e32 vcc, v183, v169
	ds_write_b16_d16_hi v173, v175 offset:1152
	s_and_saveexec_b64 s[20:21], vcc
	s_cbranch_execz .LBB0_3833
	v_mov_b32_e32 v176, v233
	v_mov_b32_e32 v174, v244
	v_mov_b32_e32 v175, v245
	v_sub_f32_e32 v174, v176, v174
	v_mul_f32_e32 v174, 0x3fb8aa3b, v174
	v_exp_f32_e32 v174, v174
	s_nop 0
	v_mul_f32_e32 v174, v37, v174
	v_mul_f32_e32 v174, v175, v174
.LBB0_3833:
	s_or_b64 exec, exec, s[20:21]
	v_bfe_u32 v175, v174, 16, 1
	v_add3_u32 v174, v174, v175, s30
	v_or_b32_e32 v182, 42, v170
	ds_write_b16_d16_hi v173, v174 offset:1296
	v_cmp_ge_i32_e32 vcc, v182, v169
	v_mov_b32_e32 v174, 0
	v_mov_b32_e32 v175, 0
	s_and_saveexec_b64 s[20:21], vcc
	s_cbranch_execz .LBB0_3835
	v_mov_b32_e32 v175, v234
	v_mov_b32_e32 v176, v244
	v_mov_b32_e32 v177, v245
	v_sub_f32_e32 v175, v175, v176
	v_mul_f32_e32 v175, 0x3fb8aa3b, v175
	v_exp_f32_e32 v175, v175
	s_nop 0
	v_mul_f32_e32 v175, v38, v175
	v_mul_f32_e32 v175, v177, v175
.LBB0_3835:
	s_or_b64 exec, exec, s[20:21]
	v_bfe_u32 v176, v175, 16, 1
	v_or_b32_e32 v181, 43, v170
	v_add3_u32 v175, v175, v176, s30
	v_cmp_ge_i32_e32 vcc, v181, v169
	ds_write_b16_d16_hi v173, v175 offset:1440
	s_and_saveexec_b64 s[20:21], vcc
	s_cbranch_execz .LBB0_3837
	v_mov_b32_e32 v176, v235
	v_mov_b32_e32 v174, v244
	v_mov_b32_e32 v175, v245
	v_sub_f32_e32 v174, v176, v174
	v_mul_f32_e32 v174, 0x3fb8aa3b, v174
	v_exp_f32_e32 v174, v174
	s_nop 0
	v_mul_f32_e32 v174, v39, v174
	v_mul_f32_e32 v174, v175, v174
.LBB0_3837:
	s_or_b64 exec, exec, s[20:21]
	v_bfe_u32 v175, v174, 16, 1
	v_add3_u32 v174, v174, v175, s30
	ds_write_b16_d16_hi v173, v174 offset:1584
	v_or_b32_e32 v180, 48, v170
	v_cmp_ge_i32_e32 vcc, v180, v169
	v_mov_b32_e32 v174, 0
	v_mov_b32_e32 v175, 0
	s_and_saveexec_b64 s[20:21], vcc
	s_cbranch_execz .LBB0_3839
	v_mov_b32_e32 v175, v236
	v_mov_b32_e32 v176, v244
	v_mov_b32_e32 v177, v245
	v_sub_f32_e32 v175, v175, v176
	v_mul_f32_e32 v175, 0x3fb8aa3b, v175
	v_exp_f32_e32 v175, v175
	s_nop 0
	v_mul_f32_e32 v175, v40, v175
	v_mul_f32_e32 v175, v177, v175
.LBB0_3839:
	s_or_b64 exec, exec, s[20:21]
	v_bfe_u32 v176, v175, 16, 1
	v_or_b32_e32 v179, 49, v170
	v_add3_u32 v175, v175, v176, s30
	v_cmp_ge_i32_e32 vcc, v179, v169
	ds_write_b16_d16_hi v173, v175 offset:2304
	s_and_saveexec_b64 s[20:21], vcc
	s_cbranch_execz .LBB0_3841
	v_mov_b32_e32 v176, v237
	v_mov_b32_e32 v174, v244
	v_mov_b32_e32 v175, v245
	v_sub_f32_e32 v174, v176, v174
	v_mul_f32_e32 v174, 0x3fb8aa3b, v174
	v_exp_f32_e32 v174, v174
	s_nop 0
	v_mul_f32_e32 v174, v41, v174
	v_mul_f32_e32 v174, v175, v174
.LBB0_3841:
	s_or_b64 exec, exec, s[20:21]
	v_bfe_u32 v175, v174, 16, 1
	v_add3_u32 v174, v174, v175, s30
	v_or_b32_e32 v178, 50, v170
	ds_write_b16_d16_hi v173, v174 offset:2448
	v_cmp_ge_i32_e32 vcc, v178, v169
	v_mov_b32_e32 v174, 0
	v_mov_b32_e32 v175, 0
	s_and_saveexec_b64 s[20:21], vcc
	s_cbranch_execz .LBB0_3843
	v_mov_b32_e32 v175, v238
	v_mov_b32_e32 v176, v244
	v_mov_b32_e32 v177, v245
	v_sub_f32_e32 v175, v175, v176
	v_mul_f32_e32 v175, 0x3fb8aa3b, v175
	v_exp_f32_e32 v175, v175
	s_nop 0
	v_mul_f32_e32 v175, v42, v175
	v_mul_f32_e32 v175, v177, v175
.LBB0_3843:
	s_or_b64 exec, exec, s[20:21]
	v_bfe_u32 v176, v175, 16, 1
	v_or_b32_e32 v177, 51, v170
	v_add3_u32 v175, v175, v176, s30
	v_cmp_ge_i32_e32 vcc, v177, v169
	ds_write_b16_d16_hi v173, v175 offset:2592
	s_and_saveexec_b64 s[20:21], vcc
	s_cbranch_execz .LBB0_3845
	v_mov_b32_e32 v176, v239
	v_mov_b32_e32 v174, v244
	v_mov_b32_e32 v175, v245
	v_sub_f32_e32 v174, v176, v174
	v_mul_f32_e32 v174, 0x3fb8aa3b, v174
	v_exp_f32_e32 v174, v174
	s_nop 0
	v_mul_f32_e32 v174, v43, v174
	v_mul_f32_e32 v174, v175, v174
.LBB0_3845:
	s_or_b64 exec, exec, s[20:21]
	v_bfe_u32 v175, v174, 16, 1
	v_add3_u32 v174, v174, v175, s30
	v_or_b32_e32 v176, 56, v170
	ds_write_b16_d16_hi v173, v174 offset:2736
	v_cmp_ge_i32_e32 vcc, v176, v169
	v_mov_b32_e32 v174, 0
	v_mov_b32_e32 v175, 0
	s_and_saveexec_b64 s[20:21], vcc
	s_cbranch_execz .LBB0_3847
	v_mov_b32_e32 v175, v240
	v_mov_b32_e32 v190, v244
	v_mov_b32_e32 v191, v245
	v_sub_f32_e32 v175, v175, v190
	v_mul_f32_e32 v175, 0x3fb8aa3b, v175
	v_exp_f32_e32 v175, v175
	s_nop 0
	v_mul_f32_e32 v175, v44, v175
	v_mul_f32_e32 v175, v191, v175
.LBB0_3847:
	s_or_b64 exec, exec, s[20:21]
	v_bfe_u32 v189, v175, 16, 1
	v_add3_u32 v175, v175, v189, s30
	ds_write_b16_d16_hi v173, v175 offset:3456
	v_or_b32_e32 v175, 57, v170
	v_cmp_ge_i32_e32 vcc, v175, v169
	s_and_saveexec_b64 s[20:21], vcc
	s_cbranch_execz .LBB0_3849
	v_mov_b32_e32 v174, v241
	v_mov_b32_e32 v190, v244
	v_mov_b32_e32 v191, v245
	v_sub_f32_e32 v174, v174, v190
	v_mul_f32_e32 v174, 0x3fb8aa3b, v174
	v_exp_f32_e32 v174, v174
	s_nop 0
	v_mul_f32_e32 v174, v45, v174
	v_mul_f32_e32 v174, v191, v174
.LBB0_3849:
	s_or_b64 exec, exec, s[20:21]
	v_bfe_u32 v189, v174, 16, 1
	v_add3_u32 v174, v174, v189, s30
	ds_write_b16_d16_hi v173, v174 offset:3600
	v_or_b32_e32 v174, 58, v170
	v_cmp_ge_i32_e32 vcc, v174, v169
	v_mov_b32_e32 v189, 0
	v_mov_b32_e32 v190, 0
	s_and_saveexec_b64 s[20:21], vcc
	s_cbranch_execz .LBB0_3851
	v_mov_b32_e32 v192, v242
	v_mov_b32_e32 v190, v244
	v_mov_b32_e32 v191, v245
	v_sub_f32_e32 v190, v192, v190
	v_mul_f32_e32 v190, 0x3fb8aa3b, v190
	v_exp_f32_e32 v190, v190
	s_nop 0
	v_mul_f32_e32 v190, v46, v190
	v_mul_f32_e32 v190, v191, v190
; __device__ __forceinline__ void phase_ssd_out(const Params& p, int layer, unsigned char* smem) {
;     ...
; #pragma unroll
;             for (int mt = 0; mt < 2; mt++)
; #pragma unroll
;               for (int nt = 0; nt < 2; nt++)
; #pragma unroll
;                 for (int i = 0; i < 16; i++) {
;                   int row = wm * 64 + mt * 32 + (i & 3) + 8 * (i >> 2) + 4 * hi;
;                   int cloc = nt * 32 + cl;
;                   int s = ks * 64 + cloc;
;                   float val = 0.f;
;                   if (row >= s) val = cb[mt][nt][i] * __expf(sAcs[row] - sAcs[s]) * sDt[s];
;                   if (row == s) val += Dh;
;                   sA[row * LDK + cloc] = f2bf(val);
;                   if ((i & 7) == 7) __builtin_amdgcn_sched_barrier(0);
.LBB0_3851:
	s_or_b64 exec, exec, s[20:21]
	v_bfe_u32 v191, v190, 16, 1
	v_or_b32_e32 v170, 59, v170
	v_add3_u32 v190, v190, v191, s30
	v_cmp_ge_i32_e32 vcc, v170, v169
	ds_write_b16_d16_hi v173, v190 offset:3744
	s_and_saveexec_b64 s[20:21], vcc
	s_cbranch_execz .LBB0_3853
	v_mov_b32_e32 v189, v243
	v_mov_b32_e32 v168, v244
	v_mov_b32_e32 v169, v245
	v_sub_f32_e32 v168, v189, v168
	v_mul_f32_e32 v168, 0x3fb8aa3b, v168
	v_exp_f32_e32 v168, v168
	s_nop 0
	v_mul_f32_e32 v168, v47, v168
	v_mul_f32_e32 v189, v169, v168
.LBB0_3853:
	s_or_b64 exec, exec, s[20:21]
	v_bfe_u32 v168, v189, 16, 1
	v_add3_u32 v168, v189, v168, s30
	ds_write_b16_d16_hi v173, v168 offset:3888
	v_cmp_ge_i32_e32 vcc, v187, v171
	v_mov_b32_e32 v168, 0
	v_mov_b32_e32 v169, 0
	s_and_saveexec_b64 s[20:21], vcc
	s_cbranch_execz .LBB0_3855
	v_mov_b32_e32 v169, v224
	v_mov_b32_e32 v190, v246
	v_mov_b32_e32 v191, v247
	v_sub_f32_e32 v169, v169, v190
	v_mul_f32_e32 v169, 0x3fb8aa3b, v169
	v_exp_f32_e32 v169, v169
	s_nop 0
	v_mul_f32_e32 v169, v48, v169
	v_mul_f32_e32 v169, v191, v169
.LBB0_3855:
	s_or_b64 exec, exec, s[20:21]
	v_add_f32_e32 v189, v98, v169
	v_cmp_eq_u32_e32 vcc, v187, v171
	s_nop 1
	v_cndmask_b32_e32 v169, v169, v189, vcc
	v_bfe_u32 v187, v169, 16, 1
	v_add3_u32 v169, v169, v187, s30
	v_cmp_ge_i32_e32 vcc, v188, v171
	ds_write_b16_d16_hi v173, v169 offset:64
	s_and_saveexec_b64 s[20:21], vcc
	s_cbranch_execz .LBB0_3857
	v_mov_b32_e32 v187, v225
	v_mov_b32_e32 v168, v246
	v_mov_b32_e32 v169, v247
	v_sub_f32_e32 v168, v187, v168
	v_mul_f32_e32 v168, 0x3fb8aa3b, v168
	v_exp_f32_e32 v168, v168
	s_nop 0
	v_mul_f32_e32 v168, v49, v168
	v_mul_f32_e32 v168, v169, v168
.LBB0_3857:
	s_or_b64 exec, exec, s[20:21]
	v_add_f32_e32 v169, v98, v168
	v_cmp_eq_u32_e32 vcc, v188, v171
	s_nop 1
	v_cndmask_b32_e32 v168, v168, v169, vcc
	v_bfe_u32 v169, v168, 16, 1
	v_add3_u32 v168, v168, v169, s30
	ds_write_b16_d16_hi v173, v168 offset:208
	v_cmp_ge_i32_e32 vcc, v186, v171
	v_mov_b32_e32 v168, 0
	v_mov_b32_e32 v169, 0
	s_and_saveexec_b64 s[20:21], vcc
	s_cbranch_execz .LBB0_3859
	v_mov_b32_e32 v169, v226
	v_mov_b32_e32 v188, v246
	v_mov_b32_e32 v189, v247
	v_sub_f32_e32 v169, v169, v188
	v_mul_f32_e32 v169, 0x3fb8aa3b, v169
	v_exp_f32_e32 v169, v169
	s_nop 0
	v_mul_f32_e32 v169, v50, v169
	v_mul_f32_e32 v169, v189, v169
.LBB0_3859:
	s_or_b64 exec, exec, s[20:21]
	v_add_f32_e32 v187, v98, v169
	v_cmp_eq_u32_e32 vcc, v186, v171
	s_nop 1
	v_cndmask_b32_e32 v169, v169, v187, vcc
	v_bfe_u32 v186, v169, 16, 1
	v_add3_u32 v169, v169, v186, s30
	v_cmp_ge_i32_e32 vcc, v185, v171
	ds_write_b16_d16_hi v173, v169 offset:352
	s_and_saveexec_b64 s[20:21], vcc
	s_cbranch_execz .LBB0_3861
	v_mov_b32_e32 v186, v227
	v_mov_b32_e32 v168, v246
	v_mov_b32_e32 v169, v247
	v_sub_f32_e32 v168, v186, v168
	v_mul_f32_e32 v168, 0x3fb8aa3b, v168
	v_exp_f32_e32 v168, v168
	s_nop 0
	v_mul_f32_e32 v168, v51, v168
	v_mul_f32_e32 v168, v169, v168
.LBB0_3861:
	s_or_b64 exec, exec, s[20:21]
	v_add_f32_e32 v169, v98, v168
	v_cmp_eq_u32_e32 vcc, v185, v171
	s_nop 1
	v_cndmask_b32_e32 v168, v168, v169, vcc
	v_bfe_u32 v169, v168, 16, 1
	v_add3_u32 v168, v168, v169, s30
	ds_write_b16_d16_hi v173, v168 offset:496
	v_cmp_ge_i32_e32 vcc, v184, v171
	v_mov_b32_e32 v168, 0
	v_mov_b32_e32 v169, 0
	s_and_saveexec_b64 s[20:21], vcc
	s_cbranch_execz .LBB0_3863
	v_mov_b32_e32 v169, v232
	v_mov_b32_e32 v186, v246
	v_mov_b32_e32 v187, v247
	v_sub_f32_e32 v169, v169, v186
	v_mul_f32_e32 v169, 0x3fb8aa3b, v169
	v_exp_f32_e32 v169, v169
	s_nop 0
	v_mul_f32_e32 v169, v52, v169
	v_mul_f32_e32 v169, v187, v169
.LBB0_3863:
	s_or_b64 exec, exec, s[20:21]
	v_add_f32_e32 v185, v98, v169
	v_cmp_eq_u32_e32 vcc, v184, v171
	s_nop 1
	v_cndmask_b32_e32 v169, v169, v185, vcc
	v_bfe_u32 v184, v169, 16, 1
	v_add3_u32 v169, v169, v184, s30
	v_cmp_ge_i32_e32 vcc, v183, v171
	ds_write_b16_d16_hi v173, v169 offset:1216
	s_and_saveexec_b64 s[20:21], vcc
	s_cbranch_execz .LBB0_3865
	v_mov_b32_e32 v184, v233
	v_mov_b32_e32 v168, v246
	v_mov_b32_e32 v169, v247
	v_sub_f32_e32 v168, v184, v168
	v_mul_f32_e32 v168, 0x3fb8aa3b, v168
	v_exp_f32_e32 v168, v168
	s_nop 0
	v_mul_f32_e32 v168, v53, v168
	v_mul_f32_e32 v168, v169, v168
.LBB0_3865:
	s_or_b64 exec, exec, s[20:21]
	v_add_f32_e32 v169, v98, v168
	v_cmp_eq_u32_e32 vcc, v183, v171
	s_nop 1
	v_cndmask_b32_e32 v168, v168, v169, vcc
	v_bfe_u32 v169, v168, 16, 1
	v_add3_u32 v168, v168, v169, s30
	ds_write_b16_d16_hi v173, v168 offset:1360
	v_cmp_ge_i32_e32 vcc, v182, v171
	v_mov_b32_e32 v168, 0
	v_mov_b32_e32 v169, 0
	s_and_saveexec_b64 s[20:21], vcc
	s_cbranch_execz .LBB0_3867
	v_mov_b32_e32 v169, v234
	v_mov_b32_e32 v184, v246
	v_mov_b32_e32 v185, v247
	v_sub_f32_e32 v169, v169, v184
	v_mul_f32_e32 v169, 0x3fb8aa3b, v169
	v_exp_f32_e32 v169, v169
	s_nop 0
	v_mul_f32_e32 v169, v54, v169
	v_mul_f32_e32 v169, v185, v169
.LBB0_3867:
	s_or_b64 exec, exec, s[20:21]
	v_add_f32_e32 v183, v98, v169
	v_cmp_eq_u32_e32 vcc, v182, v171
	s_nop 1
	v_cndmask_b32_e32 v169, v169, v183, vcc
	v_bfe_u32 v182, v169, 16, 1
	v_add3_u32 v169, v169, v182, s30
	v_cmp_ge_i32_e32 vcc, v181, v171
	ds_write_b16_d16_hi v173, v169 offset:1504
	s_and_saveexec_b64 s[20:21], vcc
	s_cbranch_execz .LBB0_3869
	v_mov_b32_e32 v182, v235
	v_mov_b32_e32 v168, v246
	v_mov_b32_e32 v169, v247
	v_sub_f32_e32 v168, v182, v168
	v_mul_f32_e32 v168, 0x3fb8aa3b, v168
	v_exp_f32_e32 v168, v168
	s_nop 0
	v_mul_f32_e32 v168, v55, v168
	v_mul_f32_e32 v168, v169, v168
; __device__ __forceinline__ void phase_ssd_out(const Params& p, int layer, unsigned char* smem) {
;     ...
; #pragma unroll
;             for (int mt = 0; mt < 2; mt++)
; #pragma unroll
;               for (int nt = 0; nt < 2; nt++)
; #pragma unroll
;                 for (int i = 0; i < 16; i++) {
;                   int row = wm * 64 + mt * 32 + (i & 3) + 8 * (i >> 2) + 4 * hi;
;                   int cloc = nt * 32 + cl;
;                   int s = ks * 64 + cloc;
;                   float val = 0.f;
;                   if (row >= s) val = cb[mt][nt][i] * __expf(sAcs[row] - sAcs[s]) * sDt[s];
;                   if (row == s) val += Dh;
;                   sA[row * LDK + cloc] = f2bf(val);
;                   if ((i & 7) == 7) __builtin_amdgcn_sched_barrier(0);
.LBB0_3869:
	s_or_b64 exec, exec, s[20:21]
	v_add_f32_e32 v169, v98, v168
	v_cmp_eq_u32_e32 vcc, v181, v171
	s_nop 1
	v_cndmask_b32_e32 v168, v168, v169, vcc
	v_bfe_u32 v169, v168, 16, 1
	v_add3_u32 v168, v168, v169, s30
	ds_write_b16_d16_hi v173, v168 offset:1648
	v_cmp_ge_i32_e32 vcc, v180, v171
	v_mov_b32_e32 v168, 0
	v_mov_b32_e32 v169, 0
	s_and_saveexec_b64 s[20:21], vcc
	s_cbranch_execz .LBB0_3871
	v_mov_b32_e32 v169, v236
	v_mov_b32_e32 v182, v246
	v_mov_b32_e32 v183, v247
	v_sub_f32_e32 v169, v169, v182
	v_mul_f32_e32 v169, 0x3fb8aa3b, v169
	v_exp_f32_e32 v169, v169
	s_nop 0
	v_mul_f32_e32 v169, v56, v169
	v_mul_f32_e32 v169, v183, v169
.LBB0_3871:
	s_or_b64 exec, exec, s[20:21]
	v_add_f32_e32 v181, v98, v169
	v_cmp_eq_u32_e32 vcc, v180, v171
	s_nop 1
	v_cndmask_b32_e32 v169, v169, v181, vcc
	v_bfe_u32 v180, v169, 16, 1
	v_add3_u32 v169, v169, v180, s30
	v_cmp_ge_i32_e32 vcc, v179, v171
	ds_write_b16_d16_hi v173, v169 offset:2368
	s_and_saveexec_b64 s[20:21], vcc
	s_cbranch_execz .LBB0_3873
	v_mov_b32_e32 v180, v237
	v_mov_b32_e32 v168, v246
	v_mov_b32_e32 v169, v247
	v_sub_f32_e32 v168, v180, v168
	v_mul_f32_e32 v168, 0x3fb8aa3b, v168
	v_exp_f32_e32 v168, v168
	s_nop 0
	v_mul_f32_e32 v168, v57, v168
	v_mul_f32_e32 v168, v169, v168
.LBB0_3873:
	s_or_b64 exec, exec, s[20:21]
	v_add_f32_e32 v169, v98, v168
	v_cmp_eq_u32_e32 vcc, v179, v171
	s_nop 1
	v_cndmask_b32_e32 v168, v168, v169, vcc
	v_bfe_u32 v169, v168, 16, 1
	v_add3_u32 v168, v168, v169, s30
	ds_write_b16_d16_hi v173, v168 offset:2512
	v_cmp_ge_i32_e32 vcc, v178, v171
	v_mov_b32_e32 v168, 0
	v_mov_b32_e32 v169, 0
	s_and_saveexec_b64 s[20:21], vcc
	s_cbranch_execz .LBB0_3875
	v_mov_b32_e32 v169, v238
	v_mov_b32_e32 v180, v246
	v_mov_b32_e32 v181, v247
	v_sub_f32_e32 v169, v169, v180
	v_mul_f32_e32 v169, 0x3fb8aa3b, v169
	v_exp_f32_e32 v169, v169
	s_nop 0
	v_mul_f32_e32 v169, v58, v169
	v_mul_f32_e32 v169, v181, v169
.LBB0_3875:
	s_or_b64 exec, exec, s[20:21]
	v_add_f32_e32 v179, v98, v169
	v_cmp_eq_u32_e32 vcc, v178, v171
	s_nop 1
	v_cndmask_b32_e32 v169, v169, v179, vcc
	v_bfe_u32 v178, v169, 16, 1
	v_add3_u32 v169, v169, v178, s30
	v_cmp_ge_i32_e32 vcc, v177, v171
	ds_write_b16_d16_hi v173, v169 offset:2656
	s_and_saveexec_b64 s[20:21], vcc
	s_cbranch_execz .LBB0_3877
	v_mov_b32_e32 v178, v239
	v_mov_b32_e32 v168, v246
	v_mov_b32_e32 v169, v247
	v_sub_f32_e32 v168, v178, v168
	v_mul_f32_e32 v168, 0x3fb8aa3b, v168
	v_exp_f32_e32 v168, v168
	s_nop 0
	v_mul_f32_e32 v168, v59, v168
	v_mul_f32_e32 v168, v169, v168
.LBB0_3877:
	s_or_b64 exec, exec, s[20:21]
	v_add_f32_e32 v169, v98, v168
	v_cmp_eq_u32_e32 vcc, v177, v171
	s_nop 1
	v_cndmask_b32_e32 v168, v168, v169, vcc
	v_bfe_u32 v169, v168, 16, 1
	v_add3_u32 v168, v168, v169, s30
	ds_write_b16_d16_hi v173, v168 offset:2800
	v_cmp_ge_i32_e32 vcc, v176, v171
	v_mov_b32_e32 v168, 0
	v_mov_b32_e32 v169, 0
	s_and_saveexec_b64 s[20:21], vcc
	s_cbranch_execz .LBB0_3879
	v_mov_b32_e32 v169, v240
	v_mov_b32_e32 v178, v246
	v_mov_b32_e32 v179, v247
	v_sub_f32_e32 v169, v169, v178
	v_mul_f32_e32 v169, 0x3fb8aa3b, v169
	v_exp_f32_e32 v169, v169
	s_nop 0
	v_mul_f32_e32 v169, v60, v169
	v_mul_f32_e32 v169, v179, v169
.LBB0_3879:
	s_or_b64 exec, exec, s[20:21]
	v_add_f32_e32 v177, v98, v169
	v_cmp_eq_u32_e32 vcc, v176, v171
	s_nop 1
	v_cndmask_b32_e32 v169, v169, v177, vcc
	v_bfe_u32 v176, v169, 16, 1
	v_add3_u32 v169, v169, v176, s30
	v_cmp_ge_i32_e32 vcc, v175, v171
	ds_write_b16_d16_hi v173, v169 offset:3520
	s_and_saveexec_b64 s[20:21], vcc
	s_cbranch_execz .LBB0_3881
	v_mov_b32_e32 v176, v241
	v_mov_b32_e32 v168, v246
	v_mov_b32_e32 v169, v247
	v_sub_f32_e32 v168, v176, v168
	v_mul_f32_e32 v168, 0x3fb8aa3b, v168
	v_exp_f32_e32 v168, v168
	s_nop 0
	v_mul_f32_e32 v168, v61, v168
	v_mul_f32_e32 v168, v169, v168
.LBB0_3881:
	s_or_b64 exec, exec, s[20:21]
	v_add_f32_e32 v169, v98, v168
	v_cmp_eq_u32_e32 vcc, v175, v171
	s_nop 1
	v_cndmask_b32_e32 v168, v168, v169, vcc
	v_bfe_u32 v169, v168, 16, 1
	v_add3_u32 v168, v168, v169, s30
	ds_write_b16_d16_hi v173, v168 offset:3664
	v_cmp_ge_i32_e32 vcc, v174, v171
	v_mov_b32_e32 v168, 0
	v_mov_b32_e32 v169, 0
	s_and_saveexec_b64 s[20:21], vcc
	s_cbranch_execz .LBB0_3883
	v_mov_b32_e32 v169, v242
	v_mov_b32_e32 v176, v246
	v_mov_b32_e32 v177, v247
	v_sub_f32_e32 v169, v169, v176
	v_mul_f32_e32 v169, 0x3fb8aa3b, v169
	v_exp_f32_e32 v169, v169
	s_nop 0
	v_mul_f32_e32 v169, v62, v169
	v_mul_f32_e32 v169, v177, v169
.LBB0_3883:
	s_or_b64 exec, exec, s[20:21]
	v_add_f32_e32 v175, v98, v169
	v_cmp_eq_u32_e32 vcc, v174, v171
	s_nop 1
	v_cndmask_b32_e32 v169, v169, v175, vcc
	v_bfe_u32 v174, v169, 16, 1
	v_add3_u32 v169, v169, v174, s30
	v_cmp_ge_i32_e32 vcc, v170, v171
	ds_write_b16_d16_hi v173, v169 offset:3808
	s_and_saveexec_b64 s[20:21], vcc
	s_cbranch_execz .LBB0_3750
	v_mov_b32_e32 v167, v243
	v_mov_b32_e32 v168, v246
	v_mov_b32_e32 v169, v247
	v_sub_f32_e32 v167, v167, v168
	v_mul_f32_e32 v167, 0x3fb8aa3b, v167
	v_exp_f32_e32 v167, v167
	s_nop 0
	v_mul_f32_e32 v167, v63, v167
	v_mul_f32_e32 v168, v169, v167
	s_branch .LBB0_3750

; __global__ void __launch_bounds__(256, 2) mega(Params p) {
;   __shared__ __attribute__((aligned(16))) unsigned char smem[SMEM_BYTES];
;   if (p.phase_hi > 1000000) cg::this_grid().sync();
;     ...
;   PhaseRunner<0>::run(p, smem, xb);
; }
	.amdhsa_kernel _Z4mega6Params
		.amdhsa_group_segment_fixed_size 77840
		.amdhsa_private_segment_fixed_size 0
		.amdhsa_kernarg_size 424
		.amdhsa_user_sgpr_count 2
		.amdhsa_user_sgpr_dispatch_ptr 0
		.amdhsa_user_sgpr_queue_ptr 0
		.amdhsa_user_sgpr_kernarg_segment_ptr 1
		.amdhsa_user_sgpr_dispatch_id 0
		.amdhsa_user_sgpr_kernarg_preload_length 0
		.amdhsa_user_sgpr_kernarg_preload_offset 0
		.amdhsa_user_sgpr_private_segment_size 0
		.amdhsa_uses_dynamic_stack 0
		.amdhsa_enable_private_segment 0
		.amdhsa_system_sgpr_workgroup_id_x 1
		.amdhsa_system_sgpr_workgroup_id_y 0
		.amdhsa_system_sgpr_workgroup_id_z 0
		.amdhsa_system_sgpr_workgroup_info 0
		.amdhsa_system_vgpr_workitem_id 2
		.amdhsa_next_free_vgpr 253
		.amdhsa_next_free_sgpr 102
		.amdhsa_accum_offset 256
		.amdhsa_reserve_vcc 1
		.amdhsa_float_round_mode_32 0
		.amdhsa_float_round_mode_16_64 0
		.amdhsa_float_denorm_mode_32 3
		.amdhsa_float_denorm_mode_16_64 3
		.amdhsa_dx10_clamp 1
		.amdhsa_ieee_mode 1
		.amdhsa_fp16_overflow 0
		.amdhsa_tg_split 0
		.amdhsa_exception_fp_ieee_invalid_op 0
		.amdhsa_exception_fp_denorm_src 0
		.amdhsa_exception_fp_ieee_div_zero 0
		.amdhsa_exception_fp_ieee_overflow 0
		.amdhsa_exception_fp_ieee_underflow 0
		.amdhsa_exception_fp_ieee_inexact 0
		.amdhsa_exception_int_div_zero 0
	.end_amdhsa_kernel

; __global__ void __launch_bounds__(256, 2) mega(Params p) {
;   __shared__ __attribute__((aligned(16))) unsigned char smem[SMEM_BYTES];
;   if (p.phase_hi > 1000000) cg::this_grid().sync();
;     ...
;   PhaseRunner<0>::run(p, smem, xb);
; }
amdhsa.kernels:
  - .agpr_count:     0
    .args:
      - .offset:         0
        .size:           168
        .value_kind:     by_value
      - .offset:         168
        .size:           4
        .value_kind:     hidden_block_count_x
      - .offset:         172
        .size:           4
        .value_kind:     hidden_block_count_y
      - .offset:         176
        .size:           4
        .value_kind:     hidden_block_count_z
      - .offset:         180
        .size:           2
        .value_kind:     hidden_group_size_x
      - .offset:         182
        .size:           2
        .value_kind:     hidden_group_size_y
      - .offset:         184
        .size:           2
        .value_kind:     hidden_group_size_z
      - .offset:         186
        .size:           2
        .value_kind:     hidden_remainder_x
      - .offset:         188
        .size:           2
        .value_kind:     hidden_remainder_y
      - .offset:         190
        .size:           2
        .value_kind:     hidden_remainder_z
      - .offset:         208
        .size:           8
        .value_kind:     hidden_global_offset_x
      - .offset:         216
        .size:           8
        .value_kind:     hidden_global_offset_y
      - .offset:         224
        .size:           8
        .value_kind:     hidden_global_offset_z
      - .offset:         232
        .size:           2
        .value_kind:     hidden_grid_dims
      - .offset:         256
        .size:           8
        .value_kind:     hidden_multigrid_sync_arg
    .group_segment_fixed_size: 77840
    .kernarg_segment_align: 8
    .kernarg_segment_size: 424
    .language:       OpenCL C
    .language_version:
      - 2
      - 0
    .max_flat_workgroup_size: 256
    .name:           _Z4mega6Params
    .private_segment_fixed_size: 0
    .sgpr_count:     108
    .sgpr_spill_count: 106
    .symbol:         _Z4mega6Params.kd
    .uniform_work_group_size: 1
    .uses_dynamic_stack: false
    .vgpr_count:     253
    .vgpr_spill_count: 0
    .wavefront_size: 64
